# K-loop MFMA issue order: snake walk so consecutive MFMAs share one operand fragment (operand-sharing order 1,3,2,4 of the four 8-MFMA groups)
# speedup vs baseline: 1.0061x; 1.0061x over previous
.LBB0_140:
	s_ashr_i32 s37, s36, 31
	s_lshl_b64 s[42:43], s[36:37], 19
	s_add_u32 s42, s62, s42
	s_addc_u32 s43, s63, s43
	s_and_b64 s[44:45], s[0:1], exec
	s_cselect_b32 s37, s43, s49
	s_cselect_b32 s77, s42, s48
	s_ashr_i32 s39, s38, 31
	s_lshl_b64 s[44:45], s[38:39], 19
	s_add_u32 s44, s54, s44
	s_addc_u32 s45, s55, s45
	s_and_b64 s[52:53], s[0:1], exec
	s_cselect_b32 s39, s45, s51
	s_cselect_b32 s78, s44, s50
	s_add_u32 s48, s48, 0x40080
	s_addc_u32 s49, s49, 0
	s_add_u32 s79, s50, 0x100
	s_addc_u32 s80, s51, 0
	s_mov_b32 s81, -2
	ds_read_b128 v[150:153], v147
	ds_read_b128 v[154:157], v147 offset:1024
	ds_read_b128 v[158:161], v147 offset:2048
	ds_read_b128 v[162:165], v147 offset:3072
	ds_read_b128 v[166:169], v148
	ds_read_b128 v[170:173], v148 offset:1024
	ds_read_b128 v[174:177], v148 offset:2048
	ds_read_b128 v[178:181], v148 offset:3072
	s_add_u32 s50, s48, 0xfffc0080
	s_addc_u32 s51, s49, -1
	s_cmp_eq_u32 s81, 12
	s_cselect_b32 s53, s37, s51
	s_cselect_b32 s52, s77, s50
	s_cselect_b32 s51, s39, s80
	s_cselect_b32 s50, s78, s79
	v_lshl_add_u64 v[214:215], s[48:49], 0, v[136:137]
	s_add_i32 m0, s47, 0xc000
	ds_read_b128 v[182:185], v149
	ds_read_b128 v[186:189], v149 offset:1024
	ds_read_b128 v[190:193], v149 offset:2048
	ds_read_b128 v[194:197], v149 offset:3072
	ds_read_b128 v[198:201], v149 offset:4096
	ds_read_b128 v[202:205], v149 offset:5120
	ds_read_b128 v[206:209], v149 offset:6144
	ds_read_b128 v[210:213], v149 offset:7168
	global_load_lds_dwordx4 v[214:215], off
	v_lshl_add_u64 v[214:215], s[48:49], 0, v[138:139]
	s_add_i32 m0, s47, 0xe000
	s_nop 0
	global_load_lds_dwordx4 v[214:215], off
	s_waitcnt vmcnt(8)
	s_waitcnt lgkmcnt(0)
	s_setprio 1
	s_barrier
	v_mfma_f32_16x16x32_bf16 v[124:127], v[150:153], v[182:185], 0
	v_mfma_f32_16x16x32_bf16 v[116:119], v[158:161], v[182:185], 0
	v_mfma_f32_16x16x32_bf16 v[100:103], v[158:161], v[190:193], 0
	v_mfma_f32_16x16x32_bf16 v[108:111], v[150:153], v[190:193], 0
	v_mfma_f32_16x16x32_bf16 v[92:95], v[150:153], v[198:201], 0
	v_mfma_f32_16x16x32_bf16 v[84:87], v[158:161], v[198:201], 0
	v_mfma_f32_16x16x32_bf16 v[68:71], v[158:161], v[206:209], 0
	v_mfma_f32_16x16x32_bf16 v[76:79], v[150:153], v[206:209], 0
	v_mfma_f32_16x16x32_bf16 v[72:75], v[166:169], v[206:209], 0
	v_mfma_f32_16x16x32_bf16 v[64:67], v[174:177], v[206:209], 0
	v_mfma_f32_16x16x32_bf16 v[80:83], v[174:177], v[198:201], 0
	v_mfma_f32_16x16x32_bf16 v[88:91], v[166:169], v[198:201], 0
	v_mfma_f32_16x16x32_bf16 v[104:107], v[166:169], v[190:193], 0
	v_mfma_f32_16x16x32_bf16 v[96:99], v[174:177], v[190:193], 0
	v_mfma_f32_16x16x32_bf16 v[112:115], v[174:177], v[182:185], 0
	v_mfma_f32_16x16x32_bf16 v[120:123], v[166:169], v[182:185], 0
	v_mfma_f32_16x16x32_bf16 v[124:127], v[154:157], v[186:189], v[124:127]
	v_mfma_f32_16x16x32_bf16 v[116:119], v[162:165], v[186:189], v[116:119]
	v_mfma_f32_16x16x32_bf16 v[100:103], v[162:165], v[194:197], v[100:103]
	v_mfma_f32_16x16x32_bf16 v[108:111], v[154:157], v[194:197], v[108:111]
	v_mfma_f32_16x16x32_bf16 v[92:95], v[154:157], v[202:205], v[92:95]
	v_mfma_f32_16x16x32_bf16 v[84:87], v[162:165], v[202:205], v[84:87]
	v_mfma_f32_16x16x32_bf16 v[68:71], v[162:165], v[210:213], v[68:71]
	v_mfma_f32_16x16x32_bf16 v[76:79], v[154:157], v[210:213], v[76:79]
	v_mfma_f32_16x16x32_bf16 v[72:75], v[170:173], v[210:213], v[72:75]
	v_mfma_f32_16x16x32_bf16 v[64:67], v[178:181], v[210:213], v[64:67]
	v_mfma_f32_16x16x32_bf16 v[80:83], v[178:181], v[202:205], v[80:83]
	v_mfma_f32_16x16x32_bf16 v[88:91], v[170:173], v[202:205], v[88:91]
	v_mfma_f32_16x16x32_bf16 v[104:107], v[170:173], v[194:197], v[104:107]
	v_mfma_f32_16x16x32_bf16 v[96:99], v[178:181], v[194:197], v[96:99]
	v_mfma_f32_16x16x32_bf16 v[112:115], v[178:181], v[186:189], v[112:115]
	v_mfma_f32_16x16x32_bf16 v[120:123], v[170:173], v[186:189], v[120:123]
	s_barrier
	s_setprio 0
	s_add_i32 s82, s73, s56
	v_lshl_add_u64 v[214:215], s[50:51], 0, v[132:133]
	s_mov_b32 m0, s82
	ds_read_b128 v[182:185], v149 offset:16384
	ds_read_b128 v[186:189], v149 offset:17408
	ds_read_b128 v[190:193], v149 offset:18432
	ds_read_b128 v[194:197], v149 offset:19456
	ds_read_b128 v[198:201], v149 offset:20480
	ds_read_b128 v[202:205], v149 offset:21504
	ds_read_b128 v[206:209], v149 offset:22528
	ds_read_b128 v[210:213], v149 offset:23552
	global_load_lds_dwordx4 v[214:215], off
	s_add_i32 m0, s82, 0x2000
	s_add_u32 s88, s50, 0x40000
	v_lshl_add_u64 v[216:217], s[50:51], 0, v[128:129]
	s_addc_u32 s89, s51, 0
	s_add_i32 s82, s74, s56
	global_load_lds_dwordx4 v[216:217], off
	v_lshl_add_u64 v[218:219], s[88:89], 0, v[132:133]
	s_mov_b32 m0, s82
	v_lshl_add_u64 v[220:221], s[52:53], 0, v[130:131]
	global_load_lds_dwordx4 v[218:219], off
	v_lshl_add_u64 v[218:219], s[88:89], 0, v[128:129]
	s_add_i32 m0, s82, 0x2000
	s_nop 0
	global_load_lds_dwordx4 v[218:219], off
	v_lshl_add_u64 v[218:219], s[52:53], 0, v[134:135]
	s_mov_b32 m0, s47
	s_nop 0
	global_load_lds_dwordx4 v[218:219], off
	s_mov_b32 m0, s59
	s_nop 0
	global_load_lds_dwordx4 v[220:221], off
	s_waitcnt vmcnt(8)
	s_waitcnt lgkmcnt(0)
	s_setprio 1
	s_barrier
	v_mfma_f32_16x16x32_bf16 v[60:63], v[150:153], v[182:185], 0
	v_mfma_f32_16x16x32_bf16 v[52:55], v[158:161], v[182:185], 0
	v_mfma_f32_16x16x32_bf16 v[36:39], v[158:161], v[190:193], 0
	v_mfma_f32_16x16x32_bf16 v[44:47], v[150:153], v[190:193], 0
	v_mfma_f32_16x16x32_bf16 v[28:31], v[150:153], v[198:201], 0
	v_mfma_f32_16x16x32_bf16 v[20:23], v[158:161], v[198:201], 0
	v_mfma_f32_16x16x32_bf16 v[4:7], v[158:161], v[206:209], 0
	v_mfma_f32_16x16x32_bf16 v[12:15], v[150:153], v[206:209], 0
	v_mfma_f32_16x16x32_bf16 v[8:11], v[166:169], v[206:209], 0
	v_mfma_f32_16x16x32_bf16 v[0:3], v[174:177], v[206:209], 0
	v_mfma_f32_16x16x32_bf16 v[16:19], v[174:177], v[198:201], 0
	v_mfma_f32_16x16x32_bf16 v[24:27], v[166:169], v[198:201], 0
	v_mfma_f32_16x16x32_bf16 v[40:43], v[166:169], v[190:193], 0
	v_mfma_f32_16x16x32_bf16 v[32:35], v[174:177], v[190:193], 0
	v_mfma_f32_16x16x32_bf16 v[48:51], v[174:177], v[182:185], 0
	v_mfma_f32_16x16x32_bf16 v[56:59], v[166:169], v[182:185], 0
	v_mfma_f32_16x16x32_bf16 v[60:63], v[154:157], v[186:189], v[60:63]
	v_mfma_f32_16x16x32_bf16 v[52:55], v[162:165], v[186:189], v[52:55]
	v_mfma_f32_16x16x32_bf16 v[36:39], v[162:165], v[194:197], v[36:39]
	v_mfma_f32_16x16x32_bf16 v[44:47], v[154:157], v[194:197], v[44:47]
	v_mfma_f32_16x16x32_bf16 v[28:31], v[154:157], v[202:205], v[28:31]
	v_mfma_f32_16x16x32_bf16 v[20:23], v[162:165], v[202:205], v[20:23]
	v_mfma_f32_16x16x32_bf16 v[4:7], v[162:165], v[210:213], v[4:7]
	v_mfma_f32_16x16x32_bf16 v[12:15], v[154:157], v[210:213], v[12:15]
	v_mfma_f32_16x16x32_bf16 v[8:11], v[170:173], v[210:213], v[8:11]
	v_mfma_f32_16x16x32_bf16 v[0:3], v[178:181], v[210:213], v[0:3]
	v_mfma_f32_16x16x32_bf16 v[16:19], v[178:181], v[202:205], v[16:19]
	v_mfma_f32_16x16x32_bf16 v[24:27], v[170:173], v[202:205], v[24:27]
	v_mfma_f32_16x16x32_bf16 v[40:43], v[170:173], v[194:197], v[40:43]
	v_mfma_f32_16x16x32_bf16 v[32:35], v[178:181], v[194:197], v[32:35]
	v_mfma_f32_16x16x32_bf16 v[48:51], v[178:181], v[186:189], v[48:51]
	v_mfma_f32_16x16x32_bf16 v[56:59], v[170:173], v[186:189], v[56:59]
	s_barrier
	s_setprio 0
	s_add_i32 s82, 0, 0x18000
	s_add_i32 s85, 0, 0x1c000
	v_add_u32_e32 v162, s82, v145
	v_add_u32_e32 v178, s85, v145
	ds_read_b128 v[150:153], v162
	ds_read_b128 v[154:157], v162 offset:1024
	ds_read_b128 v[158:161], v162 offset:2048
	ds_read_b128 v[162:165], v162 offset:3072
	ds_read_b128 v[166:169], v178
	ds_read_b128 v[170:173], v178 offset:1024
	ds_read_b128 v[174:177], v178 offset:2048
	ds_read_b128 v[178:181], v178 offset:3072
	s_add_u32 s52, s52, 0x40000
	s_addc_u32 s53, s53, 0
	s_mov_b32 m0, s66
	v_lshl_add_u64 v[222:223], s[52:53], 0, v[134:135]
	ds_read_b128 v[182:185], v149 offset:32768
	ds_read_b128 v[186:189], v149 offset:33792
	ds_read_b128 v[190:193], v149 offset:34816
	ds_read_b128 v[194:197], v149 offset:35840
	ds_read_b128 v[198:201], v149 offset:36864
	ds_read_b128 v[202:205], v149 offset:37888
	ds_read_b128 v[206:209], v149 offset:38912
	ds_read_b128 v[210:213], v149 offset:39936
	global_load_lds_dwordx4 v[222:223], off
	v_lshl_add_u64 v[222:223], s[52:53], 0, v[130:131]
	s_mov_b32 m0, s67
	s_nop 0
	global_load_lds_dwordx4 v[222:223], off
	s_waitcnt vmcnt(8)
	s_waitcnt lgkmcnt(0)
	s_setprio 1
	s_barrier
	v_mfma_f32_16x16x32_bf16 v[124:127], v[150:153], v[182:185], v[124:127]
	v_mfma_f32_16x16x32_bf16 v[116:119], v[158:161], v[182:185], v[116:119]
	v_mfma_f32_16x16x32_bf16 v[100:103], v[158:161], v[190:193], v[100:103]
	v_mfma_f32_16x16x32_bf16 v[108:111], v[150:153], v[190:193], v[108:111]
	v_mfma_f32_16x16x32_bf16 v[92:95], v[150:153], v[198:201], v[92:95]
	v_mfma_f32_16x16x32_bf16 v[84:87], v[158:161], v[198:201], v[84:87]
	v_mfma_f32_16x16x32_bf16 v[68:71], v[158:161], v[206:209], v[68:71]
	v_mfma_f32_16x16x32_bf16 v[76:79], v[150:153], v[206:209], v[76:79]
	v_mfma_f32_16x16x32_bf16 v[72:75], v[166:169], v[206:209], v[72:75]
	v_mfma_f32_16x16x32_bf16 v[64:67], v[174:177], v[206:209], v[64:67]
	v_mfma_f32_16x16x32_bf16 v[80:83], v[174:177], v[198:201], v[80:83]
	v_mfma_f32_16x16x32_bf16 v[88:91], v[166:169], v[198:201], v[88:91]
	v_mfma_f32_16x16x32_bf16 v[104:107], v[166:169], v[190:193], v[104:107]
	v_mfma_f32_16x16x32_bf16 v[96:99], v[174:177], v[190:193], v[96:99]
	v_mfma_f32_16x16x32_bf16 v[112:115], v[174:177], v[182:185], v[112:115]
	v_mfma_f32_16x16x32_bf16 v[120:123], v[166:169], v[182:185], v[120:123]
	v_mfma_f32_16x16x32_bf16 v[124:127], v[154:157], v[186:189], v[124:127]
	v_mfma_f32_16x16x32_bf16 v[116:119], v[162:165], v[186:189], v[116:119]
	v_mfma_f32_16x16x32_bf16 v[100:103], v[162:165], v[194:197], v[100:103]
	v_mfma_f32_16x16x32_bf16 v[108:111], v[154:157], v[194:197], v[108:111]
	v_mfma_f32_16x16x32_bf16 v[92:95], v[154:157], v[202:205], v[92:95]
	v_mfma_f32_16x16x32_bf16 v[84:87], v[162:165], v[202:205], v[84:87]
	v_mfma_f32_16x16x32_bf16 v[68:71], v[162:165], v[210:213], v[68:71]
	v_mfma_f32_16x16x32_bf16 v[76:79], v[154:157], v[210:213], v[76:79]
	v_mfma_f32_16x16x32_bf16 v[72:75], v[170:173], v[210:213], v[72:75]
	v_mfma_f32_16x16x32_bf16 v[64:67], v[178:181], v[210:213], v[64:67]
	v_mfma_f32_16x16x32_bf16 v[80:83], v[178:181], v[202:205], v[80:83]
	v_mfma_f32_16x16x32_bf16 v[88:91], v[170:173], v[202:205], v[88:91]
	v_mfma_f32_16x16x32_bf16 v[104:107], v[170:173], v[194:197], v[104:107]
	v_mfma_f32_16x16x32_bf16 v[96:99], v[178:181], v[194:197], v[96:99]
	v_mfma_f32_16x16x32_bf16 v[112:115], v[178:181], v[186:189], v[112:115]
	v_mfma_f32_16x16x32_bf16 v[120:123], v[170:173], v[186:189], v[120:123]
	s_barrier
	s_setprio 0
	s_add_i32 s52, s82, s56
	v_lshl_add_u64 v[214:215], v[214:215], 0, s[10:11]
	s_mov_b32 m0, s52
	ds_read_b128 v[182:185], v149 offset:49152
	ds_read_b128 v[186:189], v149 offset:50176
	ds_read_b128 v[190:193], v149 offset:51200
	ds_read_b128 v[194:197], v149 offset:52224
	ds_read_b128 v[198:201], v149 offset:53248
	ds_read_b128 v[202:205], v149 offset:54272
	ds_read_b128 v[206:209], v149 offset:55296
	ds_read_b128 v[210:213], v149 offset:56320
	global_load_lds_dwordx4 v[214:215], off
	s_add_i32 m0, s52, 0x2000
	s_add_u32 s50, s50, 0x40080
	v_lshl_add_u64 v[214:215], v[216:217], 0, s[10:11]
	s_addc_u32 s51, s51, 0
	s_add_i32 s52, s85, s56
	global_load_lds_dwordx4 v[214:215], off
	v_lshl_add_u64 v[214:215], s[50:51], 0, v[132:133]
	s_mov_b32 m0, s52
	s_nop 0
	global_load_lds_dwordx4 v[214:215], off
	v_lshl_add_u64 v[214:215], s[50:51], 0, v[128:129]
	s_add_i32 m0, s52, 0x2000
	s_nop 0
	global_load_lds_dwordx4 v[214:215], off
	v_lshl_add_u64 v[214:215], v[218:219], 0, s[10:11]
	s_mov_b32 m0, s69
	s_nop 0
	global_load_lds_dwordx4 v[214:215], off
	v_lshl_add_u64 v[214:215], v[220:221], 0, s[10:11]
	s_mov_b32 m0, s70
	s_nop 0
	global_load_lds_dwordx4 v[214:215], off
	s_waitcnt vmcnt(8)
	s_waitcnt lgkmcnt(0)
	s_setprio 1
	s_barrier
	v_mfma_f32_16x16x32_bf16 v[60:63], v[150:153], v[182:185], v[60:63]
	v_mfma_f32_16x16x32_bf16 v[52:55], v[158:161], v[182:185], v[52:55]
	v_mfma_f32_16x16x32_bf16 v[36:39], v[158:161], v[190:193], v[36:39]
	v_mfma_f32_16x16x32_bf16 v[44:47], v[150:153], v[190:193], v[44:47]
	v_mfma_f32_16x16x32_bf16 v[28:31], v[150:153], v[198:201], v[28:31]
	v_mfma_f32_16x16x32_bf16 v[20:23], v[158:161], v[198:201], v[20:23]
	v_mfma_f32_16x16x32_bf16 v[4:7], v[158:161], v[206:209], v[4:7]
	v_mfma_f32_16x16x32_bf16 v[12:15], v[150:153], v[206:209], v[12:15]
	v_mfma_f32_16x16x32_bf16 v[8:11], v[166:169], v[206:209], v[8:11]
	v_mfma_f32_16x16x32_bf16 v[0:3], v[174:177], v[206:209], v[0:3]
	v_mfma_f32_16x16x32_bf16 v[16:19], v[174:177], v[198:201], v[16:19]
	v_mfma_f32_16x16x32_bf16 v[24:27], v[166:169], v[198:201], v[24:27]
	v_mfma_f32_16x16x32_bf16 v[40:43], v[166:169], v[190:193], v[40:43]
	v_mfma_f32_16x16x32_bf16 v[32:35], v[174:177], v[190:193], v[32:35]
	v_mfma_f32_16x16x32_bf16 v[48:51], v[174:177], v[182:185], v[48:51]
	v_mfma_f32_16x16x32_bf16 v[56:59], v[166:169], v[182:185], v[56:59]
	v_mfma_f32_16x16x32_bf16 v[60:63], v[154:157], v[186:189], v[60:63]
	v_mfma_f32_16x16x32_bf16 v[52:55], v[162:165], v[186:189], v[52:55]
	v_mfma_f32_16x16x32_bf16 v[36:39], v[162:165], v[194:197], v[36:39]
	v_mfma_f32_16x16x32_bf16 v[44:47], v[154:157], v[194:197], v[44:47]
	v_mfma_f32_16x16x32_bf16 v[28:31], v[154:157], v[202:205], v[28:31]
	v_mfma_f32_16x16x32_bf16 v[20:23], v[162:165], v[202:205], v[20:23]
	v_mfma_f32_16x16x32_bf16 v[4:7], v[162:165], v[210:213], v[4:7]
	v_mfma_f32_16x16x32_bf16 v[12:15], v[154:157], v[210:213], v[12:15]
	v_mfma_f32_16x16x32_bf16 v[8:11], v[170:173], v[210:213], v[8:11]
	v_mfma_f32_16x16x32_bf16 v[0:3], v[178:181], v[210:213], v[0:3]
	v_mfma_f32_16x16x32_bf16 v[16:19], v[178:181], v[202:205], v[16:19]
	v_mfma_f32_16x16x32_bf16 v[24:27], v[170:173], v[202:205], v[24:27]
	v_mfma_f32_16x16x32_bf16 v[40:43], v[170:173], v[194:197], v[40:43]
	v_mfma_f32_16x16x32_bf16 v[32:35], v[178:181], v[194:197], v[32:35]
	v_mfma_f32_16x16x32_bf16 v[48:51], v[178:181], v[186:189], v[48:51]
	v_mfma_f32_16x16x32_bf16 v[56:59], v[170:173], v[186:189], v[56:59]
	s_barrier
	s_setprio 0
	s_add_i32 s81, s81, 2
	s_add_u32 s48, s48, 0x100
	s_addc_u32 s49, s49, 0
	s_add_u32 s79, s79, 0x100
	s_addc_u32 s80, s80, 0
	s_cmp_gt_u32 s81, 13
.LBB0_141:
	ds_read_b128 v[150:153], v147
	ds_read_b128 v[154:157], v147 offset:1024
	ds_read_b128 v[158:161], v147 offset:2048
	ds_read_b128 v[162:165], v147 offset:3072
	ds_read_b128 v[166:169], v148
	ds_read_b128 v[170:173], v148 offset:1024
	ds_read_b128 v[174:177], v148 offset:2048
	ds_read_b128 v[178:181], v148 offset:3072
	s_add_u32 s50, s48, 0xfffc0080
	s_addc_u32 s51, s49, -1
	s_cmp_eq_u32 s81, 12
	s_cselect_b32 s53, s37, s51
	s_cselect_b32 s52, s77, s50
	s_cselect_b32 s51, s39, s80
	s_cselect_b32 s50, s78, s79
	v_lshl_add_u64 v[214:215], s[48:49], 0, v[136:137]
	s_add_i32 m0, s47, 0xc000
	ds_read_b128 v[182:185], v149
	ds_read_b128 v[186:189], v149 offset:1024
	ds_read_b128 v[190:193], v149 offset:2048
	ds_read_b128 v[194:197], v149 offset:3072
	ds_read_b128 v[198:201], v149 offset:4096
	ds_read_b128 v[202:205], v149 offset:5120
	ds_read_b128 v[206:209], v149 offset:6144
	ds_read_b128 v[210:213], v149 offset:7168
	global_load_lds_dwordx4 v[214:215], off
	v_lshl_add_u64 v[214:215], s[48:49], 0, v[138:139]
	s_add_i32 m0, s47, 0xe000
	s_nop 0
	global_load_lds_dwordx4 v[214:215], off
	s_waitcnt vmcnt(8)
	s_waitcnt lgkmcnt(0)
	s_setprio 1
	s_barrier
	v_mfma_f32_16x16x32_bf16 v[124:127], v[150:153], v[182:185], v[124:127]
	v_mfma_f32_16x16x32_bf16 v[116:119], v[158:161], v[182:185], v[116:119]
	v_mfma_f32_16x16x32_bf16 v[100:103], v[158:161], v[190:193], v[100:103]
	v_mfma_f32_16x16x32_bf16 v[108:111], v[150:153], v[190:193], v[108:111]
	v_mfma_f32_16x16x32_bf16 v[92:95], v[150:153], v[198:201], v[92:95]
	v_mfma_f32_16x16x32_bf16 v[84:87], v[158:161], v[198:201], v[84:87]
	v_mfma_f32_16x16x32_bf16 v[68:71], v[158:161], v[206:209], v[68:71]
	v_mfma_f32_16x16x32_bf16 v[76:79], v[150:153], v[206:209], v[76:79]
	v_mfma_f32_16x16x32_bf16 v[72:75], v[166:169], v[206:209], v[72:75]
	v_mfma_f32_16x16x32_bf16 v[64:67], v[174:177], v[206:209], v[64:67]
	v_mfma_f32_16x16x32_bf16 v[80:83], v[174:177], v[198:201], v[80:83]
	v_mfma_f32_16x16x32_bf16 v[88:91], v[166:169], v[198:201], v[88:91]
	v_mfma_f32_16x16x32_bf16 v[104:107], v[166:169], v[190:193], v[104:107]
	v_mfma_f32_16x16x32_bf16 v[96:99], v[174:177], v[190:193], v[96:99]
	v_mfma_f32_16x16x32_bf16 v[112:115], v[174:177], v[182:185], v[112:115]
	v_mfma_f32_16x16x32_bf16 v[120:123], v[166:169], v[182:185], v[120:123]
	v_mfma_f32_16x16x32_bf16 v[124:127], v[154:157], v[186:189], v[124:127]
	v_mfma_f32_16x16x32_bf16 v[116:119], v[162:165], v[186:189], v[116:119]
	v_mfma_f32_16x16x32_bf16 v[100:103], v[162:165], v[194:197], v[100:103]
	v_mfma_f32_16x16x32_bf16 v[108:111], v[154:157], v[194:197], v[108:111]
	v_mfma_f32_16x16x32_bf16 v[92:95], v[154:157], v[202:205], v[92:95]
	v_mfma_f32_16x16x32_bf16 v[84:87], v[162:165], v[202:205], v[84:87]
	v_mfma_f32_16x16x32_bf16 v[68:71], v[162:165], v[210:213], v[68:71]
	v_mfma_f32_16x16x32_bf16 v[76:79], v[154:157], v[210:213], v[76:79]
	v_mfma_f32_16x16x32_bf16 v[72:75], v[170:173], v[210:213], v[72:75]
	v_mfma_f32_16x16x32_bf16 v[64:67], v[178:181], v[210:213], v[64:67]
	v_mfma_f32_16x16x32_bf16 v[80:83], v[178:181], v[202:205], v[80:83]
	v_mfma_f32_16x16x32_bf16 v[88:91], v[170:173], v[202:205], v[88:91]
	v_mfma_f32_16x16x32_bf16 v[104:107], v[170:173], v[194:197], v[104:107]
	v_mfma_f32_16x16x32_bf16 v[96:99], v[178:181], v[194:197], v[96:99]
	v_mfma_f32_16x16x32_bf16 v[112:115], v[178:181], v[186:189], v[112:115]
	v_mfma_f32_16x16x32_bf16 v[120:123], v[170:173], v[186:189], v[120:123]
	s_barrier
	s_setprio 0
	s_add_i32 s82, s73, s56
	v_lshl_add_u64 v[214:215], s[50:51], 0, v[132:133]
	s_mov_b32 m0, s82
	ds_read_b128 v[182:185], v149 offset:16384
	ds_read_b128 v[186:189], v149 offset:17408
	ds_read_b128 v[190:193], v149 offset:18432
	ds_read_b128 v[194:197], v149 offset:19456
	ds_read_b128 v[198:201], v149 offset:20480
	ds_read_b128 v[202:205], v149 offset:21504
	ds_read_b128 v[206:209], v149 offset:22528
	ds_read_b128 v[210:213], v149 offset:23552
	global_load_lds_dwordx4 v[214:215], off
	s_add_i32 m0, s82, 0x2000
	s_add_u32 s88, s50, 0x40000
	v_lshl_add_u64 v[216:217], s[50:51], 0, v[128:129]
	s_addc_u32 s89, s51, 0
	s_add_i32 s82, s74, s56
	global_load_lds_dwordx4 v[216:217], off
	v_lshl_add_u64 v[218:219], s[88:89], 0, v[132:133]
	s_mov_b32 m0, s82
	v_lshl_add_u64 v[220:221], s[52:53], 0, v[130:131]
	global_load_lds_dwordx4 v[218:219], off
	v_lshl_add_u64 v[218:219], s[88:89], 0, v[128:129]
	s_add_i32 m0, s82, 0x2000
	s_nop 0
	global_load_lds_dwordx4 v[218:219], off
	v_lshl_add_u64 v[218:219], s[52:53], 0, v[134:135]
	s_mov_b32 m0, s47
	s_nop 0
	global_load_lds_dwordx4 v[218:219], off
	s_mov_b32 m0, s59
	s_nop 0
	global_load_lds_dwordx4 v[220:221], off
	s_waitcnt vmcnt(8)
	s_waitcnt lgkmcnt(0)
	s_setprio 1
	s_barrier
	v_mfma_f32_16x16x32_bf16 v[60:63], v[150:153], v[182:185], v[60:63]
	v_mfma_f32_16x16x32_bf16 v[52:55], v[158:161], v[182:185], v[52:55]
	v_mfma_f32_16x16x32_bf16 v[36:39], v[158:161], v[190:193], v[36:39]
	v_mfma_f32_16x16x32_bf16 v[44:47], v[150:153], v[190:193], v[44:47]
	v_mfma_f32_16x16x32_bf16 v[28:31], v[150:153], v[198:201], v[28:31]
	v_mfma_f32_16x16x32_bf16 v[20:23], v[158:161], v[198:201], v[20:23]
	v_mfma_f32_16x16x32_bf16 v[4:7], v[158:161], v[206:209], v[4:7]
	v_mfma_f32_16x16x32_bf16 v[12:15], v[150:153], v[206:209], v[12:15]
	v_mfma_f32_16x16x32_bf16 v[8:11], v[166:169], v[206:209], v[8:11]
	v_mfma_f32_16x16x32_bf16 v[0:3], v[174:177], v[206:209], v[0:3]
	v_mfma_f32_16x16x32_bf16 v[16:19], v[174:177], v[198:201], v[16:19]
	v_mfma_f32_16x16x32_bf16 v[24:27], v[166:169], v[198:201], v[24:27]
	v_mfma_f32_16x16x32_bf16 v[40:43], v[166:169], v[190:193], v[40:43]
	v_mfma_f32_16x16x32_bf16 v[32:35], v[174:177], v[190:193], v[32:35]
	v_mfma_f32_16x16x32_bf16 v[48:51], v[174:177], v[182:185], v[48:51]
	v_mfma_f32_16x16x32_bf16 v[56:59], v[166:169], v[182:185], v[56:59]
	v_mfma_f32_16x16x32_bf16 v[60:63], v[154:157], v[186:189], v[60:63]
	v_mfma_f32_16x16x32_bf16 v[52:55], v[162:165], v[186:189], v[52:55]
	v_mfma_f32_16x16x32_bf16 v[36:39], v[162:165], v[194:197], v[36:39]
	v_mfma_f32_16x16x32_bf16 v[44:47], v[154:157], v[194:197], v[44:47]
	v_mfma_f32_16x16x32_bf16 v[28:31], v[154:157], v[202:205], v[28:31]
	v_mfma_f32_16x16x32_bf16 v[20:23], v[162:165], v[202:205], v[20:23]
	v_mfma_f32_16x16x32_bf16 v[4:7], v[162:165], v[210:213], v[4:7]
	v_mfma_f32_16x16x32_bf16 v[12:15], v[154:157], v[210:213], v[12:15]
	v_mfma_f32_16x16x32_bf16 v[8:11], v[170:173], v[210:213], v[8:11]
	v_mfma_f32_16x16x32_bf16 v[0:3], v[178:181], v[210:213], v[0:3]
	v_mfma_f32_16x16x32_bf16 v[16:19], v[178:181], v[202:205], v[16:19]
	v_mfma_f32_16x16x32_bf16 v[24:27], v[170:173], v[202:205], v[24:27]
	v_mfma_f32_16x16x32_bf16 v[40:43], v[170:173], v[194:197], v[40:43]
	v_mfma_f32_16x16x32_bf16 v[32:35], v[178:181], v[194:197], v[32:35]
	v_mfma_f32_16x16x32_bf16 v[48:51], v[178:181], v[186:189], v[48:51]
	v_mfma_f32_16x16x32_bf16 v[56:59], v[170:173], v[186:189], v[56:59]
	s_barrier
	s_setprio 0
	s_add_i32 s82, 0, 0x18000
	s_add_i32 s85, 0, 0x1c000
	v_add_u32_e32 v162, s82, v145
	v_add_u32_e32 v178, s85, v145
	ds_read_b128 v[150:153], v162
	ds_read_b128 v[154:157], v162 offset:1024
	ds_read_b128 v[158:161], v162 offset:2048
	ds_read_b128 v[162:165], v162 offset:3072
	ds_read_b128 v[166:169], v178
	ds_read_b128 v[170:173], v178 offset:1024
	ds_read_b128 v[174:177], v178 offset:2048
	ds_read_b128 v[178:181], v178 offset:3072
	s_add_u32 s52, s52, 0x40000
	s_addc_u32 s53, s53, 0
	s_mov_b32 m0, s66
	v_lshl_add_u64 v[222:223], s[52:53], 0, v[134:135]
	ds_read_b128 v[182:185], v149 offset:32768
	ds_read_b128 v[186:189], v149 offset:33792
	ds_read_b128 v[190:193], v149 offset:34816
	ds_read_b128 v[194:197], v149 offset:35840
	ds_read_b128 v[198:201], v149 offset:36864
	ds_read_b128 v[202:205], v149 offset:37888
	ds_read_b128 v[206:209], v149 offset:38912
	ds_read_b128 v[210:213], v149 offset:39936
	global_load_lds_dwordx4 v[222:223], off
	v_lshl_add_u64 v[222:223], s[52:53], 0, v[130:131]
	s_mov_b32 m0, s67
	s_nop 0
	global_load_lds_dwordx4 v[222:223], off
	s_waitcnt vmcnt(8)
	s_waitcnt lgkmcnt(0)
	s_setprio 1
	s_barrier
	v_mfma_f32_16x16x32_bf16 v[124:127], v[150:153], v[182:185], v[124:127]
	v_mfma_f32_16x16x32_bf16 v[116:119], v[158:161], v[182:185], v[116:119]
	v_mfma_f32_16x16x32_bf16 v[100:103], v[158:161], v[190:193], v[100:103]
	v_mfma_f32_16x16x32_bf16 v[108:111], v[150:153], v[190:193], v[108:111]
	v_mfma_f32_16x16x32_bf16 v[92:95], v[150:153], v[198:201], v[92:95]
	v_mfma_f32_16x16x32_bf16 v[84:87], v[158:161], v[198:201], v[84:87]
	v_mfma_f32_16x16x32_bf16 v[68:71], v[158:161], v[206:209], v[68:71]
	v_mfma_f32_16x16x32_bf16 v[76:79], v[150:153], v[206:209], v[76:79]
	v_mfma_f32_16x16x32_bf16 v[72:75], v[166:169], v[206:209], v[72:75]
	v_mfma_f32_16x16x32_bf16 v[64:67], v[174:177], v[206:209], v[64:67]
	v_mfma_f32_16x16x32_bf16 v[80:83], v[174:177], v[198:201], v[80:83]
	v_mfma_f32_16x16x32_bf16 v[88:91], v[166:169], v[198:201], v[88:91]
	v_mfma_f32_16x16x32_bf16 v[104:107], v[166:169], v[190:193], v[104:107]
	v_mfma_f32_16x16x32_bf16 v[96:99], v[174:177], v[190:193], v[96:99]
	v_mfma_f32_16x16x32_bf16 v[112:115], v[174:177], v[182:185], v[112:115]
	v_mfma_f32_16x16x32_bf16 v[120:123], v[166:169], v[182:185], v[120:123]
	v_mfma_f32_16x16x32_bf16 v[124:127], v[154:157], v[186:189], v[124:127]
	v_mfma_f32_16x16x32_bf16 v[116:119], v[162:165], v[186:189], v[116:119]
	v_mfma_f32_16x16x32_bf16 v[100:103], v[162:165], v[194:197], v[100:103]
	v_mfma_f32_16x16x32_bf16 v[108:111], v[154:157], v[194:197], v[108:111]
	v_mfma_f32_16x16x32_bf16 v[92:95], v[154:157], v[202:205], v[92:95]
	v_mfma_f32_16x16x32_bf16 v[84:87], v[162:165], v[202:205], v[84:87]
	v_mfma_f32_16x16x32_bf16 v[68:71], v[162:165], v[210:213], v[68:71]
	v_mfma_f32_16x16x32_bf16 v[76:79], v[154:157], v[210:213], v[76:79]
	v_mfma_f32_16x16x32_bf16 v[72:75], v[170:173], v[210:213], v[72:75]
	v_mfma_f32_16x16x32_bf16 v[64:67], v[178:181], v[210:213], v[64:67]
	v_mfma_f32_16x16x32_bf16 v[80:83], v[178:181], v[202:205], v[80:83]
	v_mfma_f32_16x16x32_bf16 v[88:91], v[170:173], v[202:205], v[88:91]
	v_mfma_f32_16x16x32_bf16 v[104:107], v[170:173], v[194:197], v[104:107]
	v_mfma_f32_16x16x32_bf16 v[96:99], v[178:181], v[194:197], v[96:99]
	v_mfma_f32_16x16x32_bf16 v[112:115], v[178:181], v[186:189], v[112:115]
	v_mfma_f32_16x16x32_bf16 v[120:123], v[170:173], v[186:189], v[120:123]
	s_barrier
	s_setprio 0
	s_add_i32 s52, s82, s56
	v_lshl_add_u64 v[214:215], v[214:215], 0, s[10:11]
	s_mov_b32 m0, s52
	ds_read_b128 v[182:185], v149 offset:49152
	ds_read_b128 v[186:189], v149 offset:50176
	ds_read_b128 v[190:193], v149 offset:51200
	ds_read_b128 v[194:197], v149 offset:52224
	ds_read_b128 v[198:201], v149 offset:53248
	ds_read_b128 v[202:205], v149 offset:54272
	ds_read_b128 v[206:209], v149 offset:55296
	ds_read_b128 v[210:213], v149 offset:56320
	global_load_lds_dwordx4 v[214:215], off
	s_add_i32 m0, s52, 0x2000
	s_add_u32 s50, s50, 0x40080
	v_lshl_add_u64 v[214:215], v[216:217], 0, s[10:11]
	s_addc_u32 s51, s51, 0
	s_add_i32 s52, s85, s56
	global_load_lds_dwordx4 v[214:215], off
	v_lshl_add_u64 v[214:215], s[50:51], 0, v[132:133]
	s_mov_b32 m0, s52
	s_nop 0
	global_load_lds_dwordx4 v[214:215], off
	v_lshl_add_u64 v[214:215], s[50:51], 0, v[128:129]
	s_add_i32 m0, s52, 0x2000
	s_nop 0
	global_load_lds_dwordx4 v[214:215], off
	v_lshl_add_u64 v[214:215], v[218:219], 0, s[10:11]
	s_mov_b32 m0, s69
	s_nop 0
	global_load_lds_dwordx4 v[214:215], off
	v_lshl_add_u64 v[214:215], v[220:221], 0, s[10:11]
	s_mov_b32 m0, s70
	s_nop 0
	global_load_lds_dwordx4 v[214:215], off
	s_waitcnt vmcnt(8)
	s_waitcnt lgkmcnt(0)
	s_setprio 1
	s_barrier
	v_mfma_f32_16x16x32_bf16 v[60:63], v[150:153], v[182:185], v[60:63]
	v_mfma_f32_16x16x32_bf16 v[52:55], v[158:161], v[182:185], v[52:55]
	v_mfma_f32_16x16x32_bf16 v[36:39], v[158:161], v[190:193], v[36:39]
	v_mfma_f32_16x16x32_bf16 v[44:47], v[150:153], v[190:193], v[44:47]
	v_mfma_f32_16x16x32_bf16 v[28:31], v[150:153], v[198:201], v[28:31]
	v_mfma_f32_16x16x32_bf16 v[20:23], v[158:161], v[198:201], v[20:23]
	v_mfma_f32_16x16x32_bf16 v[4:7], v[158:161], v[206:209], v[4:7]
	v_mfma_f32_16x16x32_bf16 v[12:15], v[150:153], v[206:209], v[12:15]
	v_mfma_f32_16x16x32_bf16 v[8:11], v[166:169], v[206:209], v[8:11]
	v_mfma_f32_16x16x32_bf16 v[0:3], v[174:177], v[206:209], v[0:3]
	v_mfma_f32_16x16x32_bf16 v[16:19], v[174:177], v[198:201], v[16:19]
	v_mfma_f32_16x16x32_bf16 v[24:27], v[166:169], v[198:201], v[24:27]
	v_mfma_f32_16x16x32_bf16 v[40:43], v[166:169], v[190:193], v[40:43]
	v_mfma_f32_16x16x32_bf16 v[32:35], v[174:177], v[190:193], v[32:35]
	v_mfma_f32_16x16x32_bf16 v[48:51], v[174:177], v[182:185], v[48:51]
	v_mfma_f32_16x16x32_bf16 v[56:59], v[166:169], v[182:185], v[56:59]
	v_mfma_f32_16x16x32_bf16 v[60:63], v[154:157], v[186:189], v[60:63]
	v_mfma_f32_16x16x32_bf16 v[52:55], v[162:165], v[186:189], v[52:55]
	v_mfma_f32_16x16x32_bf16 v[36:39], v[162:165], v[194:197], v[36:39]
	v_mfma_f32_16x16x32_bf16 v[44:47], v[154:157], v[194:197], v[44:47]
	v_mfma_f32_16x16x32_bf16 v[28:31], v[154:157], v[202:205], v[28:31]
	v_mfma_f32_16x16x32_bf16 v[20:23], v[162:165], v[202:205], v[20:23]
	v_mfma_f32_16x16x32_bf16 v[4:7], v[162:165], v[210:213], v[4:7]
	v_mfma_f32_16x16x32_bf16 v[12:15], v[154:157], v[210:213], v[12:15]
	v_mfma_f32_16x16x32_bf16 v[8:11], v[170:173], v[210:213], v[8:11]
	v_mfma_f32_16x16x32_bf16 v[0:3], v[178:181], v[210:213], v[0:3]
	v_mfma_f32_16x16x32_bf16 v[16:19], v[178:181], v[202:205], v[16:19]
	v_mfma_f32_16x16x32_bf16 v[24:27], v[170:173], v[202:205], v[24:27]
	v_mfma_f32_16x16x32_bf16 v[40:43], v[170:173], v[194:197], v[40:43]
	v_mfma_f32_16x16x32_bf16 v[32:35], v[178:181], v[194:197], v[32:35]
	v_mfma_f32_16x16x32_bf16 v[48:51], v[178:181], v[186:189], v[48:51]
	v_mfma_f32_16x16x32_bf16 v[56:59], v[170:173], v[186:189], v[56:59]
	s_barrier
	s_setprio 0
	s_add_i32 s81, s81, 2
	s_add_u32 s48, s48, 0x100
	s_addc_u32 s49, s49, 0
	s_add_u32 s79, s79, 0x100
	s_addc_u32 s80, s80, 0
	s_cmp_gt_u32 s81, 13
	s_cbranch_scc0 .LBB0_141
	s_and_b64 vcc, exec, s[26:27]
	s_cbranch_vccz .LBB0_144
	s_barrier

.LBB0_220:
	s_add_u32 s95, s52, 0x100
	s_addc_u32 s96, s53, 0
	s_mov_b32 s97, -2
	ds_read_b128 v[88:91], v233
	ds_read_b128 v[92:95], v233 offset:1024
	ds_read_b128 v[112:115], v233 offset:2048
	ds_read_b128 v[116:119], v233 offset:3072
	ds_read_b128 v[132:135], v234
	ds_read_b128 v[136:139], v234 offset:1024
	ds_read_b128 v[152:155], v234 offset:2048
	ds_read_b128 v[156:159], v234 offset:3072
	s_add_u32 s52, s50, 0x100
	s_addc_u32 s53, s51, 0
	s_cmp_eq_u32 s97, 40
	s_cselect_b32 s57, s9, s53
	s_cselect_b32 s56, s8, s52
	s_cselect_b32 s55, s41, s96
	s_cselect_b32 s54, s40, s95
	v_lshl_add_u64 v[216:217], s[50:51], 0, v[196:197]
	s_add_i32 m0, s67, 0xc000
	ds_read_b128 v[160:163], v235
	ds_read_b128 v[164:167], v235 offset:1024
	ds_read_b128 v[168:171], v235 offset:2048
	ds_read_b128 v[172:175], v235 offset:3072
	ds_read_b128 v[176:179], v235 offset:4096
	ds_read_b128 v[180:183], v235 offset:5120
	ds_read_b128 v[208:211], v235 offset:6144
	ds_read_b128 v[212:215], v235 offset:7168
	global_load_lds_dwordx4 v[216:217], off
	v_lshl_add_u64 v[216:217], s[50:51], 0, v[198:199]
	s_add_i32 m0, s67, 0xe000
	s_nop 0
	global_load_lds_dwordx4 v[216:217], off
	s_waitcnt vmcnt(8)
	s_waitcnt lgkmcnt(0)
	s_setprio 1
	s_barrier
	v_mfma_f32_16x16x32_bf16 v[148:151], v[88:91], v[160:163], 0
	v_mfma_f32_16x16x32_bf16 v[144:147], v[112:115], v[160:163], 0
	v_mfma_f32_16x16x32_bf16 v[120:123], v[112:115], v[168:171], 0
	v_mfma_f32_16x16x32_bf16 v[124:127], v[88:91], v[168:171], 0
	v_mfma_f32_16x16x32_bf16 v[100:103], v[88:91], v[176:179], 0
	v_mfma_f32_16x16x32_bf16 v[96:99], v[112:115], v[176:179], 0
	v_mfma_f32_16x16x32_bf16 v[72:75], v[112:115], v[208:211], 0
	v_mfma_f32_16x16x32_bf16 v[76:79], v[88:91], v[208:211], 0
	v_mfma_f32_16x16x32_bf16 v[68:71], v[132:135], v[208:211], 0
	v_mfma_f32_16x16x32_bf16 v[64:67], v[152:155], v[208:211], 0
	v_mfma_f32_16x16x32_bf16 v[80:83], v[152:155], v[176:179], 0
	v_mfma_f32_16x16x32_bf16 v[84:87], v[132:135], v[176:179], 0
	v_mfma_f32_16x16x32_bf16 v[108:111], v[132:135], v[168:171], 0
	v_mfma_f32_16x16x32_bf16 v[104:107], v[152:155], v[168:171], 0
	v_mfma_f32_16x16x32_bf16 v[128:131], v[152:155], v[160:163], 0
	v_mfma_f32_16x16x32_bf16 v[140:143], v[132:135], v[160:163], 0
	v_mfma_f32_16x16x32_bf16 v[148:151], v[92:95], v[164:167], v[148:151]
	v_mfma_f32_16x16x32_bf16 v[144:147], v[116:119], v[164:167], v[144:147]
	v_mfma_f32_16x16x32_bf16 v[120:123], v[116:119], v[172:175], v[120:123]
	v_mfma_f32_16x16x32_bf16 v[124:127], v[92:95], v[172:175], v[124:127]
	v_mfma_f32_16x16x32_bf16 v[100:103], v[92:95], v[180:183], v[100:103]
	v_mfma_f32_16x16x32_bf16 v[96:99], v[116:119], v[180:183], v[96:99]
	v_mfma_f32_16x16x32_bf16 v[72:75], v[116:119], v[212:215], v[72:75]
	v_mfma_f32_16x16x32_bf16 v[76:79], v[92:95], v[212:215], v[76:79]
	v_mfma_f32_16x16x32_bf16 v[68:71], v[136:139], v[212:215], v[68:71]
	v_mfma_f32_16x16x32_bf16 v[64:67], v[156:159], v[212:215], v[64:67]
	v_mfma_f32_16x16x32_bf16 v[80:83], v[156:159], v[180:183], v[80:83]
	v_mfma_f32_16x16x32_bf16 v[84:87], v[136:139], v[180:183], v[84:87]
	v_mfma_f32_16x16x32_bf16 v[108:111], v[136:139], v[172:175], v[108:111]
	v_mfma_f32_16x16x32_bf16 v[104:107], v[156:159], v[172:175], v[104:107]
	v_mfma_f32_16x16x32_bf16 v[128:131], v[156:159], v[164:167], v[128:131]
	v_mfma_f32_16x16x32_bf16 v[140:143], v[136:139], v[164:167], v[140:143]
	s_barrier
	s_setprio 0
	s_add_i32 s50, s82, s66
	v_lshl_add_u64 v[216:217], s[54:55], 0, v[186:187]
	s_mov_b32 m0, s50
	ds_read_b128 v[160:163], v235 offset:16384
	ds_read_b128 v[164:167], v235 offset:17408
	ds_read_b128 v[168:171], v235 offset:18432
	ds_read_b128 v[172:175], v235 offset:19456
	ds_read_b128 v[176:179], v235 offset:20480
	ds_read_b128 v[180:183], v235 offset:21504
	ds_read_b128 v[208:211], v235 offset:22528
	ds_read_b128 v[212:215], v235 offset:23552
	global_load_lds_dwordx4 v[216:217], off
	s_add_i32 m0, s50, 0x2000
	s_add_u32 s50, s54, 0xb0000
	v_lshl_add_u64 v[218:219], s[54:55], 0, v[190:191]
	s_addc_u32 s51, s55, 0
	s_add_i32 vcc_lo, s85, s66
	global_load_lds_dwordx4 v[218:219], off
	v_lshl_add_u64 v[220:221], s[50:51], 0, v[186:187]
	s_mov_b32 m0, vcc_lo
	v_lshl_add_u64 v[222:223], s[56:57], 0, v[188:189]
	global_load_lds_dwordx4 v[220:221], off
	v_lshl_add_u64 v[220:221], s[50:51], 0, v[190:191]
	s_add_i32 m0, vcc_lo, 0x2000
	s_nop 0
	global_load_lds_dwordx4 v[220:221], off
	v_lshl_add_u64 v[220:221], s[56:57], 0, v[184:185]
	s_mov_b32 m0, s67
	s_nop 0
	global_load_lds_dwordx4 v[220:221], off
	s_mov_b32 m0, s68
	s_nop 0
	global_load_lds_dwordx4 v[222:223], off
	s_waitcnt vmcnt(8)
	s_waitcnt lgkmcnt(0)
	s_setprio 1
	s_barrier
	v_mfma_f32_16x16x32_bf16 v[60:63], v[88:91], v[160:163], 0
	v_mfma_f32_16x16x32_bf16 v[56:59], v[112:115], v[160:163], 0
	v_mfma_f32_16x16x32_bf16 v[40:43], v[112:115], v[168:171], 0
	v_mfma_f32_16x16x32_bf16 v[44:47], v[88:91], v[168:171], 0
	v_mfma_f32_16x16x32_bf16 v[28:31], v[88:91], v[176:179], 0
	v_mfma_f32_16x16x32_bf16 v[24:27], v[112:115], v[176:179], 0
	v_mfma_f32_16x16x32_bf16 v[8:11], v[112:115], v[208:211], 0
	v_mfma_f32_16x16x32_bf16 v[12:15], v[88:91], v[208:211], 0
	v_mfma_f32_16x16x32_bf16 v[4:7], v[132:135], v[208:211], 0
	v_mfma_f32_16x16x32_bf16 v[0:3], v[152:155], v[208:211], 0
	v_mfma_f32_16x16x32_bf16 v[16:19], v[152:155], v[176:179], 0
	v_mfma_f32_16x16x32_bf16 v[20:23], v[132:135], v[176:179], 0
	v_mfma_f32_16x16x32_bf16 v[36:39], v[132:135], v[168:171], 0
	v_mfma_f32_16x16x32_bf16 v[32:35], v[152:155], v[168:171], 0
	v_mfma_f32_16x16x32_bf16 v[48:51], v[152:155], v[160:163], 0
	v_mfma_f32_16x16x32_bf16 v[52:55], v[132:135], v[160:163], 0
	v_mfma_f32_16x16x32_bf16 v[60:63], v[92:95], v[164:167], v[60:63]
	v_mfma_f32_16x16x32_bf16 v[56:59], v[116:119], v[164:167], v[56:59]
	v_mfma_f32_16x16x32_bf16 v[40:43], v[116:119], v[172:175], v[40:43]
	v_mfma_f32_16x16x32_bf16 v[44:47], v[92:95], v[172:175], v[44:47]
	v_mfma_f32_16x16x32_bf16 v[28:31], v[92:95], v[180:183], v[28:31]
	v_mfma_f32_16x16x32_bf16 v[24:27], v[116:119], v[180:183], v[24:27]
	v_mfma_f32_16x16x32_bf16 v[8:11], v[116:119], v[212:215], v[8:11]
	v_mfma_f32_16x16x32_bf16 v[12:15], v[92:95], v[212:215], v[12:15]
	v_mfma_f32_16x16x32_bf16 v[4:7], v[136:139], v[212:215], v[4:7]
	v_mfma_f32_16x16x32_bf16 v[0:3], v[156:159], v[212:215], v[0:3]
	v_mfma_f32_16x16x32_bf16 v[16:19], v[156:159], v[180:183], v[16:19]
	v_mfma_f32_16x16x32_bf16 v[20:23], v[136:139], v[180:183], v[20:23]
	v_mfma_f32_16x16x32_bf16 v[36:39], v[136:139], v[172:175], v[36:39]
	v_mfma_f32_16x16x32_bf16 v[32:35], v[156:159], v[172:175], v[32:35]
	v_mfma_f32_16x16x32_bf16 v[48:51], v[156:159], v[164:167], v[48:51]
	v_mfma_f32_16x16x32_bf16 v[52:55], v[136:139], v[164:167], v[52:55]
	s_barrier
	s_setprio 0
	s_add_i32 vcc_lo, 0, 0x18000
	s_add_i32 vcc_hi, 0, 0x1c000
	v_add_u32_e32 v116, vcc_lo, v230
	v_add_u32_e32 v156, vcc_hi, v230
	ds_read_b128 v[88:91], v116
	ds_read_b128 v[92:95], v116 offset:1024
	ds_read_b128 v[112:115], v116 offset:2048
	ds_read_b128 v[116:119], v116 offset:3072
	ds_read_b128 v[132:135], v156
	ds_read_b128 v[136:139], v156 offset:1024
	ds_read_b128 v[152:155], v156 offset:2048
	ds_read_b128 v[156:159], v156 offset:3072
	s_add_u32 s50, s56, 0xb0000
	s_addc_u32 s51, s57, 0
	s_mov_b32 m0, s69
	v_lshl_add_u64 v[224:225], s[50:51], 0, v[184:185]
	ds_read_b128 v[160:163], v235 offset:32768
	ds_read_b128 v[164:167], v235 offset:33792
	ds_read_b128 v[168:171], v235 offset:34816
	ds_read_b128 v[172:175], v235 offset:35840
	ds_read_b128 v[176:179], v235 offset:36864
	ds_read_b128 v[180:183], v235 offset:37888
	ds_read_b128 v[208:211], v235 offset:38912
	ds_read_b128 v[212:215], v235 offset:39936
	global_load_lds_dwordx4 v[224:225], off
	v_lshl_add_u64 v[224:225], s[50:51], 0, v[188:189]
	s_mov_b32 m0, s70
	s_nop 0
	global_load_lds_dwordx4 v[224:225], off
	s_waitcnt vmcnt(8)
	s_waitcnt lgkmcnt(0)
	s_setprio 1
	s_barrier
	v_mfma_f32_16x16x32_bf16 v[148:151], v[88:91], v[160:163], v[148:151]
	v_mfma_f32_16x16x32_bf16 v[144:147], v[112:115], v[160:163], v[144:147]
	v_mfma_f32_16x16x32_bf16 v[120:123], v[112:115], v[168:171], v[120:123]
	v_mfma_f32_16x16x32_bf16 v[124:127], v[88:91], v[168:171], v[124:127]
	v_mfma_f32_16x16x32_bf16 v[100:103], v[88:91], v[176:179], v[100:103]
	v_mfma_f32_16x16x32_bf16 v[96:99], v[112:115], v[176:179], v[96:99]
	v_mfma_f32_16x16x32_bf16 v[72:75], v[112:115], v[208:211], v[72:75]
	v_mfma_f32_16x16x32_bf16 v[76:79], v[88:91], v[208:211], v[76:79]
	v_mfma_f32_16x16x32_bf16 v[68:71], v[132:135], v[208:211], v[68:71]
	v_mfma_f32_16x16x32_bf16 v[64:67], v[152:155], v[208:211], v[64:67]
	v_mfma_f32_16x16x32_bf16 v[80:83], v[152:155], v[176:179], v[80:83]
	v_mfma_f32_16x16x32_bf16 v[84:87], v[132:135], v[176:179], v[84:87]
	v_mfma_f32_16x16x32_bf16 v[108:111], v[132:135], v[168:171], v[108:111]
	v_mfma_f32_16x16x32_bf16 v[104:107], v[152:155], v[168:171], v[104:107]
	v_mfma_f32_16x16x32_bf16 v[128:131], v[152:155], v[160:163], v[128:131]
	v_mfma_f32_16x16x32_bf16 v[140:143], v[132:135], v[160:163], v[140:143]
	v_mfma_f32_16x16x32_bf16 v[148:151], v[92:95], v[164:167], v[148:151]
	v_mfma_f32_16x16x32_bf16 v[144:147], v[116:119], v[164:167], v[144:147]
	v_mfma_f32_16x16x32_bf16 v[120:123], v[116:119], v[172:175], v[120:123]
	v_mfma_f32_16x16x32_bf16 v[124:127], v[92:95], v[172:175], v[124:127]
	v_mfma_f32_16x16x32_bf16 v[100:103], v[92:95], v[180:183], v[100:103]
	v_mfma_f32_16x16x32_bf16 v[96:99], v[116:119], v[180:183], v[96:99]
	v_mfma_f32_16x16x32_bf16 v[72:75], v[116:119], v[212:215], v[72:75]
	v_mfma_f32_16x16x32_bf16 v[76:79], v[92:95], v[212:215], v[76:79]
	v_mfma_f32_16x16x32_bf16 v[68:71], v[136:139], v[212:215], v[68:71]
	v_mfma_f32_16x16x32_bf16 v[64:67], v[156:159], v[212:215], v[64:67]
	v_mfma_f32_16x16x32_bf16 v[80:83], v[156:159], v[180:183], v[80:83]
	v_mfma_f32_16x16x32_bf16 v[84:87], v[136:139], v[180:183], v[84:87]
	v_mfma_f32_16x16x32_bf16 v[108:111], v[136:139], v[172:175], v[108:111]
	v_mfma_f32_16x16x32_bf16 v[104:107], v[156:159], v[172:175], v[104:107]
	v_mfma_f32_16x16x32_bf16 v[128:131], v[156:159], v[164:167], v[128:131]
	v_mfma_f32_16x16x32_bf16 v[140:143], v[136:139], v[164:167], v[140:143]
	s_barrier
	s_setprio 0
	s_add_i32 s50, vcc_lo, s66
	v_lshl_add_u64 v[216:217], v[216:217], 0, s[46:47]
	s_mov_b32 m0, s50
	ds_read_b128 v[160:163], v235 offset:49152
	ds_read_b128 v[164:167], v235 offset:50176
	ds_read_b128 v[168:171], v235 offset:51200
	ds_read_b128 v[172:175], v235 offset:52224
	ds_read_b128 v[176:179], v235 offset:53248
	ds_read_b128 v[180:183], v235 offset:54272
	ds_read_b128 v[208:211], v235 offset:55296
	ds_read_b128 v[212:215], v235 offset:56320
	global_load_lds_dwordx4 v[216:217], off
	s_add_i32 m0, s50, 0x2000
	s_add_u32 s50, s54, 0xb0080
	v_lshl_add_u64 v[216:217], v[218:219], 0, s[46:47]
	s_addc_u32 s51, s55, 0
	s_add_i32 s54, vcc_hi, s66
	global_load_lds_dwordx4 v[216:217], off
	v_lshl_add_u64 v[216:217], s[50:51], 0, v[186:187]
	s_mov_b32 m0, s54
	s_nop 0
	global_load_lds_dwordx4 v[216:217], off
	v_lshl_add_u64 v[216:217], s[50:51], 0, v[190:191]
	s_add_i32 m0, s54, 0x2000
	s_nop 0
	global_load_lds_dwordx4 v[216:217], off
	v_lshl_add_u64 v[216:217], v[220:221], 0, s[46:47]
	s_mov_b32 m0, s74
	s_nop 0
	global_load_lds_dwordx4 v[216:217], off
	v_lshl_add_u64 v[216:217], v[222:223], 0, s[46:47]
	s_mov_b32 m0, s75
	s_nop 0
	global_load_lds_dwordx4 v[216:217], off
	s_waitcnt vmcnt(8)
	s_waitcnt lgkmcnt(0)
	s_setprio 1
	s_barrier
	v_mfma_f32_16x16x32_bf16 v[60:63], v[88:91], v[160:163], v[60:63]
	v_mfma_f32_16x16x32_bf16 v[56:59], v[112:115], v[160:163], v[56:59]
	v_mfma_f32_16x16x32_bf16 v[40:43], v[112:115], v[168:171], v[40:43]
	v_mfma_f32_16x16x32_bf16 v[44:47], v[88:91], v[168:171], v[44:47]
	v_mfma_f32_16x16x32_bf16 v[28:31], v[88:91], v[176:179], v[28:31]
	v_mfma_f32_16x16x32_bf16 v[24:27], v[112:115], v[176:179], v[24:27]
	v_mfma_f32_16x16x32_bf16 v[8:11], v[112:115], v[208:211], v[8:11]
	v_mfma_f32_16x16x32_bf16 v[12:15], v[88:91], v[208:211], v[12:15]
	v_mfma_f32_16x16x32_bf16 v[4:7], v[132:135], v[208:211], v[4:7]
	v_mfma_f32_16x16x32_bf16 v[0:3], v[152:155], v[208:211], v[0:3]
	v_mfma_f32_16x16x32_bf16 v[16:19], v[152:155], v[176:179], v[16:19]
	v_mfma_f32_16x16x32_bf16 v[20:23], v[132:135], v[176:179], v[20:23]
	v_mfma_f32_16x16x32_bf16 v[36:39], v[132:135], v[168:171], v[36:39]
	v_mfma_f32_16x16x32_bf16 v[32:35], v[152:155], v[168:171], v[32:35]
	v_mfma_f32_16x16x32_bf16 v[48:51], v[152:155], v[160:163], v[48:51]
	v_mfma_f32_16x16x32_bf16 v[52:55], v[132:135], v[160:163], v[52:55]
	v_mfma_f32_16x16x32_bf16 v[60:63], v[92:95], v[164:167], v[60:63]
	v_mfma_f32_16x16x32_bf16 v[56:59], v[116:119], v[164:167], v[56:59]
	v_mfma_f32_16x16x32_bf16 v[40:43], v[116:119], v[172:175], v[40:43]
	v_mfma_f32_16x16x32_bf16 v[44:47], v[92:95], v[172:175], v[44:47]
	v_mfma_f32_16x16x32_bf16 v[28:31], v[92:95], v[180:183], v[28:31]
	v_mfma_f32_16x16x32_bf16 v[24:27], v[116:119], v[180:183], v[24:27]
	v_mfma_f32_16x16x32_bf16 v[8:11], v[116:119], v[212:215], v[8:11]
	v_mfma_f32_16x16x32_bf16 v[12:15], v[92:95], v[212:215], v[12:15]
	v_mfma_f32_16x16x32_bf16 v[4:7], v[136:139], v[212:215], v[4:7]
	v_mfma_f32_16x16x32_bf16 v[0:3], v[156:159], v[212:215], v[0:3]
	v_mfma_f32_16x16x32_bf16 v[16:19], v[156:159], v[180:183], v[16:19]
	v_mfma_f32_16x16x32_bf16 v[20:23], v[136:139], v[180:183], v[20:23]
	v_mfma_f32_16x16x32_bf16 v[36:39], v[136:139], v[172:175], v[36:39]
	v_mfma_f32_16x16x32_bf16 v[32:35], v[156:159], v[172:175], v[32:35]
	v_mfma_f32_16x16x32_bf16 v[48:51], v[156:159], v[164:167], v[48:51]
	v_mfma_f32_16x16x32_bf16 v[52:55], v[136:139], v[164:167], v[52:55]
	s_barrier
	s_setprio 0
	s_add_i32 s97, s97, 2
	s_add_u32 s95, s95, 0x100
	s_addc_u32 s96, s96, 0
	s_cmp_gt_u32 s97, 41
	s_mov_b64 s[50:51], s[52:53]
.LBB0_221:
	ds_read_b128 v[88:91], v233
	ds_read_b128 v[92:95], v233 offset:1024
	ds_read_b128 v[112:115], v233 offset:2048
	ds_read_b128 v[116:119], v233 offset:3072
	ds_read_b128 v[132:135], v234
	ds_read_b128 v[136:139], v234 offset:1024
	ds_read_b128 v[152:155], v234 offset:2048
	ds_read_b128 v[156:159], v234 offset:3072
	s_add_u32 s52, s50, 0x100
	s_addc_u32 s53, s51, 0
	s_cmp_eq_u32 s97, 40
	s_cselect_b32 s57, s9, s53
	s_cselect_b32 s56, s8, s52
	s_cselect_b32 s55, s41, s96
	s_cselect_b32 s54, s40, s95
	v_lshl_add_u64 v[216:217], s[50:51], 0, v[196:197]
	s_add_i32 m0, s67, 0xc000
	ds_read_b128 v[160:163], v235
	ds_read_b128 v[164:167], v235 offset:1024
	ds_read_b128 v[168:171], v235 offset:2048
	ds_read_b128 v[172:175], v235 offset:3072
	ds_read_b128 v[176:179], v235 offset:4096
	ds_read_b128 v[180:183], v235 offset:5120
	ds_read_b128 v[208:211], v235 offset:6144
	ds_read_b128 v[212:215], v235 offset:7168
	global_load_lds_dwordx4 v[216:217], off
	v_lshl_add_u64 v[216:217], s[50:51], 0, v[198:199]
	s_add_i32 m0, s67, 0xe000
	s_nop 0
	global_load_lds_dwordx4 v[216:217], off
	s_waitcnt vmcnt(8)
	s_waitcnt lgkmcnt(0)
	s_setprio 1
	s_barrier
	v_mfma_f32_16x16x32_bf16 v[148:151], v[88:91], v[160:163], v[148:151]
	v_mfma_f32_16x16x32_bf16 v[144:147], v[112:115], v[160:163], v[144:147]
	v_mfma_f32_16x16x32_bf16 v[120:123], v[112:115], v[168:171], v[120:123]
	v_mfma_f32_16x16x32_bf16 v[124:127], v[88:91], v[168:171], v[124:127]
	v_mfma_f32_16x16x32_bf16 v[100:103], v[88:91], v[176:179], v[100:103]
	v_mfma_f32_16x16x32_bf16 v[96:99], v[112:115], v[176:179], v[96:99]
	v_mfma_f32_16x16x32_bf16 v[72:75], v[112:115], v[208:211], v[72:75]
	v_mfma_f32_16x16x32_bf16 v[76:79], v[88:91], v[208:211], v[76:79]
	v_mfma_f32_16x16x32_bf16 v[68:71], v[132:135], v[208:211], v[68:71]
	v_mfma_f32_16x16x32_bf16 v[64:67], v[152:155], v[208:211], v[64:67]
	v_mfma_f32_16x16x32_bf16 v[80:83], v[152:155], v[176:179], v[80:83]
	v_mfma_f32_16x16x32_bf16 v[84:87], v[132:135], v[176:179], v[84:87]
	v_mfma_f32_16x16x32_bf16 v[108:111], v[132:135], v[168:171], v[108:111]
	v_mfma_f32_16x16x32_bf16 v[104:107], v[152:155], v[168:171], v[104:107]
	v_mfma_f32_16x16x32_bf16 v[128:131], v[152:155], v[160:163], v[128:131]
	v_mfma_f32_16x16x32_bf16 v[140:143], v[132:135], v[160:163], v[140:143]
	v_mfma_f32_16x16x32_bf16 v[148:151], v[92:95], v[164:167], v[148:151]
	v_mfma_f32_16x16x32_bf16 v[144:147], v[116:119], v[164:167], v[144:147]
	v_mfma_f32_16x16x32_bf16 v[120:123], v[116:119], v[172:175], v[120:123]
	v_mfma_f32_16x16x32_bf16 v[124:127], v[92:95], v[172:175], v[124:127]
	v_mfma_f32_16x16x32_bf16 v[100:103], v[92:95], v[180:183], v[100:103]
	v_mfma_f32_16x16x32_bf16 v[96:99], v[116:119], v[180:183], v[96:99]
	v_mfma_f32_16x16x32_bf16 v[72:75], v[116:119], v[212:215], v[72:75]
	v_mfma_f32_16x16x32_bf16 v[76:79], v[92:95], v[212:215], v[76:79]
	v_mfma_f32_16x16x32_bf16 v[68:71], v[136:139], v[212:215], v[68:71]
	v_mfma_f32_16x16x32_bf16 v[64:67], v[156:159], v[212:215], v[64:67]
	v_mfma_f32_16x16x32_bf16 v[80:83], v[156:159], v[180:183], v[80:83]
	v_mfma_f32_16x16x32_bf16 v[84:87], v[136:139], v[180:183], v[84:87]
	v_mfma_f32_16x16x32_bf16 v[108:111], v[136:139], v[172:175], v[108:111]
	v_mfma_f32_16x16x32_bf16 v[104:107], v[156:159], v[172:175], v[104:107]
	v_mfma_f32_16x16x32_bf16 v[128:131], v[156:159], v[164:167], v[128:131]
	v_mfma_f32_16x16x32_bf16 v[140:143], v[136:139], v[164:167], v[140:143]
	s_barrier
	s_setprio 0
	s_add_i32 s50, s82, s66
	v_lshl_add_u64 v[216:217], s[54:55], 0, v[186:187]
	s_mov_b32 m0, s50
	ds_read_b128 v[160:163], v235 offset:16384
	ds_read_b128 v[164:167], v235 offset:17408
	ds_read_b128 v[168:171], v235 offset:18432
	ds_read_b128 v[172:175], v235 offset:19456
	ds_read_b128 v[176:179], v235 offset:20480
	ds_read_b128 v[180:183], v235 offset:21504
	ds_read_b128 v[208:211], v235 offset:22528
	ds_read_b128 v[212:215], v235 offset:23552
	global_load_lds_dwordx4 v[216:217], off
	s_add_i32 m0, s50, 0x2000
	s_add_u32 s50, s54, 0xb0000
	v_lshl_add_u64 v[218:219], s[54:55], 0, v[190:191]
	s_addc_u32 s51, s55, 0
	s_add_i32 vcc_lo, s85, s66
	global_load_lds_dwordx4 v[218:219], off
	v_lshl_add_u64 v[220:221], s[50:51], 0, v[186:187]
	s_mov_b32 m0, vcc_lo
	v_lshl_add_u64 v[222:223], s[56:57], 0, v[188:189]
	global_load_lds_dwordx4 v[220:221], off
	v_lshl_add_u64 v[220:221], s[50:51], 0, v[190:191]
	s_add_i32 m0, vcc_lo, 0x2000
	s_nop 0
	global_load_lds_dwordx4 v[220:221], off
	v_lshl_add_u64 v[220:221], s[56:57], 0, v[184:185]
	s_mov_b32 m0, s67
	s_nop 0
	global_load_lds_dwordx4 v[220:221], off
	s_mov_b32 m0, s68
	s_nop 0
	global_load_lds_dwordx4 v[222:223], off
	s_waitcnt vmcnt(8)
	s_waitcnt lgkmcnt(0)
	s_setprio 1
	s_barrier
	v_mfma_f32_16x16x32_bf16 v[60:63], v[88:91], v[160:163], v[60:63]
	v_mfma_f32_16x16x32_bf16 v[56:59], v[112:115], v[160:163], v[56:59]
	v_mfma_f32_16x16x32_bf16 v[40:43], v[112:115], v[168:171], v[40:43]
	v_mfma_f32_16x16x32_bf16 v[44:47], v[88:91], v[168:171], v[44:47]
	v_mfma_f32_16x16x32_bf16 v[28:31], v[88:91], v[176:179], v[28:31]
	v_mfma_f32_16x16x32_bf16 v[24:27], v[112:115], v[176:179], v[24:27]
	v_mfma_f32_16x16x32_bf16 v[8:11], v[112:115], v[208:211], v[8:11]
	v_mfma_f32_16x16x32_bf16 v[12:15], v[88:91], v[208:211], v[12:15]
	v_mfma_f32_16x16x32_bf16 v[4:7], v[132:135], v[208:211], v[4:7]
	v_mfma_f32_16x16x32_bf16 v[0:3], v[152:155], v[208:211], v[0:3]
	v_mfma_f32_16x16x32_bf16 v[16:19], v[152:155], v[176:179], v[16:19]
	v_mfma_f32_16x16x32_bf16 v[20:23], v[132:135], v[176:179], v[20:23]
	v_mfma_f32_16x16x32_bf16 v[36:39], v[132:135], v[168:171], v[36:39]
	v_mfma_f32_16x16x32_bf16 v[32:35], v[152:155], v[168:171], v[32:35]
	v_mfma_f32_16x16x32_bf16 v[48:51], v[152:155], v[160:163], v[48:51]
	v_mfma_f32_16x16x32_bf16 v[52:55], v[132:135], v[160:163], v[52:55]
	v_mfma_f32_16x16x32_bf16 v[60:63], v[92:95], v[164:167], v[60:63]
	v_mfma_f32_16x16x32_bf16 v[56:59], v[116:119], v[164:167], v[56:59]
	v_mfma_f32_16x16x32_bf16 v[40:43], v[116:119], v[172:175], v[40:43]
	v_mfma_f32_16x16x32_bf16 v[44:47], v[92:95], v[172:175], v[44:47]
	v_mfma_f32_16x16x32_bf16 v[28:31], v[92:95], v[180:183], v[28:31]
	v_mfma_f32_16x16x32_bf16 v[24:27], v[116:119], v[180:183], v[24:27]
	v_mfma_f32_16x16x32_bf16 v[8:11], v[116:119], v[212:215], v[8:11]
	v_mfma_f32_16x16x32_bf16 v[12:15], v[92:95], v[212:215], v[12:15]
	v_mfma_f32_16x16x32_bf16 v[4:7], v[136:139], v[212:215], v[4:7]
	v_mfma_f32_16x16x32_bf16 v[0:3], v[156:159], v[212:215], v[0:3]
	v_mfma_f32_16x16x32_bf16 v[16:19], v[156:159], v[180:183], v[16:19]
	v_mfma_f32_16x16x32_bf16 v[20:23], v[136:139], v[180:183], v[20:23]
	v_mfma_f32_16x16x32_bf16 v[36:39], v[136:139], v[172:175], v[36:39]
	v_mfma_f32_16x16x32_bf16 v[32:35], v[156:159], v[172:175], v[32:35]
	v_mfma_f32_16x16x32_bf16 v[48:51], v[156:159], v[164:167], v[48:51]
	v_mfma_f32_16x16x32_bf16 v[52:55], v[136:139], v[164:167], v[52:55]
	s_barrier
	s_setprio 0
	s_add_i32 vcc_lo, 0, 0x18000
	s_add_i32 vcc_hi, 0, 0x1c000
	v_add_u32_e32 v116, vcc_lo, v230
	v_add_u32_e32 v156, vcc_hi, v230
	ds_read_b128 v[88:91], v116
	ds_read_b128 v[92:95], v116 offset:1024
	ds_read_b128 v[112:115], v116 offset:2048
	ds_read_b128 v[116:119], v116 offset:3072
	ds_read_b128 v[132:135], v156
	ds_read_b128 v[136:139], v156 offset:1024
	ds_read_b128 v[152:155], v156 offset:2048
	ds_read_b128 v[156:159], v156 offset:3072
	s_add_u32 s50, s56, 0xb0000
	s_addc_u32 s51, s57, 0
	s_mov_b32 m0, s69
	v_lshl_add_u64 v[224:225], s[50:51], 0, v[184:185]
	ds_read_b128 v[160:163], v235 offset:32768
	ds_read_b128 v[164:167], v235 offset:33792
	ds_read_b128 v[168:171], v235 offset:34816
	ds_read_b128 v[172:175], v235 offset:35840
	ds_read_b128 v[176:179], v235 offset:36864
	ds_read_b128 v[180:183], v235 offset:37888
	ds_read_b128 v[208:211], v235 offset:38912
	ds_read_b128 v[212:215], v235 offset:39936
	global_load_lds_dwordx4 v[224:225], off
	v_lshl_add_u64 v[224:225], s[50:51], 0, v[188:189]
	s_mov_b32 m0, s70
	s_nop 0
	global_load_lds_dwordx4 v[224:225], off
	s_waitcnt vmcnt(8)
	s_waitcnt lgkmcnt(0)
	s_setprio 1
	s_barrier
	v_mfma_f32_16x16x32_bf16 v[148:151], v[88:91], v[160:163], v[148:151]
	v_mfma_f32_16x16x32_bf16 v[144:147], v[112:115], v[160:163], v[144:147]
	v_mfma_f32_16x16x32_bf16 v[120:123], v[112:115], v[168:171], v[120:123]
	v_mfma_f32_16x16x32_bf16 v[124:127], v[88:91], v[168:171], v[124:127]
	v_mfma_f32_16x16x32_bf16 v[100:103], v[88:91], v[176:179], v[100:103]
	v_mfma_f32_16x16x32_bf16 v[96:99], v[112:115], v[176:179], v[96:99]
	v_mfma_f32_16x16x32_bf16 v[72:75], v[112:115], v[208:211], v[72:75]
	v_mfma_f32_16x16x32_bf16 v[76:79], v[88:91], v[208:211], v[76:79]
	v_mfma_f32_16x16x32_bf16 v[68:71], v[132:135], v[208:211], v[68:71]
	v_mfma_f32_16x16x32_bf16 v[64:67], v[152:155], v[208:211], v[64:67]
	v_mfma_f32_16x16x32_bf16 v[80:83], v[152:155], v[176:179], v[80:83]
	v_mfma_f32_16x16x32_bf16 v[84:87], v[132:135], v[176:179], v[84:87]
	v_mfma_f32_16x16x32_bf16 v[108:111], v[132:135], v[168:171], v[108:111]
	v_mfma_f32_16x16x32_bf16 v[104:107], v[152:155], v[168:171], v[104:107]
	v_mfma_f32_16x16x32_bf16 v[128:131], v[152:155], v[160:163], v[128:131]
	v_mfma_f32_16x16x32_bf16 v[140:143], v[132:135], v[160:163], v[140:143]
	v_mfma_f32_16x16x32_bf16 v[148:151], v[92:95], v[164:167], v[148:151]
	v_mfma_f32_16x16x32_bf16 v[144:147], v[116:119], v[164:167], v[144:147]
	v_mfma_f32_16x16x32_bf16 v[120:123], v[116:119], v[172:175], v[120:123]
	v_mfma_f32_16x16x32_bf16 v[124:127], v[92:95], v[172:175], v[124:127]
	v_mfma_f32_16x16x32_bf16 v[100:103], v[92:95], v[180:183], v[100:103]
	v_mfma_f32_16x16x32_bf16 v[96:99], v[116:119], v[180:183], v[96:99]
	v_mfma_f32_16x16x32_bf16 v[72:75], v[116:119], v[212:215], v[72:75]
	v_mfma_f32_16x16x32_bf16 v[76:79], v[92:95], v[212:215], v[76:79]
	v_mfma_f32_16x16x32_bf16 v[68:71], v[136:139], v[212:215], v[68:71]
	v_mfma_f32_16x16x32_bf16 v[64:67], v[156:159], v[212:215], v[64:67]
	v_mfma_f32_16x16x32_bf16 v[80:83], v[156:159], v[180:183], v[80:83]
	v_mfma_f32_16x16x32_bf16 v[84:87], v[136:139], v[180:183], v[84:87]
	v_mfma_f32_16x16x32_bf16 v[108:111], v[136:139], v[172:175], v[108:111]
	v_mfma_f32_16x16x32_bf16 v[104:107], v[156:159], v[172:175], v[104:107]
	v_mfma_f32_16x16x32_bf16 v[128:131], v[156:159], v[164:167], v[128:131]
	v_mfma_f32_16x16x32_bf16 v[140:143], v[136:139], v[164:167], v[140:143]
	s_barrier
	s_setprio 0
	s_add_i32 s50, vcc_lo, s66
	v_lshl_add_u64 v[216:217], v[216:217], 0, s[46:47]
	s_mov_b32 m0, s50
	ds_read_b128 v[160:163], v235 offset:49152
	ds_read_b128 v[164:167], v235 offset:50176
	ds_read_b128 v[168:171], v235 offset:51200
	ds_read_b128 v[172:175], v235 offset:52224
	ds_read_b128 v[176:179], v235 offset:53248
	ds_read_b128 v[180:183], v235 offset:54272
	ds_read_b128 v[208:211], v235 offset:55296
	ds_read_b128 v[212:215], v235 offset:56320
	global_load_lds_dwordx4 v[216:217], off
	s_add_i32 m0, s50, 0x2000
	s_add_u32 s50, s54, 0xb0080
	v_lshl_add_u64 v[216:217], v[218:219], 0, s[46:47]
	s_addc_u32 s51, s55, 0
	s_add_i32 s54, vcc_hi, s66
	global_load_lds_dwordx4 v[216:217], off
	v_lshl_add_u64 v[216:217], s[50:51], 0, v[186:187]
	s_mov_b32 m0, s54
	s_nop 0
	global_load_lds_dwordx4 v[216:217], off
	v_lshl_add_u64 v[216:217], s[50:51], 0, v[190:191]
	s_add_i32 m0, s54, 0x2000
	s_nop 0
	global_load_lds_dwordx4 v[216:217], off
	v_lshl_add_u64 v[216:217], v[220:221], 0, s[46:47]
	s_mov_b32 m0, s74
	s_nop 0
	global_load_lds_dwordx4 v[216:217], off
	v_lshl_add_u64 v[216:217], v[222:223], 0, s[46:47]
	s_mov_b32 m0, s75
	s_nop 0
	global_load_lds_dwordx4 v[216:217], off
	s_waitcnt vmcnt(8)
	s_waitcnt lgkmcnt(0)
	s_setprio 1
	s_barrier
	v_mfma_f32_16x16x32_bf16 v[60:63], v[88:91], v[160:163], v[60:63]
	v_mfma_f32_16x16x32_bf16 v[56:59], v[112:115], v[160:163], v[56:59]
	v_mfma_f32_16x16x32_bf16 v[40:43], v[112:115], v[168:171], v[40:43]
	v_mfma_f32_16x16x32_bf16 v[44:47], v[88:91], v[168:171], v[44:47]
	v_mfma_f32_16x16x32_bf16 v[28:31], v[88:91], v[176:179], v[28:31]
	v_mfma_f32_16x16x32_bf16 v[24:27], v[112:115], v[176:179], v[24:27]
	v_mfma_f32_16x16x32_bf16 v[8:11], v[112:115], v[208:211], v[8:11]
	v_mfma_f32_16x16x32_bf16 v[12:15], v[88:91], v[208:211], v[12:15]
	v_mfma_f32_16x16x32_bf16 v[4:7], v[132:135], v[208:211], v[4:7]
	v_mfma_f32_16x16x32_bf16 v[0:3], v[152:155], v[208:211], v[0:3]
	v_mfma_f32_16x16x32_bf16 v[16:19], v[152:155], v[176:179], v[16:19]
	v_mfma_f32_16x16x32_bf16 v[20:23], v[132:135], v[176:179], v[20:23]
	v_mfma_f32_16x16x32_bf16 v[36:39], v[132:135], v[168:171], v[36:39]
	v_mfma_f32_16x16x32_bf16 v[32:35], v[152:155], v[168:171], v[32:35]
	v_mfma_f32_16x16x32_bf16 v[48:51], v[152:155], v[160:163], v[48:51]
	v_mfma_f32_16x16x32_bf16 v[52:55], v[132:135], v[160:163], v[52:55]
	v_mfma_f32_16x16x32_bf16 v[60:63], v[92:95], v[164:167], v[60:63]
	v_mfma_f32_16x16x32_bf16 v[56:59], v[116:119], v[164:167], v[56:59]
	v_mfma_f32_16x16x32_bf16 v[40:43], v[116:119], v[172:175], v[40:43]
	v_mfma_f32_16x16x32_bf16 v[44:47], v[92:95], v[172:175], v[44:47]
	v_mfma_f32_16x16x32_bf16 v[28:31], v[92:95], v[180:183], v[28:31]
	v_mfma_f32_16x16x32_bf16 v[24:27], v[116:119], v[180:183], v[24:27]
	v_mfma_f32_16x16x32_bf16 v[8:11], v[116:119], v[212:215], v[8:11]
	v_mfma_f32_16x16x32_bf16 v[12:15], v[92:95], v[212:215], v[12:15]
	v_mfma_f32_16x16x32_bf16 v[4:7], v[136:139], v[212:215], v[4:7]
	v_mfma_f32_16x16x32_bf16 v[0:3], v[156:159], v[212:215], v[0:3]
	v_mfma_f32_16x16x32_bf16 v[16:19], v[156:159], v[180:183], v[16:19]
	v_mfma_f32_16x16x32_bf16 v[20:23], v[136:139], v[180:183], v[20:23]
	v_mfma_f32_16x16x32_bf16 v[36:39], v[136:139], v[172:175], v[36:39]
	v_mfma_f32_16x16x32_bf16 v[32:35], v[156:159], v[172:175], v[32:35]
	v_mfma_f32_16x16x32_bf16 v[48:51], v[156:159], v[164:167], v[48:51]
	v_mfma_f32_16x16x32_bf16 v[52:55], v[136:139], v[164:167], v[52:55]
	s_barrier
	s_setprio 0
	s_add_i32 s97, s97, 2
	s_add_u32 s95, s95, 0x100
	s_addc_u32 s96, s96, 0
	s_cmp_gt_u32 s97, 41
	s_mov_b64 s[50:51], s[52:53]
	s_cbranch_scc0 .LBB0_221
	s_and_b64 vcc, exec, s[48:49]
	s_cbranch_vccz .LBB0_224
	s_barrier

.LBB0_312:
	s_ashr_i32 s43, s42, 31
	s_lshl_b64 s[46:47], s[42:43], 19
	s_add_u32 s46, s62, s46
	s_addc_u32 s47, s63, s47
	s_and_b64 s[48:49], s[4:5], exec
	s_cselect_b32 s10, s47, s53
	s_cselect_b32 s43, s46, s52
	s_ashr_i32 s45, s44, 31
	s_lshl_b64 s[48:49], s[44:45], 19
	s_add_u32 s48, s70, s48
	s_addc_u32 s49, s71, s49
	s_and_b64 s[56:57], s[4:5], exec
	s_cselect_b32 s45, s49, s55
	s_cselect_b32 s51, s48, s54
	s_add_u32 s52, s52, 0x40080
	s_addc_u32 s53, s53, 0
	s_add_u32 s67, s54, 0x100
	s_addc_u32 s68, s55, 0
	s_mov_b32 s69, -2
	ds_read_b128 v[128:131], v179
	ds_read_b128 v[132:135], v179 offset:1024
	ds_read_b128 v[136:139], v179 offset:2048
	ds_read_b128 v[140:143], v179 offset:3072
	ds_read_b128 v[188:191], v181
	ds_read_b128 v[192:195], v181 offset:1024
	ds_read_b128 v[196:199], v181 offset:2048
	ds_read_b128 v[200:203], v181 offset:3072
	s_add_u32 s54, s52, 0xfffc0080
	s_addc_u32 s55, s53, -1
	s_cmp_eq_u32 s69, 12
	s_cselect_b32 s57, s10, s55
	s_cselect_b32 s56, s43, s54
	s_cselect_b32 s55, s45, s68
	s_cselect_b32 s54, s51, s67
	v_lshl_add_u64 v[238:239], s[52:53], 0, v[162:163]
	s_add_i32 m0, s75, 0xc000
	ds_read_b128 v[204:207], v183
	ds_read_b128 v[208:211], v183 offset:1024
	ds_read_b128 v[212:215], v183 offset:2048
	ds_read_b128 v[216:219], v183 offset:3072
	ds_read_b128 v[220:223], v183 offset:4096
	ds_read_b128 v[224:227], v183 offset:5120
	ds_read_b128 v[230:233], v183 offset:6144
	ds_read_b128 v[234:237], v183 offset:7168
	global_load_lds_dwordx4 v[238:239], off
	v_lshl_add_u64 v[238:239], s[52:53], 0, v[164:165]
	s_add_i32 m0, s75, 0xe000
	s_nop 0
	global_load_lds_dwordx4 v[238:239], off
	s_waitcnt vmcnt(8)
	s_waitcnt lgkmcnt(0)
	s_setprio 1
	s_barrier
	v_mfma_f32_16x16x32_bf16 v[124:127], v[128:131], v[204:207], 0
	v_mfma_f32_16x16x32_bf16 v[120:123], v[136:139], v[204:207], 0
	v_mfma_f32_16x16x32_bf16 v[104:107], v[136:139], v[212:215], 0
	v_mfma_f32_16x16x32_bf16 v[108:111], v[128:131], v[212:215], 0
	v_mfma_f32_16x16x32_bf16 v[92:95], v[128:131], v[220:223], 0
	v_mfma_f32_16x16x32_bf16 v[88:91], v[136:139], v[220:223], 0
	v_mfma_f32_16x16x32_bf16 v[72:75], v[136:139], v[230:233], 0
	v_mfma_f32_16x16x32_bf16 v[76:79], v[128:131], v[230:233], 0
	v_mfma_f32_16x16x32_bf16 v[68:71], v[188:191], v[230:233], 0
	v_mfma_f32_16x16x32_bf16 v[64:67], v[196:199], v[230:233], 0
	v_mfma_f32_16x16x32_bf16 v[80:83], v[196:199], v[220:223], 0
	v_mfma_f32_16x16x32_bf16 v[84:87], v[188:191], v[220:223], 0
	v_mfma_f32_16x16x32_bf16 v[100:103], v[188:191], v[212:215], 0
	v_mfma_f32_16x16x32_bf16 v[96:99], v[196:199], v[212:215], 0
	v_mfma_f32_16x16x32_bf16 v[112:115], v[196:199], v[204:207], 0
	v_mfma_f32_16x16x32_bf16 v[116:119], v[188:191], v[204:207], 0
	v_mfma_f32_16x16x32_bf16 v[124:127], v[132:135], v[208:211], v[124:127]
	v_mfma_f32_16x16x32_bf16 v[120:123], v[140:143], v[208:211], v[120:123]
	v_mfma_f32_16x16x32_bf16 v[104:107], v[140:143], v[216:219], v[104:107]
	v_mfma_f32_16x16x32_bf16 v[108:111], v[132:135], v[216:219], v[108:111]
	v_mfma_f32_16x16x32_bf16 v[92:95], v[132:135], v[224:227], v[92:95]
	v_mfma_f32_16x16x32_bf16 v[88:91], v[140:143], v[224:227], v[88:91]
	v_mfma_f32_16x16x32_bf16 v[72:75], v[140:143], v[234:237], v[72:75]
	v_mfma_f32_16x16x32_bf16 v[76:79], v[132:135], v[234:237], v[76:79]
	v_mfma_f32_16x16x32_bf16 v[68:71], v[192:195], v[234:237], v[68:71]
	v_mfma_f32_16x16x32_bf16 v[64:67], v[200:203], v[234:237], v[64:67]
	v_mfma_f32_16x16x32_bf16 v[80:83], v[200:203], v[224:227], v[80:83]
	v_mfma_f32_16x16x32_bf16 v[84:87], v[192:195], v[224:227], v[84:87]
	v_mfma_f32_16x16x32_bf16 v[100:103], v[192:195], v[216:219], v[100:103]
	v_mfma_f32_16x16x32_bf16 v[96:99], v[200:203], v[216:219], v[96:99]
	v_mfma_f32_16x16x32_bf16 v[112:115], v[200:203], v[208:211], v[112:115]
	v_mfma_f32_16x16x32_bf16 v[116:119], v[192:195], v[208:211], v[116:119]
	s_barrier
	s_setprio 0
	s_add_i32 vcc_lo, s92, s72
	v_lshl_add_u64 v[238:239], s[54:55], 0, v[148:149]
	s_mov_b32 m0, vcc_lo
	ds_read_b128 v[204:207], v183 offset:16384
	ds_read_b128 v[208:211], v183 offset:17408
	ds_read_b128 v[212:215], v183 offset:18432
	ds_read_b128 v[216:219], v183 offset:19456
	ds_read_b128 v[220:223], v183 offset:20480
	ds_read_b128 v[224:227], v183 offset:21504
	ds_read_b128 v[230:233], v183 offset:22528
	ds_read_b128 v[234:237], v183 offset:23552
	global_load_lds_dwordx4 v[238:239], off
	s_add_i32 m0, vcc_lo, 0x2000
	s_add_u32 vcc_lo, s54, 0x40000
	v_lshl_add_u64 v[240:241], s[54:55], 0, v[144:145]
	s_addc_u32 vcc_hi, s55, 0
	s_add_i32 s83, s93, s72
	global_load_lds_dwordx4 v[240:241], off
	v_lshl_add_u64 v[242:243], vcc, 0, v[148:149]
	s_mov_b32 m0, s83
	v_lshl_add_u64 v[244:245], s[56:57], 0, v[146:147]
	global_load_lds_dwordx4 v[242:243], off
	v_lshl_add_u64 v[242:243], vcc, 0, v[144:145]
	s_add_i32 m0, s83, 0x2000
	s_nop 0
	global_load_lds_dwordx4 v[242:243], off
	v_lshl_add_u64 v[242:243], s[56:57], 0, v[150:151]
	s_mov_b32 m0, s75
	s_nop 0
	global_load_lds_dwordx4 v[242:243], off
	s_mov_b32 m0, s76
	s_nop 0
	global_load_lds_dwordx4 v[244:245], off
	s_waitcnt vmcnt(8)
	s_waitcnt lgkmcnt(0)
	s_setprio 1
	s_barrier
	v_mfma_f32_16x16x32_bf16 v[60:63], v[128:131], v[204:207], 0
	v_mfma_f32_16x16x32_bf16 v[56:59], v[136:139], v[204:207], 0
	v_mfma_f32_16x16x32_bf16 v[40:43], v[136:139], v[212:215], 0
	v_mfma_f32_16x16x32_bf16 v[44:47], v[128:131], v[212:215], 0
	v_mfma_f32_16x16x32_bf16 v[28:31], v[128:131], v[220:223], 0
	v_mfma_f32_16x16x32_bf16 v[24:27], v[136:139], v[220:223], 0
	v_mfma_f32_16x16x32_bf16 v[8:11], v[136:139], v[230:233], 0
	v_mfma_f32_16x16x32_bf16 v[12:15], v[128:131], v[230:233], 0
	v_mfma_f32_16x16x32_bf16 v[4:7], v[188:191], v[230:233], 0
	v_mfma_f32_16x16x32_bf16 v[0:3], v[196:199], v[230:233], 0
	v_mfma_f32_16x16x32_bf16 v[16:19], v[196:199], v[220:223], 0
	v_mfma_f32_16x16x32_bf16 v[20:23], v[188:191], v[220:223], 0
	v_mfma_f32_16x16x32_bf16 v[36:39], v[188:191], v[212:215], 0
	v_mfma_f32_16x16x32_bf16 v[32:35], v[196:199], v[212:215], 0
	v_mfma_f32_16x16x32_bf16 v[48:51], v[196:199], v[204:207], 0
	v_mfma_f32_16x16x32_bf16 v[52:55], v[188:191], v[204:207], 0
	v_mfma_f32_16x16x32_bf16 v[60:63], v[132:135], v[208:211], v[60:63]
	v_mfma_f32_16x16x32_bf16 v[56:59], v[140:143], v[208:211], v[56:59]
	v_mfma_f32_16x16x32_bf16 v[40:43], v[140:143], v[216:219], v[40:43]
	v_mfma_f32_16x16x32_bf16 v[44:47], v[132:135], v[216:219], v[44:47]
	v_mfma_f32_16x16x32_bf16 v[28:31], v[132:135], v[224:227], v[28:31]
	v_mfma_f32_16x16x32_bf16 v[24:27], v[140:143], v[224:227], v[24:27]
	v_mfma_f32_16x16x32_bf16 v[8:11], v[140:143], v[234:237], v[8:11]
	v_mfma_f32_16x16x32_bf16 v[12:15], v[132:135], v[234:237], v[12:15]
	v_mfma_f32_16x16x32_bf16 v[4:7], v[192:195], v[234:237], v[4:7]
	v_mfma_f32_16x16x32_bf16 v[0:3], v[200:203], v[234:237], v[0:3]
	v_mfma_f32_16x16x32_bf16 v[16:19], v[200:203], v[224:227], v[16:19]
	v_mfma_f32_16x16x32_bf16 v[20:23], v[192:195], v[224:227], v[20:23]
	v_mfma_f32_16x16x32_bf16 v[36:39], v[192:195], v[216:219], v[36:39]
	v_mfma_f32_16x16x32_bf16 v[32:35], v[200:203], v[216:219], v[32:35]
	v_mfma_f32_16x16x32_bf16 v[48:51], v[200:203], v[208:211], v[48:51]
	v_mfma_f32_16x16x32_bf16 v[52:55], v[192:195], v[208:211], v[52:55]
	s_barrier
	s_setprio 0
	s_add_i32 s83, 0, 0x18000
	s_add_i32 vcc_lo, 0, 0x1c000
	v_add_u32_e32 v140, s83, v157
	v_add_u32_e32 v171, vcc_lo, v157
	ds_read_b128 v[128:131], v140
	ds_read_b128 v[132:135], v140 offset:1024
	ds_read_b128 v[136:139], v140 offset:2048
	ds_read_b128 v[140:143], v140 offset:3072
	ds_read_b128 v[188:191], v171
	ds_read_b128 v[192:195], v171 offset:1024
	ds_read_b128 v[196:199], v171 offset:2048
	ds_read_b128 v[200:203], v171 offset:3072
	s_add_u32 s56, s56, 0x40000
	s_addc_u32 s57, s57, 0
	s_mov_b32 m0, s77
	v_lshl_add_u64 v[246:247], s[56:57], 0, v[150:151]
	ds_read_b128 v[204:207], v183 offset:32768
	ds_read_b128 v[208:211], v183 offset:33792
	ds_read_b128 v[212:215], v183 offset:34816
	ds_read_b128 v[216:219], v183 offset:35840
	ds_read_b128 v[220:223], v183 offset:36864
	ds_read_b128 v[224:227], v183 offset:37888
	ds_read_b128 v[230:233], v183 offset:38912
	ds_read_b128 v[234:237], v183 offset:39936
	global_load_lds_dwordx4 v[246:247], off
	v_lshl_add_u64 v[246:247], s[56:57], 0, v[146:147]
	s_mov_b32 m0, s78
	s_nop 0
	global_load_lds_dwordx4 v[246:247], off
	s_waitcnt vmcnt(8)
	s_waitcnt lgkmcnt(0)
	s_setprio 1
	s_barrier
	v_mfma_f32_16x16x32_bf16 v[124:127], v[128:131], v[204:207], v[124:127]
	v_mfma_f32_16x16x32_bf16 v[120:123], v[136:139], v[204:207], v[120:123]
	v_mfma_f32_16x16x32_bf16 v[104:107], v[136:139], v[212:215], v[104:107]
	v_mfma_f32_16x16x32_bf16 v[108:111], v[128:131], v[212:215], v[108:111]
	v_mfma_f32_16x16x32_bf16 v[92:95], v[128:131], v[220:223], v[92:95]
	v_mfma_f32_16x16x32_bf16 v[88:91], v[136:139], v[220:223], v[88:91]
	v_mfma_f32_16x16x32_bf16 v[72:75], v[136:139], v[230:233], v[72:75]
	v_mfma_f32_16x16x32_bf16 v[76:79], v[128:131], v[230:233], v[76:79]
	v_mfma_f32_16x16x32_bf16 v[68:71], v[188:191], v[230:233], v[68:71]
	v_mfma_f32_16x16x32_bf16 v[64:67], v[196:199], v[230:233], v[64:67]
	v_mfma_f32_16x16x32_bf16 v[80:83], v[196:199], v[220:223], v[80:83]
	v_mfma_f32_16x16x32_bf16 v[84:87], v[188:191], v[220:223], v[84:87]
	v_mfma_f32_16x16x32_bf16 v[100:103], v[188:191], v[212:215], v[100:103]
	v_mfma_f32_16x16x32_bf16 v[96:99], v[196:199], v[212:215], v[96:99]
	v_mfma_f32_16x16x32_bf16 v[112:115], v[196:199], v[204:207], v[112:115]
	v_mfma_f32_16x16x32_bf16 v[116:119], v[188:191], v[204:207], v[116:119]
	v_mfma_f32_16x16x32_bf16 v[124:127], v[132:135], v[208:211], v[124:127]
	v_mfma_f32_16x16x32_bf16 v[120:123], v[140:143], v[208:211], v[120:123]
	v_mfma_f32_16x16x32_bf16 v[104:107], v[140:143], v[216:219], v[104:107]
	v_mfma_f32_16x16x32_bf16 v[108:111], v[132:135], v[216:219], v[108:111]
	v_mfma_f32_16x16x32_bf16 v[92:95], v[132:135], v[224:227], v[92:95]
	v_mfma_f32_16x16x32_bf16 v[88:91], v[140:143], v[224:227], v[88:91]
	v_mfma_f32_16x16x32_bf16 v[72:75], v[140:143], v[234:237], v[72:75]
	v_mfma_f32_16x16x32_bf16 v[76:79], v[132:135], v[234:237], v[76:79]
	v_mfma_f32_16x16x32_bf16 v[68:71], v[192:195], v[234:237], v[68:71]
	v_mfma_f32_16x16x32_bf16 v[64:67], v[200:203], v[234:237], v[64:67]
	v_mfma_f32_16x16x32_bf16 v[80:83], v[200:203], v[224:227], v[80:83]
	v_mfma_f32_16x16x32_bf16 v[84:87], v[192:195], v[224:227], v[84:87]
	v_mfma_f32_16x16x32_bf16 v[100:103], v[192:195], v[216:219], v[100:103]
	v_mfma_f32_16x16x32_bf16 v[96:99], v[200:203], v[216:219], v[96:99]
	v_mfma_f32_16x16x32_bf16 v[112:115], v[200:203], v[208:211], v[112:115]
	v_mfma_f32_16x16x32_bf16 v[116:119], v[192:195], v[208:211], v[116:119]
	s_barrier
	s_setprio 0
	s_add_i32 s56, s83, s72
	v_lshl_add_u64 v[238:239], v[238:239], 0, s[38:39]
	s_mov_b32 m0, s56
	ds_read_b128 v[204:207], v183 offset:49152
	ds_read_b128 v[208:211], v183 offset:50176
	ds_read_b128 v[212:215], v183 offset:51200
	ds_read_b128 v[216:219], v183 offset:52224
	ds_read_b128 v[220:223], v183 offset:53248
	ds_read_b128 v[224:227], v183 offset:54272
	ds_read_b128 v[230:233], v183 offset:55296
	ds_read_b128 v[234:237], v183 offset:56320
	global_load_lds_dwordx4 v[238:239], off
	s_add_i32 m0, s56, 0x2000
	s_add_u32 s54, s54, 0x40080
	v_lshl_add_u64 v[238:239], v[240:241], 0, s[38:39]
	s_addc_u32 s55, s55, 0
	s_add_i32 s56, vcc_lo, s72
	global_load_lds_dwordx4 v[238:239], off
	v_lshl_add_u64 v[238:239], s[54:55], 0, v[148:149]
	s_mov_b32 m0, s56
	s_nop 0
	global_load_lds_dwordx4 v[238:239], off
	v_lshl_add_u64 v[238:239], s[54:55], 0, v[144:145]
	s_add_i32 m0, s56, 0x2000
	s_nop 0
	global_load_lds_dwordx4 v[238:239], off
	v_lshl_add_u64 v[238:239], v[242:243], 0, s[38:39]
	s_mov_b32 m0, s87
	s_nop 0
	global_load_lds_dwordx4 v[238:239], off
	v_lshl_add_u64 v[238:239], v[244:245], 0, s[38:39]
	s_mov_b32 m0, s88
	s_nop 0
	global_load_lds_dwordx4 v[238:239], off
	s_waitcnt vmcnt(8)
	s_waitcnt lgkmcnt(0)
	s_setprio 1
	s_barrier
	v_mfma_f32_16x16x32_bf16 v[60:63], v[128:131], v[204:207], v[60:63]
	v_mfma_f32_16x16x32_bf16 v[56:59], v[136:139], v[204:207], v[56:59]
	v_mfma_f32_16x16x32_bf16 v[40:43], v[136:139], v[212:215], v[40:43]
	v_mfma_f32_16x16x32_bf16 v[44:47], v[128:131], v[212:215], v[44:47]
	v_mfma_f32_16x16x32_bf16 v[28:31], v[128:131], v[220:223], v[28:31]
	v_mfma_f32_16x16x32_bf16 v[24:27], v[136:139], v[220:223], v[24:27]
	v_mfma_f32_16x16x32_bf16 v[8:11], v[136:139], v[230:233], v[8:11]
	v_mfma_f32_16x16x32_bf16 v[12:15], v[128:131], v[230:233], v[12:15]
	v_mfma_f32_16x16x32_bf16 v[4:7], v[188:191], v[230:233], v[4:7]
	v_mfma_f32_16x16x32_bf16 v[0:3], v[196:199], v[230:233], v[0:3]
	v_mfma_f32_16x16x32_bf16 v[16:19], v[196:199], v[220:223], v[16:19]
	v_mfma_f32_16x16x32_bf16 v[20:23], v[188:191], v[220:223], v[20:23]
	v_mfma_f32_16x16x32_bf16 v[36:39], v[188:191], v[212:215], v[36:39]
	v_mfma_f32_16x16x32_bf16 v[32:35], v[196:199], v[212:215], v[32:35]
	v_mfma_f32_16x16x32_bf16 v[48:51], v[196:199], v[204:207], v[48:51]
	v_mfma_f32_16x16x32_bf16 v[52:55], v[188:191], v[204:207], v[52:55]
	v_mfma_f32_16x16x32_bf16 v[60:63], v[132:135], v[208:211], v[60:63]
	v_mfma_f32_16x16x32_bf16 v[56:59], v[140:143], v[208:211], v[56:59]
	v_mfma_f32_16x16x32_bf16 v[40:43], v[140:143], v[216:219], v[40:43]
	v_mfma_f32_16x16x32_bf16 v[44:47], v[132:135], v[216:219], v[44:47]
	v_mfma_f32_16x16x32_bf16 v[28:31], v[132:135], v[224:227], v[28:31]
	v_mfma_f32_16x16x32_bf16 v[24:27], v[140:143], v[224:227], v[24:27]
	v_mfma_f32_16x16x32_bf16 v[8:11], v[140:143], v[234:237], v[8:11]
	v_mfma_f32_16x16x32_bf16 v[12:15], v[132:135], v[234:237], v[12:15]
	v_mfma_f32_16x16x32_bf16 v[4:7], v[192:195], v[234:237], v[4:7]
	v_mfma_f32_16x16x32_bf16 v[0:3], v[200:203], v[234:237], v[0:3]
	v_mfma_f32_16x16x32_bf16 v[16:19], v[200:203], v[224:227], v[16:19]
	v_mfma_f32_16x16x32_bf16 v[20:23], v[192:195], v[224:227], v[20:23]
	v_mfma_f32_16x16x32_bf16 v[36:39], v[192:195], v[216:219], v[36:39]
	v_mfma_f32_16x16x32_bf16 v[32:35], v[200:203], v[216:219], v[32:35]
	v_mfma_f32_16x16x32_bf16 v[48:51], v[200:203], v[208:211], v[48:51]
	v_mfma_f32_16x16x32_bf16 v[52:55], v[192:195], v[208:211], v[52:55]
	s_barrier
	s_setprio 0
	s_add_i32 s69, s69, 2
	s_add_u32 s52, s52, 0x100
	s_addc_u32 s53, s53, 0
	s_add_u32 s67, s67, 0x100
	s_addc_u32 s68, s68, 0
	s_cmp_gt_u32 s69, 13
.LBB0_313:
	ds_read_b128 v[128:131], v179
	ds_read_b128 v[132:135], v179 offset:1024
	ds_read_b128 v[136:139], v179 offset:2048
	ds_read_b128 v[140:143], v179 offset:3072
	ds_read_b128 v[188:191], v181
	ds_read_b128 v[192:195], v181 offset:1024
	ds_read_b128 v[196:199], v181 offset:2048
	ds_read_b128 v[200:203], v181 offset:3072
	s_add_u32 s54, s52, 0xfffc0080
	s_addc_u32 s55, s53, -1
	s_cmp_eq_u32 s69, 12
	s_cselect_b32 s57, s10, s55
	s_cselect_b32 s56, s43, s54
	s_cselect_b32 s55, s45, s68
	s_cselect_b32 s54, s51, s67
	v_lshl_add_u64 v[238:239], s[52:53], 0, v[162:163]
	s_add_i32 m0, s75, 0xc000
	ds_read_b128 v[204:207], v183
	ds_read_b128 v[208:211], v183 offset:1024
	ds_read_b128 v[212:215], v183 offset:2048
	ds_read_b128 v[216:219], v183 offset:3072
	ds_read_b128 v[220:223], v183 offset:4096
	ds_read_b128 v[224:227], v183 offset:5120
	ds_read_b128 v[230:233], v183 offset:6144
	ds_read_b128 v[234:237], v183 offset:7168
	global_load_lds_dwordx4 v[238:239], off
	v_lshl_add_u64 v[238:239], s[52:53], 0, v[164:165]
	s_add_i32 m0, s75, 0xe000
	s_nop 0
	global_load_lds_dwordx4 v[238:239], off
	s_waitcnt vmcnt(8)
	s_waitcnt lgkmcnt(0)
	s_setprio 1
	s_barrier
	v_mfma_f32_16x16x32_bf16 v[124:127], v[128:131], v[204:207], v[124:127]
	v_mfma_f32_16x16x32_bf16 v[120:123], v[136:139], v[204:207], v[120:123]
	v_mfma_f32_16x16x32_bf16 v[104:107], v[136:139], v[212:215], v[104:107]
	v_mfma_f32_16x16x32_bf16 v[108:111], v[128:131], v[212:215], v[108:111]
	v_mfma_f32_16x16x32_bf16 v[92:95], v[128:131], v[220:223], v[92:95]
	v_mfma_f32_16x16x32_bf16 v[88:91], v[136:139], v[220:223], v[88:91]
	v_mfma_f32_16x16x32_bf16 v[72:75], v[136:139], v[230:233], v[72:75]
	v_mfma_f32_16x16x32_bf16 v[76:79], v[128:131], v[230:233], v[76:79]
	v_mfma_f32_16x16x32_bf16 v[68:71], v[188:191], v[230:233], v[68:71]
	v_mfma_f32_16x16x32_bf16 v[64:67], v[196:199], v[230:233], v[64:67]
	v_mfma_f32_16x16x32_bf16 v[80:83], v[196:199], v[220:223], v[80:83]
	v_mfma_f32_16x16x32_bf16 v[84:87], v[188:191], v[220:223], v[84:87]
	v_mfma_f32_16x16x32_bf16 v[100:103], v[188:191], v[212:215], v[100:103]
	v_mfma_f32_16x16x32_bf16 v[96:99], v[196:199], v[212:215], v[96:99]
	v_mfma_f32_16x16x32_bf16 v[112:115], v[196:199], v[204:207], v[112:115]
	v_mfma_f32_16x16x32_bf16 v[116:119], v[188:191], v[204:207], v[116:119]
	v_mfma_f32_16x16x32_bf16 v[124:127], v[132:135], v[208:211], v[124:127]
	v_mfma_f32_16x16x32_bf16 v[120:123], v[140:143], v[208:211], v[120:123]
	v_mfma_f32_16x16x32_bf16 v[104:107], v[140:143], v[216:219], v[104:107]
	v_mfma_f32_16x16x32_bf16 v[108:111], v[132:135], v[216:219], v[108:111]
	v_mfma_f32_16x16x32_bf16 v[92:95], v[132:135], v[224:227], v[92:95]
	v_mfma_f32_16x16x32_bf16 v[88:91], v[140:143], v[224:227], v[88:91]
	v_mfma_f32_16x16x32_bf16 v[72:75], v[140:143], v[234:237], v[72:75]
	v_mfma_f32_16x16x32_bf16 v[76:79], v[132:135], v[234:237], v[76:79]
	v_mfma_f32_16x16x32_bf16 v[68:71], v[192:195], v[234:237], v[68:71]
	v_mfma_f32_16x16x32_bf16 v[64:67], v[200:203], v[234:237], v[64:67]
	v_mfma_f32_16x16x32_bf16 v[80:83], v[200:203], v[224:227], v[80:83]
	v_mfma_f32_16x16x32_bf16 v[84:87], v[192:195], v[224:227], v[84:87]
	v_mfma_f32_16x16x32_bf16 v[100:103], v[192:195], v[216:219], v[100:103]
	v_mfma_f32_16x16x32_bf16 v[96:99], v[200:203], v[216:219], v[96:99]
	v_mfma_f32_16x16x32_bf16 v[112:115], v[200:203], v[208:211], v[112:115]
	v_mfma_f32_16x16x32_bf16 v[116:119], v[192:195], v[208:211], v[116:119]
	s_barrier
	s_setprio 0
	s_add_i32 vcc_lo, s92, s72
	v_lshl_add_u64 v[238:239], s[54:55], 0, v[148:149]
	s_mov_b32 m0, vcc_lo
	ds_read_b128 v[204:207], v183 offset:16384
	ds_read_b128 v[208:211], v183 offset:17408
	ds_read_b128 v[212:215], v183 offset:18432
	ds_read_b128 v[216:219], v183 offset:19456
	ds_read_b128 v[220:223], v183 offset:20480
	ds_read_b128 v[224:227], v183 offset:21504
	ds_read_b128 v[230:233], v183 offset:22528
	ds_read_b128 v[234:237], v183 offset:23552
	global_load_lds_dwordx4 v[238:239], off
	s_add_i32 m0, vcc_lo, 0x2000
	s_add_u32 vcc_lo, s54, 0x40000
	v_lshl_add_u64 v[240:241], s[54:55], 0, v[144:145]
	s_addc_u32 vcc_hi, s55, 0
	s_add_i32 s83, s93, s72
	global_load_lds_dwordx4 v[240:241], off
	v_lshl_add_u64 v[242:243], vcc, 0, v[148:149]
	s_mov_b32 m0, s83
	v_lshl_add_u64 v[244:245], s[56:57], 0, v[146:147]
	global_load_lds_dwordx4 v[242:243], off
	v_lshl_add_u64 v[242:243], vcc, 0, v[144:145]
	s_add_i32 m0, s83, 0x2000
	s_nop 0
	global_load_lds_dwordx4 v[242:243], off
	v_lshl_add_u64 v[242:243], s[56:57], 0, v[150:151]
	s_mov_b32 m0, s75
	s_nop 0
	global_load_lds_dwordx4 v[242:243], off
	s_mov_b32 m0, s76
	s_nop 0
	global_load_lds_dwordx4 v[244:245], off
	s_waitcnt vmcnt(8)
	s_waitcnt lgkmcnt(0)
	s_setprio 1
	s_barrier
	v_mfma_f32_16x16x32_bf16 v[60:63], v[128:131], v[204:207], v[60:63]
	v_mfma_f32_16x16x32_bf16 v[56:59], v[136:139], v[204:207], v[56:59]
	v_mfma_f32_16x16x32_bf16 v[40:43], v[136:139], v[212:215], v[40:43]
	v_mfma_f32_16x16x32_bf16 v[44:47], v[128:131], v[212:215], v[44:47]
	v_mfma_f32_16x16x32_bf16 v[28:31], v[128:131], v[220:223], v[28:31]
	v_mfma_f32_16x16x32_bf16 v[24:27], v[136:139], v[220:223], v[24:27]
	v_mfma_f32_16x16x32_bf16 v[8:11], v[136:139], v[230:233], v[8:11]
	v_mfma_f32_16x16x32_bf16 v[12:15], v[128:131], v[230:233], v[12:15]
	v_mfma_f32_16x16x32_bf16 v[4:7], v[188:191], v[230:233], v[4:7]
	v_mfma_f32_16x16x32_bf16 v[0:3], v[196:199], v[230:233], v[0:3]
	v_mfma_f32_16x16x32_bf16 v[16:19], v[196:199], v[220:223], v[16:19]
	v_mfma_f32_16x16x32_bf16 v[20:23], v[188:191], v[220:223], v[20:23]
	v_mfma_f32_16x16x32_bf16 v[36:39], v[188:191], v[212:215], v[36:39]
	v_mfma_f32_16x16x32_bf16 v[32:35], v[196:199], v[212:215], v[32:35]
	v_mfma_f32_16x16x32_bf16 v[48:51], v[196:199], v[204:207], v[48:51]
	v_mfma_f32_16x16x32_bf16 v[52:55], v[188:191], v[204:207], v[52:55]
	v_mfma_f32_16x16x32_bf16 v[60:63], v[132:135], v[208:211], v[60:63]
	v_mfma_f32_16x16x32_bf16 v[56:59], v[140:143], v[208:211], v[56:59]
	v_mfma_f32_16x16x32_bf16 v[40:43], v[140:143], v[216:219], v[40:43]
	v_mfma_f32_16x16x32_bf16 v[44:47], v[132:135], v[216:219], v[44:47]
	v_mfma_f32_16x16x32_bf16 v[28:31], v[132:135], v[224:227], v[28:31]
	v_mfma_f32_16x16x32_bf16 v[24:27], v[140:143], v[224:227], v[24:27]
	v_mfma_f32_16x16x32_bf16 v[8:11], v[140:143], v[234:237], v[8:11]
	v_mfma_f32_16x16x32_bf16 v[12:15], v[132:135], v[234:237], v[12:15]
	v_mfma_f32_16x16x32_bf16 v[4:7], v[192:195], v[234:237], v[4:7]
	v_mfma_f32_16x16x32_bf16 v[0:3], v[200:203], v[234:237], v[0:3]
	v_mfma_f32_16x16x32_bf16 v[16:19], v[200:203], v[224:227], v[16:19]
	v_mfma_f32_16x16x32_bf16 v[20:23], v[192:195], v[224:227], v[20:23]
	v_mfma_f32_16x16x32_bf16 v[36:39], v[192:195], v[216:219], v[36:39]
	v_mfma_f32_16x16x32_bf16 v[32:35], v[200:203], v[216:219], v[32:35]
	v_mfma_f32_16x16x32_bf16 v[48:51], v[200:203], v[208:211], v[48:51]
	v_mfma_f32_16x16x32_bf16 v[52:55], v[192:195], v[208:211], v[52:55]
	s_barrier
	s_setprio 0
	s_add_i32 s83, 0, 0x18000
	s_add_i32 vcc_lo, 0, 0x1c000
	v_add_u32_e32 v140, s83, v157
	v_add_u32_e32 v171, vcc_lo, v157
	ds_read_b128 v[128:131], v140
	ds_read_b128 v[132:135], v140 offset:1024
	ds_read_b128 v[136:139], v140 offset:2048
	ds_read_b128 v[140:143], v140 offset:3072
	ds_read_b128 v[188:191], v171
	ds_read_b128 v[192:195], v171 offset:1024
	ds_read_b128 v[196:199], v171 offset:2048
	ds_read_b128 v[200:203], v171 offset:3072
	s_add_u32 s56, s56, 0x40000
	s_addc_u32 s57, s57, 0
	s_mov_b32 m0, s77
	v_lshl_add_u64 v[246:247], s[56:57], 0, v[150:151]
	ds_read_b128 v[204:207], v183 offset:32768
	ds_read_b128 v[208:211], v183 offset:33792
	ds_read_b128 v[212:215], v183 offset:34816
	ds_read_b128 v[216:219], v183 offset:35840
	ds_read_b128 v[220:223], v183 offset:36864
	ds_read_b128 v[224:227], v183 offset:37888
	ds_read_b128 v[230:233], v183 offset:38912
	ds_read_b128 v[234:237], v183 offset:39936
	global_load_lds_dwordx4 v[246:247], off
	v_lshl_add_u64 v[246:247], s[56:57], 0, v[146:147]
	s_mov_b32 m0, s78
	s_nop 0
	global_load_lds_dwordx4 v[246:247], off
	s_waitcnt vmcnt(8)
	s_waitcnt lgkmcnt(0)
	s_setprio 1
	s_barrier
	v_mfma_f32_16x16x32_bf16 v[124:127], v[128:131], v[204:207], v[124:127]
	v_mfma_f32_16x16x32_bf16 v[120:123], v[136:139], v[204:207], v[120:123]
	v_mfma_f32_16x16x32_bf16 v[104:107], v[136:139], v[212:215], v[104:107]
	v_mfma_f32_16x16x32_bf16 v[108:111], v[128:131], v[212:215], v[108:111]
	v_mfma_f32_16x16x32_bf16 v[92:95], v[128:131], v[220:223], v[92:95]
	v_mfma_f32_16x16x32_bf16 v[88:91], v[136:139], v[220:223], v[88:91]
	v_mfma_f32_16x16x32_bf16 v[72:75], v[136:139], v[230:233], v[72:75]
	v_mfma_f32_16x16x32_bf16 v[76:79], v[128:131], v[230:233], v[76:79]
	v_mfma_f32_16x16x32_bf16 v[68:71], v[188:191], v[230:233], v[68:71]
	v_mfma_f32_16x16x32_bf16 v[64:67], v[196:199], v[230:233], v[64:67]
	v_mfma_f32_16x16x32_bf16 v[80:83], v[196:199], v[220:223], v[80:83]
	v_mfma_f32_16x16x32_bf16 v[84:87], v[188:191], v[220:223], v[84:87]
	v_mfma_f32_16x16x32_bf16 v[100:103], v[188:191], v[212:215], v[100:103]
	v_mfma_f32_16x16x32_bf16 v[96:99], v[196:199], v[212:215], v[96:99]
	v_mfma_f32_16x16x32_bf16 v[112:115], v[196:199], v[204:207], v[112:115]
	v_mfma_f32_16x16x32_bf16 v[116:119], v[188:191], v[204:207], v[116:119]
	v_mfma_f32_16x16x32_bf16 v[124:127], v[132:135], v[208:211], v[124:127]
	v_mfma_f32_16x16x32_bf16 v[120:123], v[140:143], v[208:211], v[120:123]
	v_mfma_f32_16x16x32_bf16 v[104:107], v[140:143], v[216:219], v[104:107]
	v_mfma_f32_16x16x32_bf16 v[108:111], v[132:135], v[216:219], v[108:111]
	v_mfma_f32_16x16x32_bf16 v[92:95], v[132:135], v[224:227], v[92:95]
	v_mfma_f32_16x16x32_bf16 v[88:91], v[140:143], v[224:227], v[88:91]
	v_mfma_f32_16x16x32_bf16 v[72:75], v[140:143], v[234:237], v[72:75]
	v_mfma_f32_16x16x32_bf16 v[76:79], v[132:135], v[234:237], v[76:79]
	v_mfma_f32_16x16x32_bf16 v[68:71], v[192:195], v[234:237], v[68:71]
	v_mfma_f32_16x16x32_bf16 v[64:67], v[200:203], v[234:237], v[64:67]
	v_mfma_f32_16x16x32_bf16 v[80:83], v[200:203], v[224:227], v[80:83]
	v_mfma_f32_16x16x32_bf16 v[84:87], v[192:195], v[224:227], v[84:87]
	v_mfma_f32_16x16x32_bf16 v[100:103], v[192:195], v[216:219], v[100:103]
	v_mfma_f32_16x16x32_bf16 v[96:99], v[200:203], v[216:219], v[96:99]
	v_mfma_f32_16x16x32_bf16 v[112:115], v[200:203], v[208:211], v[112:115]
	v_mfma_f32_16x16x32_bf16 v[116:119], v[192:195], v[208:211], v[116:119]
	s_barrier
	s_setprio 0
	s_add_i32 s56, s83, s72
	v_lshl_add_u64 v[238:239], v[238:239], 0, s[38:39]
	s_mov_b32 m0, s56
	ds_read_b128 v[204:207], v183 offset:49152
	ds_read_b128 v[208:211], v183 offset:50176
	ds_read_b128 v[212:215], v183 offset:51200
	ds_read_b128 v[216:219], v183 offset:52224
	ds_read_b128 v[220:223], v183 offset:53248
	ds_read_b128 v[224:227], v183 offset:54272
	ds_read_b128 v[230:233], v183 offset:55296
	ds_read_b128 v[234:237], v183 offset:56320
	global_load_lds_dwordx4 v[238:239], off
	s_add_i32 m0, s56, 0x2000
	s_add_u32 s54, s54, 0x40080
	v_lshl_add_u64 v[238:239], v[240:241], 0, s[38:39]
	s_addc_u32 s55, s55, 0
	s_add_i32 s56, vcc_lo, s72
	global_load_lds_dwordx4 v[238:239], off
	v_lshl_add_u64 v[238:239], s[54:55], 0, v[148:149]
	s_mov_b32 m0, s56
	s_nop 0
	global_load_lds_dwordx4 v[238:239], off
	v_lshl_add_u64 v[238:239], s[54:55], 0, v[144:145]
	s_add_i32 m0, s56, 0x2000
	s_nop 0
	global_load_lds_dwordx4 v[238:239], off
	v_lshl_add_u64 v[238:239], v[242:243], 0, s[38:39]
	s_mov_b32 m0, s87
	s_nop 0
	global_load_lds_dwordx4 v[238:239], off
	v_lshl_add_u64 v[238:239], v[244:245], 0, s[38:39]
	s_mov_b32 m0, s88
	s_nop 0
	global_load_lds_dwordx4 v[238:239], off
	s_waitcnt vmcnt(8)
	s_waitcnt lgkmcnt(0)
	s_setprio 1
	s_barrier
	v_mfma_f32_16x16x32_bf16 v[60:63], v[128:131], v[204:207], v[60:63]
	v_mfma_f32_16x16x32_bf16 v[56:59], v[136:139], v[204:207], v[56:59]
	v_mfma_f32_16x16x32_bf16 v[40:43], v[136:139], v[212:215], v[40:43]
	v_mfma_f32_16x16x32_bf16 v[44:47], v[128:131], v[212:215], v[44:47]
	v_mfma_f32_16x16x32_bf16 v[28:31], v[128:131], v[220:223], v[28:31]
	v_mfma_f32_16x16x32_bf16 v[24:27], v[136:139], v[220:223], v[24:27]
	v_mfma_f32_16x16x32_bf16 v[8:11], v[136:139], v[230:233], v[8:11]
	v_mfma_f32_16x16x32_bf16 v[12:15], v[128:131], v[230:233], v[12:15]
	v_mfma_f32_16x16x32_bf16 v[4:7], v[188:191], v[230:233], v[4:7]
	v_mfma_f32_16x16x32_bf16 v[0:3], v[196:199], v[230:233], v[0:3]
	v_mfma_f32_16x16x32_bf16 v[16:19], v[196:199], v[220:223], v[16:19]
	v_mfma_f32_16x16x32_bf16 v[20:23], v[188:191], v[220:223], v[20:23]
	v_mfma_f32_16x16x32_bf16 v[36:39], v[188:191], v[212:215], v[36:39]
	v_mfma_f32_16x16x32_bf16 v[32:35], v[196:199], v[212:215], v[32:35]
	v_mfma_f32_16x16x32_bf16 v[48:51], v[196:199], v[204:207], v[48:51]
	v_mfma_f32_16x16x32_bf16 v[52:55], v[188:191], v[204:207], v[52:55]
	v_mfma_f32_16x16x32_bf16 v[60:63], v[132:135], v[208:211], v[60:63]
	v_mfma_f32_16x16x32_bf16 v[56:59], v[140:143], v[208:211], v[56:59]
	v_mfma_f32_16x16x32_bf16 v[40:43], v[140:143], v[216:219], v[40:43]
	v_mfma_f32_16x16x32_bf16 v[44:47], v[132:135], v[216:219], v[44:47]
	v_mfma_f32_16x16x32_bf16 v[28:31], v[132:135], v[224:227], v[28:31]
	v_mfma_f32_16x16x32_bf16 v[24:27], v[140:143], v[224:227], v[24:27]
	v_mfma_f32_16x16x32_bf16 v[8:11], v[140:143], v[234:237], v[8:11]
	v_mfma_f32_16x16x32_bf16 v[12:15], v[132:135], v[234:237], v[12:15]
	v_mfma_f32_16x16x32_bf16 v[4:7], v[192:195], v[234:237], v[4:7]
	v_mfma_f32_16x16x32_bf16 v[0:3], v[200:203], v[234:237], v[0:3]
	v_mfma_f32_16x16x32_bf16 v[16:19], v[200:203], v[224:227], v[16:19]
	v_mfma_f32_16x16x32_bf16 v[20:23], v[192:195], v[224:227], v[20:23]
	v_mfma_f32_16x16x32_bf16 v[36:39], v[192:195], v[216:219], v[36:39]
	v_mfma_f32_16x16x32_bf16 v[32:35], v[200:203], v[216:219], v[32:35]
	v_mfma_f32_16x16x32_bf16 v[48:51], v[200:203], v[208:211], v[48:51]
	v_mfma_f32_16x16x32_bf16 v[52:55], v[192:195], v[208:211], v[52:55]
	s_barrier
	s_setprio 0
	s_add_i32 s69, s69, 2
	s_add_u32 s52, s52, 0x100
	s_addc_u32 s53, s53, 0
	s_add_u32 s67, s67, 0x100
	s_addc_u32 s68, s68, 0
	s_cmp_gt_u32 s69, 13
	s_cbranch_scc0 .LBB0_313
	s_and_b64 vcc, exec, s[40:41]
	s_cbranch_vccz .LBB0_316
	s_barrier

.LBB0_667:
	s_ashr_i32 s23, s22, 31
	s_lshl_b64 s[38:39], s[22:23], 19
	s_add_u32 s38, s26, s38
	s_addc_u32 s39, s27, s39
	s_and_b64 s[40:41], s[6:7], exec
	s_cselect_b32 s23, s39, s45
	s_cselect_b32 s43, s38, s44
	s_ashr_i32 s37, s36, 31
	s_lshl_b64 s[40:41], s[36:37], 19
	s_add_u32 s40, s50, s40
	s_addc_u32 s41, s51, s41
	s_and_b64 s[48:49], s[6:7], exec
	s_cselect_b32 s37, s41, s47
	s_cselect_b32 s92, s40, s46
	s_add_u32 s44, s44, 0x40080
	s_addc_u32 s45, s45, 0
	s_add_u32 s93, s46, 0x100
	s_addc_u32 s94, s47, 0
	s_mov_b32 s95, -2
	s_waitcnt lgkmcnt(0)
	ds_read_b128 v[80:83], v216
	ds_read_b128 v[84:87], v216 offset:1024
	ds_read_b128 v[104:107], v216 offset:2048
	ds_read_b128 v[108:111], v216 offset:3072
	ds_read_b128 v[128:131], v217
	ds_read_b128 v[132:135], v217 offset:1024
	ds_read_b128 v[152:155], v217 offset:2048
	ds_read_b128 v[156:159], v217 offset:3072
	s_add_u32 s46, s44, 0xfffc0080
	s_addc_u32 s47, s45, -1
	s_cmp_eq_u32 s95, 12
	s_cselect_b32 s49, s23, s47
	s_cselect_b32 s48, s43, s46
	s_cselect_b32 s47, s37, s94
	s_cselect_b32 s46, s92, s93
	v_lshl_add_u64 v[224:225], s[44:45], 0, v[194:195]
	s_add_i32 m0, s53, 0xc000
	ds_read_b128 v[160:163], v218
	ds_read_b128 v[164:167], v218 offset:1024
	ds_read_b128 v[168:171], v218 offset:2048
	ds_read_b128 v[172:175], v218 offset:3072
	ds_read_b128 v[176:179], v218 offset:4096
	ds_read_b128 v[180:183], v218 offset:5120
	ds_read_b128 v[208:211], v218 offset:6144
	ds_read_b128 v[220:223], v218 offset:7168
	global_load_lds_dwordx4 v[224:225], off
	v_lshl_add_u64 v[224:225], s[44:45], 0, v[196:197]
	s_add_i32 m0, s53, 0xe000
	s_nop 0
	global_load_lds_dwordx4 v[224:225], off
	s_waitcnt vmcnt(8)
	s_waitcnt lgkmcnt(0)
	s_setprio 1
	s_barrier
	v_mfma_f32_16x16x32_bf16 v[148:151], v[80:83], v[160:163], 0
	v_mfma_f32_16x16x32_bf16 v[144:147], v[104:107], v[160:163], 0
	v_mfma_f32_16x16x32_bf16 v[120:123], v[104:107], v[168:171], 0
	v_mfma_f32_16x16x32_bf16 v[124:127], v[80:83], v[168:171], 0
	v_mfma_f32_16x16x32_bf16 v[100:103], v[80:83], v[176:179], 0
	v_mfma_f32_16x16x32_bf16 v[96:99], v[104:107], v[176:179], 0
	v_mfma_f32_16x16x32_bf16 v[72:75], v[104:107], v[208:211], 0
	v_mfma_f32_16x16x32_bf16 v[76:79], v[80:83], v[208:211], 0
	v_mfma_f32_16x16x32_bf16 v[68:71], v[128:131], v[208:211], 0
	v_mfma_f32_16x16x32_bf16 v[64:67], v[152:155], v[208:211], 0
	v_mfma_f32_16x16x32_bf16 v[88:91], v[152:155], v[176:179], 0
	v_mfma_f32_16x16x32_bf16 v[92:95], v[128:131], v[176:179], 0
	v_mfma_f32_16x16x32_bf16 v[116:119], v[128:131], v[168:171], 0
	v_mfma_f32_16x16x32_bf16 v[112:115], v[152:155], v[168:171], 0
	v_mfma_f32_16x16x32_bf16 v[136:139], v[152:155], v[160:163], 0
	v_mfma_f32_16x16x32_bf16 v[140:143], v[128:131], v[160:163], 0
	v_mfma_f32_16x16x32_bf16 v[148:151], v[84:87], v[164:167], v[148:151]
	v_mfma_f32_16x16x32_bf16 v[144:147], v[108:111], v[164:167], v[144:147]
	v_mfma_f32_16x16x32_bf16 v[120:123], v[108:111], v[172:175], v[120:123]
	v_mfma_f32_16x16x32_bf16 v[124:127], v[84:87], v[172:175], v[124:127]
	v_mfma_f32_16x16x32_bf16 v[100:103], v[84:87], v[180:183], v[100:103]
	v_mfma_f32_16x16x32_bf16 v[96:99], v[108:111], v[180:183], v[96:99]
	v_mfma_f32_16x16x32_bf16 v[72:75], v[108:111], v[220:223], v[72:75]
	v_mfma_f32_16x16x32_bf16 v[76:79], v[84:87], v[220:223], v[76:79]
	v_mfma_f32_16x16x32_bf16 v[68:71], v[132:135], v[220:223], v[68:71]
	v_mfma_f32_16x16x32_bf16 v[64:67], v[156:159], v[220:223], v[64:67]
	v_mfma_f32_16x16x32_bf16 v[88:91], v[156:159], v[180:183], v[88:91]
	v_mfma_f32_16x16x32_bf16 v[92:95], v[132:135], v[180:183], v[92:95]
	v_mfma_f32_16x16x32_bf16 v[116:119], v[132:135], v[172:175], v[116:119]
	v_mfma_f32_16x16x32_bf16 v[112:115], v[156:159], v[172:175], v[112:115]
	v_mfma_f32_16x16x32_bf16 v[136:139], v[156:159], v[164:167], v[136:139]
	v_mfma_f32_16x16x32_bf16 v[140:143], v[132:135], v[164:167], v[140:143]
	s_barrier
	s_setprio 0
	s_add_i32 s83, s78, s52
	v_lshl_add_u64 v[224:225], s[46:47], 0, v[186:187]
	s_mov_b32 m0, s83
	ds_read_b128 v[160:163], v218 offset:16384
	ds_read_b128 v[164:167], v218 offset:17408
	ds_read_b128 v[168:171], v218 offset:18432
	ds_read_b128 v[172:175], v218 offset:19456
	ds_read_b128 v[176:179], v218 offset:20480
	ds_read_b128 v[180:183], v218 offset:21504
	ds_read_b128 v[208:211], v218 offset:22528
	ds_read_b128 v[220:223], v218 offset:23552
	global_load_lds_dwordx4 v[224:225], off
	s_add_i32 m0, s83, 0x2000
	s_add_u32 s96, s46, 0x40000
	v_lshl_add_u64 v[226:227], s[46:47], 0, v[190:191]
	s_addc_u32 s97, s47, 0
	s_add_i32 s83, s79, s52
	global_load_lds_dwordx4 v[226:227], off
	v_lshl_add_u64 v[230:231], s[96:97], 0, v[186:187]
	s_mov_b32 m0, s83
	v_lshl_add_u64 v[232:233], s[48:49], 0, v[188:189]
	global_load_lds_dwordx4 v[230:231], off
	v_lshl_add_u64 v[230:231], s[96:97], 0, v[190:191]
	s_add_i32 m0, s83, 0x2000
	s_nop 0
	global_load_lds_dwordx4 v[230:231], off
	v_lshl_add_u64 v[230:231], s[48:49], 0, v[184:185]
	s_mov_b32 m0, s53
	s_nop 0
	global_load_lds_dwordx4 v[230:231], off
	s_mov_b32 m0, s54
	s_nop 0
	global_load_lds_dwordx4 v[232:233], off
	s_waitcnt vmcnt(8)
	s_waitcnt lgkmcnt(0)
	s_setprio 1
	s_barrier
	v_mfma_f32_16x16x32_bf16 v[60:63], v[80:83], v[160:163], 0
	v_mfma_f32_16x16x32_bf16 v[56:59], v[104:107], v[160:163], 0
	v_mfma_f32_16x16x32_bf16 v[40:43], v[104:107], v[168:171], 0
	v_mfma_f32_16x16x32_bf16 v[44:47], v[80:83], v[168:171], 0
	v_mfma_f32_16x16x32_bf16 v[28:31], v[80:83], v[176:179], 0
	v_mfma_f32_16x16x32_bf16 v[24:27], v[104:107], v[176:179], 0
	v_mfma_f32_16x16x32_bf16 v[8:11], v[104:107], v[208:211], 0
	v_mfma_f32_16x16x32_bf16 v[12:15], v[80:83], v[208:211], 0
	v_mfma_f32_16x16x32_bf16 v[4:7], v[128:131], v[208:211], 0
	v_mfma_f32_16x16x32_bf16 v[0:3], v[152:155], v[208:211], 0
	v_mfma_f32_16x16x32_bf16 v[16:19], v[152:155], v[176:179], 0
	v_mfma_f32_16x16x32_bf16 v[20:23], v[128:131], v[176:179], 0
	v_mfma_f32_16x16x32_bf16 v[36:39], v[128:131], v[168:171], 0
	v_mfma_f32_16x16x32_bf16 v[32:35], v[152:155], v[168:171], 0
	v_mfma_f32_16x16x32_bf16 v[48:51], v[152:155], v[160:163], 0
	v_mfma_f32_16x16x32_bf16 v[52:55], v[128:131], v[160:163], 0
	v_mfma_f32_16x16x32_bf16 v[60:63], v[84:87], v[164:167], v[60:63]
	v_mfma_f32_16x16x32_bf16 v[56:59], v[108:111], v[164:167], v[56:59]
	v_mfma_f32_16x16x32_bf16 v[40:43], v[108:111], v[172:175], v[40:43]
	v_mfma_f32_16x16x32_bf16 v[44:47], v[84:87], v[172:175], v[44:47]
	v_mfma_f32_16x16x32_bf16 v[28:31], v[84:87], v[180:183], v[28:31]
	v_mfma_f32_16x16x32_bf16 v[24:27], v[108:111], v[180:183], v[24:27]
	v_mfma_f32_16x16x32_bf16 v[8:11], v[108:111], v[220:223], v[8:11]
	v_mfma_f32_16x16x32_bf16 v[12:15], v[84:87], v[220:223], v[12:15]
	v_mfma_f32_16x16x32_bf16 v[4:7], v[132:135], v[220:223], v[4:7]
	v_mfma_f32_16x16x32_bf16 v[0:3], v[156:159], v[220:223], v[0:3]
	v_mfma_f32_16x16x32_bf16 v[16:19], v[156:159], v[180:183], v[16:19]
	v_mfma_f32_16x16x32_bf16 v[20:23], v[132:135], v[180:183], v[20:23]
	v_mfma_f32_16x16x32_bf16 v[36:39], v[132:135], v[172:175], v[36:39]
	v_mfma_f32_16x16x32_bf16 v[32:35], v[156:159], v[172:175], v[32:35]
	v_mfma_f32_16x16x32_bf16 v[48:51], v[156:159], v[164:167], v[48:51]
	v_mfma_f32_16x16x32_bf16 v[52:55], v[132:135], v[164:167], v[52:55]
	s_barrier
	s_setprio 0
	s_add_i32 s83, 0, 0x18000
	s_add_i32 s96, 0, 0x1c000
	v_add_u32_e32 v108, s83, v213
	v_add_u32_e32 v156, s96, v213
	ds_read_b128 v[80:83], v108
	ds_read_b128 v[84:87], v108 offset:1024
	ds_read_b128 v[104:107], v108 offset:2048
	ds_read_b128 v[108:111], v108 offset:3072
	ds_read_b128 v[128:131], v156
	ds_read_b128 v[132:135], v156 offset:1024
	ds_read_b128 v[152:155], v156 offset:2048
	ds_read_b128 v[156:159], v156 offset:3072
	s_add_u32 s48, s48, 0x40000
	s_addc_u32 s49, s49, 0
	s_mov_b32 m0, s55
	v_lshl_add_u64 v[234:235], s[48:49], 0, v[184:185]
	ds_read_b128 v[160:163], v218 offset:32768
	ds_read_b128 v[164:167], v218 offset:33792
	ds_read_b128 v[168:171], v218 offset:34816
	ds_read_b128 v[172:175], v218 offset:35840
	ds_read_b128 v[176:179], v218 offset:36864
	ds_read_b128 v[180:183], v218 offset:37888
	ds_read_b128 v[208:211], v218 offset:38912
	ds_read_b128 v[220:223], v218 offset:39936
	global_load_lds_dwordx4 v[234:235], off
	v_lshl_add_u64 v[234:235], s[48:49], 0, v[188:189]
	s_mov_b32 m0, s56
	s_nop 0
	global_load_lds_dwordx4 v[234:235], off
	s_waitcnt vmcnt(8)
	s_waitcnt lgkmcnt(0)
	s_setprio 1
	s_barrier
	v_mfma_f32_16x16x32_bf16 v[148:151], v[80:83], v[160:163], v[148:151]
	v_mfma_f32_16x16x32_bf16 v[144:147], v[104:107], v[160:163], v[144:147]
	v_mfma_f32_16x16x32_bf16 v[120:123], v[104:107], v[168:171], v[120:123]
	v_mfma_f32_16x16x32_bf16 v[124:127], v[80:83], v[168:171], v[124:127]
	v_mfma_f32_16x16x32_bf16 v[100:103], v[80:83], v[176:179], v[100:103]
	v_mfma_f32_16x16x32_bf16 v[96:99], v[104:107], v[176:179], v[96:99]
	v_mfma_f32_16x16x32_bf16 v[72:75], v[104:107], v[208:211], v[72:75]
	v_mfma_f32_16x16x32_bf16 v[76:79], v[80:83], v[208:211], v[76:79]
	v_mfma_f32_16x16x32_bf16 v[68:71], v[128:131], v[208:211], v[68:71]
	v_mfma_f32_16x16x32_bf16 v[64:67], v[152:155], v[208:211], v[64:67]
	v_mfma_f32_16x16x32_bf16 v[88:91], v[152:155], v[176:179], v[88:91]
	v_mfma_f32_16x16x32_bf16 v[92:95], v[128:131], v[176:179], v[92:95]
	v_mfma_f32_16x16x32_bf16 v[116:119], v[128:131], v[168:171], v[116:119]
	v_mfma_f32_16x16x32_bf16 v[112:115], v[152:155], v[168:171], v[112:115]
	v_mfma_f32_16x16x32_bf16 v[136:139], v[152:155], v[160:163], v[136:139]
	v_mfma_f32_16x16x32_bf16 v[140:143], v[128:131], v[160:163], v[140:143]
	v_mfma_f32_16x16x32_bf16 v[148:151], v[84:87], v[164:167], v[148:151]
	v_mfma_f32_16x16x32_bf16 v[144:147], v[108:111], v[164:167], v[144:147]
	v_mfma_f32_16x16x32_bf16 v[120:123], v[108:111], v[172:175], v[120:123]
	v_mfma_f32_16x16x32_bf16 v[124:127], v[84:87], v[172:175], v[124:127]
	v_mfma_f32_16x16x32_bf16 v[100:103], v[84:87], v[180:183], v[100:103]
	v_mfma_f32_16x16x32_bf16 v[96:99], v[108:111], v[180:183], v[96:99]
	v_mfma_f32_16x16x32_bf16 v[72:75], v[108:111], v[220:223], v[72:75]
	v_mfma_f32_16x16x32_bf16 v[76:79], v[84:87], v[220:223], v[76:79]
	v_mfma_f32_16x16x32_bf16 v[68:71], v[132:135], v[220:223], v[68:71]
	v_mfma_f32_16x16x32_bf16 v[64:67], v[156:159], v[220:223], v[64:67]
	v_mfma_f32_16x16x32_bf16 v[88:91], v[156:159], v[180:183], v[88:91]
	v_mfma_f32_16x16x32_bf16 v[92:95], v[132:135], v[180:183], v[92:95]
	v_mfma_f32_16x16x32_bf16 v[116:119], v[132:135], v[172:175], v[116:119]
	v_mfma_f32_16x16x32_bf16 v[112:115], v[156:159], v[172:175], v[112:115]
	v_mfma_f32_16x16x32_bf16 v[136:139], v[156:159], v[164:167], v[136:139]
	v_mfma_f32_16x16x32_bf16 v[140:143], v[132:135], v[164:167], v[140:143]
	s_barrier
	s_setprio 0
	s_add_i32 s48, s83, s52
	v_lshl_add_u64 v[224:225], v[224:225], 0, s[18:19]
	s_mov_b32 m0, s48
	ds_read_b128 v[160:163], v218 offset:49152
	ds_read_b128 v[164:167], v218 offset:50176
	ds_read_b128 v[168:171], v218 offset:51200
	ds_read_b128 v[172:175], v218 offset:52224
	ds_read_b128 v[176:179], v218 offset:53248
	ds_read_b128 v[180:183], v218 offset:54272
	ds_read_b128 v[208:211], v218 offset:55296
	ds_read_b128 v[220:223], v218 offset:56320
	global_load_lds_dwordx4 v[224:225], off
	s_add_i32 m0, s48, 0x2000
	s_add_u32 s46, s46, 0x40080
	v_lshl_add_u64 v[224:225], v[226:227], 0, s[18:19]
	s_addc_u32 s47, s47, 0
	s_add_i32 s48, s96, s52
	global_load_lds_dwordx4 v[224:225], off
	v_lshl_add_u64 v[224:225], s[46:47], 0, v[186:187]
	s_mov_b32 m0, s48
	s_nop 0
	global_load_lds_dwordx4 v[224:225], off
	v_lshl_add_u64 v[224:225], s[46:47], 0, v[190:191]
	s_add_i32 m0, s48, 0x2000
	s_nop 0
	global_load_lds_dwordx4 v[224:225], off
	v_lshl_add_u64 v[224:225], v[230:231], 0, s[18:19]
	s_mov_b32 m0, s68
	s_nop 0
	global_load_lds_dwordx4 v[224:225], off
	v_lshl_add_u64 v[224:225], v[232:233], 0, s[18:19]
	s_mov_b32 m0, s69
	s_nop 0
	global_load_lds_dwordx4 v[224:225], off
	s_waitcnt vmcnt(8)
	s_waitcnt lgkmcnt(0)
	s_setprio 1
	s_barrier
	v_mfma_f32_16x16x32_bf16 v[60:63], v[80:83], v[160:163], v[60:63]
	v_mfma_f32_16x16x32_bf16 v[56:59], v[104:107], v[160:163], v[56:59]
	v_mfma_f32_16x16x32_bf16 v[40:43], v[104:107], v[168:171], v[40:43]
	v_mfma_f32_16x16x32_bf16 v[44:47], v[80:83], v[168:171], v[44:47]
	v_mfma_f32_16x16x32_bf16 v[28:31], v[80:83], v[176:179], v[28:31]
	v_mfma_f32_16x16x32_bf16 v[24:27], v[104:107], v[176:179], v[24:27]
	v_mfma_f32_16x16x32_bf16 v[8:11], v[104:107], v[208:211], v[8:11]
	v_mfma_f32_16x16x32_bf16 v[12:15], v[80:83], v[208:211], v[12:15]
	v_mfma_f32_16x16x32_bf16 v[4:7], v[128:131], v[208:211], v[4:7]
	v_mfma_f32_16x16x32_bf16 v[0:3], v[152:155], v[208:211], v[0:3]
	v_mfma_f32_16x16x32_bf16 v[16:19], v[152:155], v[176:179], v[16:19]
	v_mfma_f32_16x16x32_bf16 v[20:23], v[128:131], v[176:179], v[20:23]
	v_mfma_f32_16x16x32_bf16 v[36:39], v[128:131], v[168:171], v[36:39]
	v_mfma_f32_16x16x32_bf16 v[32:35], v[152:155], v[168:171], v[32:35]
	v_mfma_f32_16x16x32_bf16 v[48:51], v[152:155], v[160:163], v[48:51]
	v_mfma_f32_16x16x32_bf16 v[52:55], v[128:131], v[160:163], v[52:55]
	v_mfma_f32_16x16x32_bf16 v[60:63], v[84:87], v[164:167], v[60:63]
	v_mfma_f32_16x16x32_bf16 v[56:59], v[108:111], v[164:167], v[56:59]
	v_mfma_f32_16x16x32_bf16 v[40:43], v[108:111], v[172:175], v[40:43]
	v_mfma_f32_16x16x32_bf16 v[44:47], v[84:87], v[172:175], v[44:47]
	v_mfma_f32_16x16x32_bf16 v[28:31], v[84:87], v[180:183], v[28:31]
	v_mfma_f32_16x16x32_bf16 v[24:27], v[108:111], v[180:183], v[24:27]
	v_mfma_f32_16x16x32_bf16 v[8:11], v[108:111], v[220:223], v[8:11]
	v_mfma_f32_16x16x32_bf16 v[12:15], v[84:87], v[220:223], v[12:15]
	v_mfma_f32_16x16x32_bf16 v[4:7], v[132:135], v[220:223], v[4:7]
	v_mfma_f32_16x16x32_bf16 v[0:3], v[156:159], v[220:223], v[0:3]
	v_mfma_f32_16x16x32_bf16 v[16:19], v[156:159], v[180:183], v[16:19]
	v_mfma_f32_16x16x32_bf16 v[20:23], v[132:135], v[180:183], v[20:23]
	v_mfma_f32_16x16x32_bf16 v[36:39], v[132:135], v[172:175], v[36:39]
	v_mfma_f32_16x16x32_bf16 v[32:35], v[156:159], v[172:175], v[32:35]
	v_mfma_f32_16x16x32_bf16 v[48:51], v[156:159], v[164:167], v[48:51]
	v_mfma_f32_16x16x32_bf16 v[52:55], v[132:135], v[164:167], v[52:55]
	s_barrier
	s_setprio 0
	s_add_i32 s95, s95, 2
	s_add_u32 s44, s44, 0x100
	s_addc_u32 s45, s45, 0
	s_add_u32 s93, s93, 0x100
	s_addc_u32 s94, s94, 0
	s_cmp_gt_u32 s95, 13
.LBB0_668:
	ds_read_b128 v[80:83], v216
	ds_read_b128 v[84:87], v216 offset:1024
	ds_read_b128 v[104:107], v216 offset:2048
	ds_read_b128 v[108:111], v216 offset:3072
	ds_read_b128 v[128:131], v217
	ds_read_b128 v[132:135], v217 offset:1024
	ds_read_b128 v[152:155], v217 offset:2048
	ds_read_b128 v[156:159], v217 offset:3072
	s_add_u32 s46, s44, 0xfffc0080
	s_addc_u32 s47, s45, -1
	s_cmp_eq_u32 s95, 12
	s_cselect_b32 s49, s23, s47
	s_cselect_b32 s48, s43, s46
	s_cselect_b32 s47, s37, s94
	s_cselect_b32 s46, s92, s93
	v_lshl_add_u64 v[224:225], s[44:45], 0, v[194:195]
	s_add_i32 m0, s53, 0xc000
	ds_read_b128 v[160:163], v218
	ds_read_b128 v[164:167], v218 offset:1024
	ds_read_b128 v[168:171], v218 offset:2048
	ds_read_b128 v[172:175], v218 offset:3072
	ds_read_b128 v[176:179], v218 offset:4096
	ds_read_b128 v[180:183], v218 offset:5120
	ds_read_b128 v[208:211], v218 offset:6144
	ds_read_b128 v[220:223], v218 offset:7168
	global_load_lds_dwordx4 v[224:225], off
	v_lshl_add_u64 v[224:225], s[44:45], 0, v[196:197]
	s_add_i32 m0, s53, 0xe000
	s_nop 0
	global_load_lds_dwordx4 v[224:225], off
	s_waitcnt vmcnt(8)
	s_waitcnt lgkmcnt(0)
	s_setprio 1
	s_barrier
	v_mfma_f32_16x16x32_bf16 v[148:151], v[80:83], v[160:163], v[148:151]
	v_mfma_f32_16x16x32_bf16 v[144:147], v[104:107], v[160:163], v[144:147]
	v_mfma_f32_16x16x32_bf16 v[120:123], v[104:107], v[168:171], v[120:123]
	v_mfma_f32_16x16x32_bf16 v[124:127], v[80:83], v[168:171], v[124:127]
	v_mfma_f32_16x16x32_bf16 v[100:103], v[80:83], v[176:179], v[100:103]
	v_mfma_f32_16x16x32_bf16 v[96:99], v[104:107], v[176:179], v[96:99]
	v_mfma_f32_16x16x32_bf16 v[72:75], v[104:107], v[208:211], v[72:75]
	v_mfma_f32_16x16x32_bf16 v[76:79], v[80:83], v[208:211], v[76:79]
	v_mfma_f32_16x16x32_bf16 v[68:71], v[128:131], v[208:211], v[68:71]
	v_mfma_f32_16x16x32_bf16 v[64:67], v[152:155], v[208:211], v[64:67]
	v_mfma_f32_16x16x32_bf16 v[88:91], v[152:155], v[176:179], v[88:91]
	v_mfma_f32_16x16x32_bf16 v[92:95], v[128:131], v[176:179], v[92:95]
	v_mfma_f32_16x16x32_bf16 v[116:119], v[128:131], v[168:171], v[116:119]
	v_mfma_f32_16x16x32_bf16 v[112:115], v[152:155], v[168:171], v[112:115]
	v_mfma_f32_16x16x32_bf16 v[136:139], v[152:155], v[160:163], v[136:139]
	v_mfma_f32_16x16x32_bf16 v[140:143], v[128:131], v[160:163], v[140:143]
	v_mfma_f32_16x16x32_bf16 v[148:151], v[84:87], v[164:167], v[148:151]
	v_mfma_f32_16x16x32_bf16 v[144:147], v[108:111], v[164:167], v[144:147]
	v_mfma_f32_16x16x32_bf16 v[120:123], v[108:111], v[172:175], v[120:123]
	v_mfma_f32_16x16x32_bf16 v[124:127], v[84:87], v[172:175], v[124:127]
	v_mfma_f32_16x16x32_bf16 v[100:103], v[84:87], v[180:183], v[100:103]
	v_mfma_f32_16x16x32_bf16 v[96:99], v[108:111], v[180:183], v[96:99]
	v_mfma_f32_16x16x32_bf16 v[72:75], v[108:111], v[220:223], v[72:75]
	v_mfma_f32_16x16x32_bf16 v[76:79], v[84:87], v[220:223], v[76:79]
	v_mfma_f32_16x16x32_bf16 v[68:71], v[132:135], v[220:223], v[68:71]
	v_mfma_f32_16x16x32_bf16 v[64:67], v[156:159], v[220:223], v[64:67]
	v_mfma_f32_16x16x32_bf16 v[88:91], v[156:159], v[180:183], v[88:91]
	v_mfma_f32_16x16x32_bf16 v[92:95], v[132:135], v[180:183], v[92:95]
	v_mfma_f32_16x16x32_bf16 v[116:119], v[132:135], v[172:175], v[116:119]
	v_mfma_f32_16x16x32_bf16 v[112:115], v[156:159], v[172:175], v[112:115]
	v_mfma_f32_16x16x32_bf16 v[136:139], v[156:159], v[164:167], v[136:139]
	v_mfma_f32_16x16x32_bf16 v[140:143], v[132:135], v[164:167], v[140:143]
	s_barrier
	s_setprio 0
	s_add_i32 s83, s78, s52
	v_lshl_add_u64 v[224:225], s[46:47], 0, v[186:187]
	s_mov_b32 m0, s83
	ds_read_b128 v[160:163], v218 offset:16384
	ds_read_b128 v[164:167], v218 offset:17408
	ds_read_b128 v[168:171], v218 offset:18432
	ds_read_b128 v[172:175], v218 offset:19456
	ds_read_b128 v[176:179], v218 offset:20480
	ds_read_b128 v[180:183], v218 offset:21504
	ds_read_b128 v[208:211], v218 offset:22528
	ds_read_b128 v[220:223], v218 offset:23552
	global_load_lds_dwordx4 v[224:225], off
	s_add_i32 m0, s83, 0x2000
	s_add_u32 s96, s46, 0x40000
	v_lshl_add_u64 v[226:227], s[46:47], 0, v[190:191]
	s_addc_u32 s97, s47, 0
	s_add_i32 s83, s79, s52
	global_load_lds_dwordx4 v[226:227], off
	v_lshl_add_u64 v[230:231], s[96:97], 0, v[186:187]
	s_mov_b32 m0, s83
	v_lshl_add_u64 v[232:233], s[48:49], 0, v[188:189]
	global_load_lds_dwordx4 v[230:231], off
	v_lshl_add_u64 v[230:231], s[96:97], 0, v[190:191]
	s_add_i32 m0, s83, 0x2000
	s_nop 0
	global_load_lds_dwordx4 v[230:231], off
	v_lshl_add_u64 v[230:231], s[48:49], 0, v[184:185]
	s_mov_b32 m0, s53
	s_nop 0
	global_load_lds_dwordx4 v[230:231], off
	s_mov_b32 m0, s54
	s_nop 0
	global_load_lds_dwordx4 v[232:233], off
	s_waitcnt vmcnt(8)
	s_waitcnt lgkmcnt(0)
	s_setprio 1
	s_barrier
	v_mfma_f32_16x16x32_bf16 v[60:63], v[80:83], v[160:163], v[60:63]
	v_mfma_f32_16x16x32_bf16 v[56:59], v[104:107], v[160:163], v[56:59]
	v_mfma_f32_16x16x32_bf16 v[40:43], v[104:107], v[168:171], v[40:43]
	v_mfma_f32_16x16x32_bf16 v[44:47], v[80:83], v[168:171], v[44:47]
	v_mfma_f32_16x16x32_bf16 v[28:31], v[80:83], v[176:179], v[28:31]
	v_mfma_f32_16x16x32_bf16 v[24:27], v[104:107], v[176:179], v[24:27]
	v_mfma_f32_16x16x32_bf16 v[8:11], v[104:107], v[208:211], v[8:11]
	v_mfma_f32_16x16x32_bf16 v[12:15], v[80:83], v[208:211], v[12:15]
	v_mfma_f32_16x16x32_bf16 v[4:7], v[128:131], v[208:211], v[4:7]
	v_mfma_f32_16x16x32_bf16 v[0:3], v[152:155], v[208:211], v[0:3]
	v_mfma_f32_16x16x32_bf16 v[16:19], v[152:155], v[176:179], v[16:19]
	v_mfma_f32_16x16x32_bf16 v[20:23], v[128:131], v[176:179], v[20:23]
	v_mfma_f32_16x16x32_bf16 v[36:39], v[128:131], v[168:171], v[36:39]
	v_mfma_f32_16x16x32_bf16 v[32:35], v[152:155], v[168:171], v[32:35]
	v_mfma_f32_16x16x32_bf16 v[48:51], v[152:155], v[160:163], v[48:51]
	v_mfma_f32_16x16x32_bf16 v[52:55], v[128:131], v[160:163], v[52:55]
	v_mfma_f32_16x16x32_bf16 v[60:63], v[84:87], v[164:167], v[60:63]
	v_mfma_f32_16x16x32_bf16 v[56:59], v[108:111], v[164:167], v[56:59]
	v_mfma_f32_16x16x32_bf16 v[40:43], v[108:111], v[172:175], v[40:43]
	v_mfma_f32_16x16x32_bf16 v[44:47], v[84:87], v[172:175], v[44:47]
	v_mfma_f32_16x16x32_bf16 v[28:31], v[84:87], v[180:183], v[28:31]
	v_mfma_f32_16x16x32_bf16 v[24:27], v[108:111], v[180:183], v[24:27]
	v_mfma_f32_16x16x32_bf16 v[8:11], v[108:111], v[220:223], v[8:11]
	v_mfma_f32_16x16x32_bf16 v[12:15], v[84:87], v[220:223], v[12:15]
	v_mfma_f32_16x16x32_bf16 v[4:7], v[132:135], v[220:223], v[4:7]
	v_mfma_f32_16x16x32_bf16 v[0:3], v[156:159], v[220:223], v[0:3]
	v_mfma_f32_16x16x32_bf16 v[16:19], v[156:159], v[180:183], v[16:19]
	v_mfma_f32_16x16x32_bf16 v[20:23], v[132:135], v[180:183], v[20:23]
	v_mfma_f32_16x16x32_bf16 v[36:39], v[132:135], v[172:175], v[36:39]
	v_mfma_f32_16x16x32_bf16 v[32:35], v[156:159], v[172:175], v[32:35]
	v_mfma_f32_16x16x32_bf16 v[48:51], v[156:159], v[164:167], v[48:51]
	v_mfma_f32_16x16x32_bf16 v[52:55], v[132:135], v[164:167], v[52:55]
	s_barrier
	s_setprio 0
	s_add_i32 s83, 0, 0x18000
	s_add_i32 s96, 0, 0x1c000
	v_add_u32_e32 v108, s83, v213
	v_add_u32_e32 v156, s96, v213
	ds_read_b128 v[80:83], v108
	ds_read_b128 v[84:87], v108 offset:1024
	ds_read_b128 v[104:107], v108 offset:2048
	ds_read_b128 v[108:111], v108 offset:3072
	ds_read_b128 v[128:131], v156
	ds_read_b128 v[132:135], v156 offset:1024
	ds_read_b128 v[152:155], v156 offset:2048
	ds_read_b128 v[156:159], v156 offset:3072
	s_add_u32 s48, s48, 0x40000
	s_addc_u32 s49, s49, 0
	s_mov_b32 m0, s55
	v_lshl_add_u64 v[234:235], s[48:49], 0, v[184:185]
	ds_read_b128 v[160:163], v218 offset:32768
	ds_read_b128 v[164:167], v218 offset:33792
	ds_read_b128 v[168:171], v218 offset:34816
	ds_read_b128 v[172:175], v218 offset:35840
	ds_read_b128 v[176:179], v218 offset:36864
	ds_read_b128 v[180:183], v218 offset:37888
	ds_read_b128 v[208:211], v218 offset:38912
	ds_read_b128 v[220:223], v218 offset:39936
	global_load_lds_dwordx4 v[234:235], off
	v_lshl_add_u64 v[234:235], s[48:49], 0, v[188:189]
	s_mov_b32 m0, s56
	s_nop 0
	global_load_lds_dwordx4 v[234:235], off
	s_waitcnt vmcnt(8)
	s_waitcnt lgkmcnt(0)
	s_setprio 1
	s_barrier
	v_mfma_f32_16x16x32_bf16 v[148:151], v[80:83], v[160:163], v[148:151]
	v_mfma_f32_16x16x32_bf16 v[144:147], v[104:107], v[160:163], v[144:147]
	v_mfma_f32_16x16x32_bf16 v[120:123], v[104:107], v[168:171], v[120:123]
	v_mfma_f32_16x16x32_bf16 v[124:127], v[80:83], v[168:171], v[124:127]
	v_mfma_f32_16x16x32_bf16 v[100:103], v[80:83], v[176:179], v[100:103]
	v_mfma_f32_16x16x32_bf16 v[96:99], v[104:107], v[176:179], v[96:99]
	v_mfma_f32_16x16x32_bf16 v[72:75], v[104:107], v[208:211], v[72:75]
	v_mfma_f32_16x16x32_bf16 v[76:79], v[80:83], v[208:211], v[76:79]
	v_mfma_f32_16x16x32_bf16 v[68:71], v[128:131], v[208:211], v[68:71]
	v_mfma_f32_16x16x32_bf16 v[64:67], v[152:155], v[208:211], v[64:67]
	v_mfma_f32_16x16x32_bf16 v[88:91], v[152:155], v[176:179], v[88:91]
	v_mfma_f32_16x16x32_bf16 v[92:95], v[128:131], v[176:179], v[92:95]
	v_mfma_f32_16x16x32_bf16 v[116:119], v[128:131], v[168:171], v[116:119]
	v_mfma_f32_16x16x32_bf16 v[112:115], v[152:155], v[168:171], v[112:115]
	v_mfma_f32_16x16x32_bf16 v[136:139], v[152:155], v[160:163], v[136:139]
	v_mfma_f32_16x16x32_bf16 v[140:143], v[128:131], v[160:163], v[140:143]
	v_mfma_f32_16x16x32_bf16 v[148:151], v[84:87], v[164:167], v[148:151]
	v_mfma_f32_16x16x32_bf16 v[144:147], v[108:111], v[164:167], v[144:147]
	v_mfma_f32_16x16x32_bf16 v[120:123], v[108:111], v[172:175], v[120:123]
	v_mfma_f32_16x16x32_bf16 v[124:127], v[84:87], v[172:175], v[124:127]
	v_mfma_f32_16x16x32_bf16 v[100:103], v[84:87], v[180:183], v[100:103]
	v_mfma_f32_16x16x32_bf16 v[96:99], v[108:111], v[180:183], v[96:99]
	v_mfma_f32_16x16x32_bf16 v[72:75], v[108:111], v[220:223], v[72:75]
	v_mfma_f32_16x16x32_bf16 v[76:79], v[84:87], v[220:223], v[76:79]
	v_mfma_f32_16x16x32_bf16 v[68:71], v[132:135], v[220:223], v[68:71]
	v_mfma_f32_16x16x32_bf16 v[64:67], v[156:159], v[220:223], v[64:67]
	v_mfma_f32_16x16x32_bf16 v[88:91], v[156:159], v[180:183], v[88:91]
	v_mfma_f32_16x16x32_bf16 v[92:95], v[132:135], v[180:183], v[92:95]
	v_mfma_f32_16x16x32_bf16 v[116:119], v[132:135], v[172:175], v[116:119]
	v_mfma_f32_16x16x32_bf16 v[112:115], v[156:159], v[172:175], v[112:115]
	v_mfma_f32_16x16x32_bf16 v[136:139], v[156:159], v[164:167], v[136:139]
	v_mfma_f32_16x16x32_bf16 v[140:143], v[132:135], v[164:167], v[140:143]
	s_barrier
	s_setprio 0
	s_add_i32 s48, s83, s52
	v_lshl_add_u64 v[224:225], v[224:225], 0, s[18:19]
	s_mov_b32 m0, s48
	ds_read_b128 v[160:163], v218 offset:49152
	ds_read_b128 v[164:167], v218 offset:50176
	ds_read_b128 v[168:171], v218 offset:51200
	ds_read_b128 v[172:175], v218 offset:52224
	ds_read_b128 v[176:179], v218 offset:53248
	ds_read_b128 v[180:183], v218 offset:54272
	ds_read_b128 v[208:211], v218 offset:55296
	ds_read_b128 v[220:223], v218 offset:56320
	global_load_lds_dwordx4 v[224:225], off
	s_add_i32 m0, s48, 0x2000
	s_add_u32 s46, s46, 0x40080
	v_lshl_add_u64 v[224:225], v[226:227], 0, s[18:19]
	s_addc_u32 s47, s47, 0
	s_add_i32 s48, s96, s52
	global_load_lds_dwordx4 v[224:225], off
	v_lshl_add_u64 v[224:225], s[46:47], 0, v[186:187]
	s_mov_b32 m0, s48
	s_nop 0
	global_load_lds_dwordx4 v[224:225], off
	v_lshl_add_u64 v[224:225], s[46:47], 0, v[190:191]
	s_add_i32 m0, s48, 0x2000
	s_nop 0
	global_load_lds_dwordx4 v[224:225], off
	v_lshl_add_u64 v[224:225], v[230:231], 0, s[18:19]
	s_mov_b32 m0, s68
	s_nop 0
	global_load_lds_dwordx4 v[224:225], off
	v_lshl_add_u64 v[224:225], v[232:233], 0, s[18:19]
	s_mov_b32 m0, s69
	s_nop 0
	global_load_lds_dwordx4 v[224:225], off
	s_waitcnt vmcnt(8)
	s_waitcnt lgkmcnt(0)
	s_setprio 1
	s_barrier
	v_mfma_f32_16x16x32_bf16 v[60:63], v[80:83], v[160:163], v[60:63]
	v_mfma_f32_16x16x32_bf16 v[56:59], v[104:107], v[160:163], v[56:59]
	v_mfma_f32_16x16x32_bf16 v[40:43], v[104:107], v[168:171], v[40:43]
	v_mfma_f32_16x16x32_bf16 v[44:47], v[80:83], v[168:171], v[44:47]
	v_mfma_f32_16x16x32_bf16 v[28:31], v[80:83], v[176:179], v[28:31]
	v_mfma_f32_16x16x32_bf16 v[24:27], v[104:107], v[176:179], v[24:27]
	v_mfma_f32_16x16x32_bf16 v[8:11], v[104:107], v[208:211], v[8:11]
	v_mfma_f32_16x16x32_bf16 v[12:15], v[80:83], v[208:211], v[12:15]
	v_mfma_f32_16x16x32_bf16 v[4:7], v[128:131], v[208:211], v[4:7]
	v_mfma_f32_16x16x32_bf16 v[0:3], v[152:155], v[208:211], v[0:3]
	v_mfma_f32_16x16x32_bf16 v[16:19], v[152:155], v[176:179], v[16:19]
	v_mfma_f32_16x16x32_bf16 v[20:23], v[128:131], v[176:179], v[20:23]
	v_mfma_f32_16x16x32_bf16 v[36:39], v[128:131], v[168:171], v[36:39]
	v_mfma_f32_16x16x32_bf16 v[32:35], v[152:155], v[168:171], v[32:35]
	v_mfma_f32_16x16x32_bf16 v[48:51], v[152:155], v[160:163], v[48:51]
	v_mfma_f32_16x16x32_bf16 v[52:55], v[128:131], v[160:163], v[52:55]
	v_mfma_f32_16x16x32_bf16 v[60:63], v[84:87], v[164:167], v[60:63]
	v_mfma_f32_16x16x32_bf16 v[56:59], v[108:111], v[164:167], v[56:59]
	v_mfma_f32_16x16x32_bf16 v[40:43], v[108:111], v[172:175], v[40:43]
	v_mfma_f32_16x16x32_bf16 v[44:47], v[84:87], v[172:175], v[44:47]
	v_mfma_f32_16x16x32_bf16 v[28:31], v[84:87], v[180:183], v[28:31]
	v_mfma_f32_16x16x32_bf16 v[24:27], v[108:111], v[180:183], v[24:27]
	v_mfma_f32_16x16x32_bf16 v[8:11], v[108:111], v[220:223], v[8:11]
	v_mfma_f32_16x16x32_bf16 v[12:15], v[84:87], v[220:223], v[12:15]
	v_mfma_f32_16x16x32_bf16 v[4:7], v[132:135], v[220:223], v[4:7]
	v_mfma_f32_16x16x32_bf16 v[0:3], v[156:159], v[220:223], v[0:3]
	v_mfma_f32_16x16x32_bf16 v[16:19], v[156:159], v[180:183], v[16:19]
	v_mfma_f32_16x16x32_bf16 v[20:23], v[132:135], v[180:183], v[20:23]
	v_mfma_f32_16x16x32_bf16 v[36:39], v[132:135], v[172:175], v[36:39]
	v_mfma_f32_16x16x32_bf16 v[32:35], v[156:159], v[172:175], v[32:35]
	v_mfma_f32_16x16x32_bf16 v[48:51], v[156:159], v[164:167], v[48:51]
	v_mfma_f32_16x16x32_bf16 v[52:55], v[132:135], v[164:167], v[52:55]
	s_barrier
	s_setprio 0
	s_add_i32 s95, s95, 2
	s_add_u32 s44, s44, 0x100
	s_addc_u32 s45, s45, 0
	s_add_u32 s93, s93, 0x100
	s_addc_u32 s94, s94, 0
	s_cmp_gt_u32 s95, 13
	s_cbranch_scc0 .LBB0_668
	s_and_b64 vcc, exec, s[20:21]
	s_cbranch_vccz .LBB0_671
	s_barrier

.LBB0_758:
	s_ashr_i32 s19, s18, 31
	s_lshl_b64 s[20:21], s[18:19], 19
	s_add_u32 s20, s62, s20
	s_addc_u32 s21, s63, s21
	s_and_b64 s[22:23], s[4:5], exec
	s_cselect_b32 s19, s21, s39
	s_cselect_b32 s57, s20, s38
	s_ashr_i32 s11, s10, 31
	s_lshl_b64 s[22:23], s[10:11], 19
	s_add_u32 s22, s40, s22
	s_addc_u32 s23, s41, s23
	s_and_b64 s[4:5], s[4:5], exec
	s_cselect_b32 s11, s23, s37
	s_cselect_b32 s58, s22, s36
	s_add_u32 s4, s38, 0x40080
	s_addc_u32 s5, s39, 0
	s_add_u32 s59, s36, 0x100
	s_addc_u32 s66, s37, 0
	s_mov_b32 s67, -2
	ds_read_b128 v[146:149], v172
	ds_read_b128 v[166:169], v172 offset:1024
	ds_read_b128 v[176:179], v172 offset:2048
	ds_read_b128 v[180:183], v172 offset:3072
	ds_read_b128 v[184:187], v173
	ds_read_b128 v[188:191], v173 offset:1024
	ds_read_b128 v[192:195], v173 offset:2048
	ds_read_b128 v[196:199], v173 offset:3072
	s_add_u32 s36, s4, 0xfffc0080
	s_addc_u32 s37, s5, -1
	s_cmp_eq_u32 s67, 12
	s_cselect_b32 s39, s19, s37
	s_cselect_b32 s38, s57, s36
	s_cselect_b32 s37, s11, s66
	s_cselect_b32 s36, s58, s59
	v_lshl_add_u64 v[150:151], s[4:5], 0, v[138:139]
	s_add_i32 m0, s27, 0xc000
	ds_read_b128 v[200:203], v174
	ds_read_b128 v[204:207], v174 offset:1024
	ds_read_b128 v[208:211], v174 offset:2048
	ds_read_b128 v[212:215], v174 offset:3072
	ds_read_b128 v[216:219], v174 offset:4096
	ds_read_b128 v[220:223], v174 offset:5120
	ds_read_b128 v[224:227], v174 offset:6144
	ds_read_b128 v[230:233], v174 offset:7168
	global_load_lds_dwordx4 v[150:151], off
	v_lshl_add_u64 v[150:151], s[4:5], 0, v[140:141]
	s_add_i32 m0, s27, 0xe000
	s_nop 0
	global_load_lds_dwordx4 v[150:151], off
	s_waitcnt vmcnt(8)
	s_waitcnt lgkmcnt(0)
	s_setprio 1
	s_barrier
	v_mfma_f32_16x16x32_bf16 v[124:127], v[146:149], v[200:203], 0
	v_mfma_f32_16x16x32_bf16 v[120:123], v[176:179], v[200:203], 0
	v_mfma_f32_16x16x32_bf16 v[104:107], v[176:179], v[208:211], 0
	v_mfma_f32_16x16x32_bf16 v[108:111], v[146:149], v[208:211], 0
	v_mfma_f32_16x16x32_bf16 v[92:95], v[146:149], v[216:219], 0
	v_mfma_f32_16x16x32_bf16 v[88:91], v[176:179], v[216:219], 0
	v_mfma_f32_16x16x32_bf16 v[72:75], v[176:179], v[224:227], 0
	v_mfma_f32_16x16x32_bf16 v[76:79], v[146:149], v[224:227], 0
	v_mfma_f32_16x16x32_bf16 v[68:71], v[184:187], v[224:227], 0
	v_mfma_f32_16x16x32_bf16 v[64:67], v[192:195], v[224:227], 0
	v_mfma_f32_16x16x32_bf16 v[80:83], v[192:195], v[216:219], 0
	v_mfma_f32_16x16x32_bf16 v[84:87], v[184:187], v[216:219], 0
	v_mfma_f32_16x16x32_bf16 v[100:103], v[184:187], v[208:211], 0
	v_mfma_f32_16x16x32_bf16 v[96:99], v[192:195], v[208:211], 0
	v_mfma_f32_16x16x32_bf16 v[112:115], v[192:195], v[200:203], 0
	v_mfma_f32_16x16x32_bf16 v[116:119], v[184:187], v[200:203], 0
	v_mfma_f32_16x16x32_bf16 v[124:127], v[166:169], v[204:207], v[124:127]
	v_mfma_f32_16x16x32_bf16 v[120:123], v[180:183], v[204:207], v[120:123]
	v_mfma_f32_16x16x32_bf16 v[104:107], v[180:183], v[212:215], v[104:107]
	v_mfma_f32_16x16x32_bf16 v[108:111], v[166:169], v[212:215], v[108:111]
	v_mfma_f32_16x16x32_bf16 v[92:95], v[166:169], v[220:223], v[92:95]
	v_mfma_f32_16x16x32_bf16 v[88:91], v[180:183], v[220:223], v[88:91]
	v_mfma_f32_16x16x32_bf16 v[72:75], v[180:183], v[230:233], v[72:75]
	v_mfma_f32_16x16x32_bf16 v[76:79], v[166:169], v[230:233], v[76:79]
	v_mfma_f32_16x16x32_bf16 v[68:71], v[188:191], v[230:233], v[68:71]
	v_mfma_f32_16x16x32_bf16 v[64:67], v[196:199], v[230:233], v[64:67]
	v_mfma_f32_16x16x32_bf16 v[80:83], v[196:199], v[220:223], v[80:83]
	v_mfma_f32_16x16x32_bf16 v[84:87], v[188:191], v[220:223], v[84:87]
	v_mfma_f32_16x16x32_bf16 v[100:103], v[188:191], v[212:215], v[100:103]
	v_mfma_f32_16x16x32_bf16 v[96:99], v[196:199], v[212:215], v[96:99]
	v_mfma_f32_16x16x32_bf16 v[112:115], v[196:199], v[204:207], v[112:115]
	v_mfma_f32_16x16x32_bf16 v[116:119], v[188:191], v[204:207], v[116:119]
	s_barrier
	s_setprio 0
	s_add_i32 s68, s53, s42
	v_lshl_add_u64 v[150:151], s[36:37], 0, v[132:133]
	s_mov_b32 m0, s68
	ds_read_b128 v[200:203], v174 offset:16384
	ds_read_b128 v[204:207], v174 offset:17408
	ds_read_b128 v[208:211], v174 offset:18432
	ds_read_b128 v[212:215], v174 offset:19456
	ds_read_b128 v[216:219], v174 offset:20480
	ds_read_b128 v[220:223], v174 offset:21504
	ds_read_b128 v[224:227], v174 offset:22528
	ds_read_b128 v[230:233], v174 offset:23552
	global_load_lds_dwordx4 v[150:151], off
	s_add_i32 m0, s68, 0x2000
	s_add_u32 s68, s36, 0x40000
	v_lshl_add_u64 v[154:155], s[36:37], 0, v[128:129]
	s_addc_u32 s69, s37, 0
	s_add_i32 s70, s54, s42
	global_load_lds_dwordx4 v[154:155], off
	v_lshl_add_u64 v[158:159], s[68:69], 0, v[132:133]
	s_mov_b32 m0, s70
	v_lshl_add_u64 v[162:163], s[38:39], 0, v[130:131]
	global_load_lds_dwordx4 v[158:159], off
	v_lshl_add_u64 v[158:159], s[68:69], 0, v[128:129]
	s_add_i32 m0, s70, 0x2000
	s_nop 0
	global_load_lds_dwordx4 v[158:159], off
	v_lshl_add_u64 v[158:159], s[38:39], 0, v[134:135]
	s_mov_b32 m0, s27
	s_nop 0
	global_load_lds_dwordx4 v[158:159], off
	s_mov_b32 m0, s45
	s_nop 0
	global_load_lds_dwordx4 v[162:163], off
	s_waitcnt vmcnt(8)
	s_waitcnt lgkmcnt(0)
	s_setprio 1
	s_barrier
	v_mfma_f32_16x16x32_bf16 v[60:63], v[146:149], v[200:203], 0
	v_mfma_f32_16x16x32_bf16 v[56:59], v[176:179], v[200:203], 0
	v_mfma_f32_16x16x32_bf16 v[40:43], v[176:179], v[208:211], 0
	v_mfma_f32_16x16x32_bf16 v[44:47], v[146:149], v[208:211], 0
	v_mfma_f32_16x16x32_bf16 v[28:31], v[146:149], v[216:219], 0
	v_mfma_f32_16x16x32_bf16 v[24:27], v[176:179], v[216:219], 0
	v_mfma_f32_16x16x32_bf16 v[8:11], v[176:179], v[224:227], 0
	v_mfma_f32_16x16x32_bf16 v[12:15], v[146:149], v[224:227], 0
	v_mfma_f32_16x16x32_bf16 v[4:7], v[184:187], v[224:227], 0
	v_mfma_f32_16x16x32_bf16 v[0:3], v[192:195], v[224:227], 0
	v_mfma_f32_16x16x32_bf16 v[16:19], v[192:195], v[216:219], 0
	v_mfma_f32_16x16x32_bf16 v[20:23], v[184:187], v[216:219], 0
	v_mfma_f32_16x16x32_bf16 v[36:39], v[184:187], v[208:211], 0
	v_mfma_f32_16x16x32_bf16 v[32:35], v[192:195], v[208:211], 0
	v_mfma_f32_16x16x32_bf16 v[48:51], v[192:195], v[200:203], 0
	v_mfma_f32_16x16x32_bf16 v[52:55], v[184:187], v[200:203], 0
	v_mfma_f32_16x16x32_bf16 v[60:63], v[166:169], v[204:207], v[60:63]
	v_mfma_f32_16x16x32_bf16 v[56:59], v[180:183], v[204:207], v[56:59]
	v_mfma_f32_16x16x32_bf16 v[40:43], v[180:183], v[212:215], v[40:43]
	v_mfma_f32_16x16x32_bf16 v[44:47], v[166:169], v[212:215], v[44:47]
	v_mfma_f32_16x16x32_bf16 v[28:31], v[166:169], v[220:223], v[28:31]
	v_mfma_f32_16x16x32_bf16 v[24:27], v[180:183], v[220:223], v[24:27]
	v_mfma_f32_16x16x32_bf16 v[8:11], v[180:183], v[230:233], v[8:11]
	v_mfma_f32_16x16x32_bf16 v[12:15], v[166:169], v[230:233], v[12:15]
	v_mfma_f32_16x16x32_bf16 v[4:7], v[188:191], v[230:233], v[4:7]
	v_mfma_f32_16x16x32_bf16 v[0:3], v[196:199], v[230:233], v[0:3]
	v_mfma_f32_16x16x32_bf16 v[16:19], v[196:199], v[220:223], v[16:19]
	v_mfma_f32_16x16x32_bf16 v[20:23], v[188:191], v[220:223], v[20:23]
	v_mfma_f32_16x16x32_bf16 v[36:39], v[188:191], v[212:215], v[36:39]
	v_mfma_f32_16x16x32_bf16 v[32:35], v[196:199], v[212:215], v[32:35]
	v_mfma_f32_16x16x32_bf16 v[48:51], v[196:199], v[204:207], v[48:51]
	v_mfma_f32_16x16x32_bf16 v[52:55], v[188:191], v[204:207], v[52:55]
	s_barrier
	s_setprio 0
	s_add_i32 s68, 0, 0x18000
	v_add_u32_e32 v152, s68, v157
	s_add_i32 s69, 0, 0x1c000
	ds_read_b128 v[146:149], v152
	ds_read_b128 v[166:169], v152 offset:1024
	ds_read_b128 v[176:179], v152 offset:2048
	ds_read_b128 v[180:183], v152 offset:3072
	v_add_u32_e32 v152, s69, v157
	ds_read_b128 v[184:187], v152
	ds_read_b128 v[188:191], v152 offset:1024
	ds_read_b128 v[192:195], v152 offset:2048
	ds_read_b128 v[196:199], v152 offset:3072
	s_add_u32 s38, s38, 0x40000
	s_addc_u32 s39, s39, 0
	s_mov_b32 m0, s46
	v_lshl_add_u64 v[234:235], s[38:39], 0, v[134:135]
	ds_read_b128 v[200:203], v174 offset:32768
	ds_read_b128 v[204:207], v174 offset:33792
	ds_read_b128 v[208:211], v174 offset:34816
	ds_read_b128 v[212:215], v174 offset:35840
	ds_read_b128 v[216:219], v174 offset:36864
	ds_read_b128 v[220:223], v174 offset:37888
	ds_read_b128 v[224:227], v174 offset:38912
	ds_read_b128 v[230:233], v174 offset:39936
	global_load_lds_dwordx4 v[234:235], off
	v_lshl_add_u64 v[234:235], s[38:39], 0, v[130:131]
	s_mov_b32 m0, s47
	s_nop 0
	global_load_lds_dwordx4 v[234:235], off
	s_waitcnt vmcnt(8)
	s_waitcnt lgkmcnt(0)
	s_setprio 1
	s_barrier
	v_mfma_f32_16x16x32_bf16 v[124:127], v[146:149], v[200:203], v[124:127]
	v_mfma_f32_16x16x32_bf16 v[120:123], v[176:179], v[200:203], v[120:123]
	v_mfma_f32_16x16x32_bf16 v[104:107], v[176:179], v[208:211], v[104:107]
	v_mfma_f32_16x16x32_bf16 v[108:111], v[146:149], v[208:211], v[108:111]
	v_mfma_f32_16x16x32_bf16 v[92:95], v[146:149], v[216:219], v[92:95]
	v_mfma_f32_16x16x32_bf16 v[88:91], v[176:179], v[216:219], v[88:91]
	v_mfma_f32_16x16x32_bf16 v[72:75], v[176:179], v[224:227], v[72:75]
	v_mfma_f32_16x16x32_bf16 v[76:79], v[146:149], v[224:227], v[76:79]
	v_mfma_f32_16x16x32_bf16 v[68:71], v[184:187], v[224:227], v[68:71]
	v_mfma_f32_16x16x32_bf16 v[64:67], v[192:195], v[224:227], v[64:67]
	v_mfma_f32_16x16x32_bf16 v[80:83], v[192:195], v[216:219], v[80:83]
	v_mfma_f32_16x16x32_bf16 v[84:87], v[184:187], v[216:219], v[84:87]
	v_mfma_f32_16x16x32_bf16 v[100:103], v[184:187], v[208:211], v[100:103]
	v_mfma_f32_16x16x32_bf16 v[96:99], v[192:195], v[208:211], v[96:99]
	v_mfma_f32_16x16x32_bf16 v[112:115], v[192:195], v[200:203], v[112:115]
	v_mfma_f32_16x16x32_bf16 v[116:119], v[184:187], v[200:203], v[116:119]
	v_mfma_f32_16x16x32_bf16 v[124:127], v[166:169], v[204:207], v[124:127]
	v_mfma_f32_16x16x32_bf16 v[120:123], v[180:183], v[204:207], v[120:123]
	v_mfma_f32_16x16x32_bf16 v[104:107], v[180:183], v[212:215], v[104:107]
	v_mfma_f32_16x16x32_bf16 v[108:111], v[166:169], v[212:215], v[108:111]
	v_mfma_f32_16x16x32_bf16 v[92:95], v[166:169], v[220:223], v[92:95]
	v_mfma_f32_16x16x32_bf16 v[88:91], v[180:183], v[220:223], v[88:91]
	v_mfma_f32_16x16x32_bf16 v[72:75], v[180:183], v[230:233], v[72:75]
	v_mfma_f32_16x16x32_bf16 v[76:79], v[166:169], v[230:233], v[76:79]
	v_mfma_f32_16x16x32_bf16 v[68:71], v[188:191], v[230:233], v[68:71]
	v_mfma_f32_16x16x32_bf16 v[64:67], v[196:199], v[230:233], v[64:67]
	v_mfma_f32_16x16x32_bf16 v[80:83], v[196:199], v[220:223], v[80:83]
	v_mfma_f32_16x16x32_bf16 v[84:87], v[188:191], v[220:223], v[84:87]
	v_mfma_f32_16x16x32_bf16 v[100:103], v[188:191], v[212:215], v[100:103]
	v_mfma_f32_16x16x32_bf16 v[96:99], v[196:199], v[212:215], v[96:99]
	v_mfma_f32_16x16x32_bf16 v[112:115], v[196:199], v[204:207], v[112:115]
	v_mfma_f32_16x16x32_bf16 v[116:119], v[188:191], v[204:207], v[116:119]
	s_barrier
	s_setprio 0
	s_add_i32 s38, s68, s42
	v_lshl_add_u64 v[150:151], v[150:151], 0, s[14:15]
	s_mov_b32 m0, s38
	ds_read_b128 v[200:203], v174 offset:49152
	ds_read_b128 v[204:207], v174 offset:50176
	ds_read_b128 v[208:211], v174 offset:51200
	ds_read_b128 v[212:215], v174 offset:52224
	ds_read_b128 v[216:219], v174 offset:53248
	ds_read_b128 v[220:223], v174 offset:54272
	ds_read_b128 v[224:227], v174 offset:55296
	ds_read_b128 v[230:233], v174 offset:56320
	global_load_lds_dwordx4 v[150:151], off
	s_add_i32 m0, s38, 0x2000
	s_add_u32 s36, s36, 0x40080
	v_lshl_add_u64 v[150:151], v[154:155], 0, s[14:15]
	s_addc_u32 s37, s37, 0
	s_add_i32 s38, s69, s42
	global_load_lds_dwordx4 v[150:151], off
	v_lshl_add_u64 v[150:151], s[36:37], 0, v[132:133]
	s_mov_b32 m0, s38
	s_nop 0
	global_load_lds_dwordx4 v[150:151], off
	v_lshl_add_u64 v[150:151], s[36:37], 0, v[128:129]
	s_add_i32 m0, s38, 0x2000
	s_nop 0
	global_load_lds_dwordx4 v[150:151], off
	v_lshl_add_u64 v[150:151], v[158:159], 0, s[14:15]
	s_mov_b32 m0, s49
	s_nop 0
	global_load_lds_dwordx4 v[150:151], off
	v_lshl_add_u64 v[150:151], v[162:163], 0, s[14:15]
	s_mov_b32 m0, s50
	s_nop 0
	global_load_lds_dwordx4 v[150:151], off
	s_waitcnt vmcnt(8)
	s_waitcnt lgkmcnt(0)
	s_setprio 1
	s_barrier
	v_mfma_f32_16x16x32_bf16 v[60:63], v[146:149], v[200:203], v[60:63]
	v_mfma_f32_16x16x32_bf16 v[56:59], v[176:179], v[200:203], v[56:59]
	v_mfma_f32_16x16x32_bf16 v[40:43], v[176:179], v[208:211], v[40:43]
	v_mfma_f32_16x16x32_bf16 v[44:47], v[146:149], v[208:211], v[44:47]
	v_mfma_f32_16x16x32_bf16 v[28:31], v[146:149], v[216:219], v[28:31]
	v_mfma_f32_16x16x32_bf16 v[24:27], v[176:179], v[216:219], v[24:27]
	v_mfma_f32_16x16x32_bf16 v[8:11], v[176:179], v[224:227], v[8:11]
	v_mfma_f32_16x16x32_bf16 v[12:15], v[146:149], v[224:227], v[12:15]
	v_mfma_f32_16x16x32_bf16 v[4:7], v[184:187], v[224:227], v[4:7]
	v_mfma_f32_16x16x32_bf16 v[0:3], v[192:195], v[224:227], v[0:3]
	v_mfma_f32_16x16x32_bf16 v[16:19], v[192:195], v[216:219], v[16:19]
	v_mfma_f32_16x16x32_bf16 v[20:23], v[184:187], v[216:219], v[20:23]
	v_mfma_f32_16x16x32_bf16 v[36:39], v[184:187], v[208:211], v[36:39]
	v_mfma_f32_16x16x32_bf16 v[32:35], v[192:195], v[208:211], v[32:35]
	v_mfma_f32_16x16x32_bf16 v[48:51], v[192:195], v[200:203], v[48:51]
	v_mfma_f32_16x16x32_bf16 v[52:55], v[184:187], v[200:203], v[52:55]
	v_mfma_f32_16x16x32_bf16 v[60:63], v[166:169], v[204:207], v[60:63]
	v_mfma_f32_16x16x32_bf16 v[56:59], v[180:183], v[204:207], v[56:59]
	v_mfma_f32_16x16x32_bf16 v[40:43], v[180:183], v[212:215], v[40:43]
	v_mfma_f32_16x16x32_bf16 v[44:47], v[166:169], v[212:215], v[44:47]
	v_mfma_f32_16x16x32_bf16 v[28:31], v[166:169], v[220:223], v[28:31]
	v_mfma_f32_16x16x32_bf16 v[24:27], v[180:183], v[220:223], v[24:27]
	v_mfma_f32_16x16x32_bf16 v[8:11], v[180:183], v[230:233], v[8:11]
	v_mfma_f32_16x16x32_bf16 v[12:15], v[166:169], v[230:233], v[12:15]
	v_mfma_f32_16x16x32_bf16 v[4:7], v[188:191], v[230:233], v[4:7]
	v_mfma_f32_16x16x32_bf16 v[0:3], v[196:199], v[230:233], v[0:3]
	v_mfma_f32_16x16x32_bf16 v[16:19], v[196:199], v[220:223], v[16:19]
	v_mfma_f32_16x16x32_bf16 v[20:23], v[188:191], v[220:223], v[20:23]
	v_mfma_f32_16x16x32_bf16 v[36:39], v[188:191], v[212:215], v[36:39]
	v_mfma_f32_16x16x32_bf16 v[32:35], v[196:199], v[212:215], v[32:35]
	v_mfma_f32_16x16x32_bf16 v[48:51], v[196:199], v[204:207], v[48:51]
	v_mfma_f32_16x16x32_bf16 v[52:55], v[188:191], v[204:207], v[52:55]
	s_barrier
	s_setprio 0
	s_add_i32 s67, s67, 2
	s_add_u32 s4, s4, 0x100
	s_addc_u32 s5, s5, 0
	s_add_u32 s59, s59, 0x100
	s_addc_u32 s66, s66, 0
	s_cmp_gt_u32 s67, 13
.LBB0_759:
	ds_read_b128 v[146:149], v172
	ds_read_b128 v[166:169], v172 offset:1024
	ds_read_b128 v[176:179], v172 offset:2048
	ds_read_b128 v[180:183], v172 offset:3072
	ds_read_b128 v[184:187], v173
	ds_read_b128 v[188:191], v173 offset:1024
	ds_read_b128 v[192:195], v173 offset:2048
	ds_read_b128 v[196:199], v173 offset:3072
	s_add_u32 s36, s4, 0xfffc0080
	s_addc_u32 s37, s5, -1
	s_cmp_eq_u32 s67, 12
	s_cselect_b32 s39, s19, s37
	s_cselect_b32 s38, s57, s36
	s_cselect_b32 s37, s11, s66
	s_cselect_b32 s36, s58, s59
	v_lshl_add_u64 v[150:151], s[4:5], 0, v[138:139]
	s_add_i32 m0, s27, 0xc000
	ds_read_b128 v[200:203], v174
	ds_read_b128 v[204:207], v174 offset:1024
	ds_read_b128 v[208:211], v174 offset:2048
	ds_read_b128 v[212:215], v174 offset:3072
	ds_read_b128 v[216:219], v174 offset:4096
	ds_read_b128 v[220:223], v174 offset:5120
	ds_read_b128 v[224:227], v174 offset:6144
	ds_read_b128 v[230:233], v174 offset:7168
	global_load_lds_dwordx4 v[150:151], off
	v_lshl_add_u64 v[150:151], s[4:5], 0, v[140:141]
	s_add_i32 m0, s27, 0xe000
	s_nop 0
	global_load_lds_dwordx4 v[150:151], off
	s_waitcnt vmcnt(8)
	s_waitcnt lgkmcnt(0)
	s_setprio 1
	s_barrier
	v_mfma_f32_16x16x32_bf16 v[124:127], v[146:149], v[200:203], v[124:127]
	v_mfma_f32_16x16x32_bf16 v[120:123], v[176:179], v[200:203], v[120:123]
	v_mfma_f32_16x16x32_bf16 v[104:107], v[176:179], v[208:211], v[104:107]
	v_mfma_f32_16x16x32_bf16 v[108:111], v[146:149], v[208:211], v[108:111]
	v_mfma_f32_16x16x32_bf16 v[92:95], v[146:149], v[216:219], v[92:95]
	v_mfma_f32_16x16x32_bf16 v[88:91], v[176:179], v[216:219], v[88:91]
	v_mfma_f32_16x16x32_bf16 v[72:75], v[176:179], v[224:227], v[72:75]
	v_mfma_f32_16x16x32_bf16 v[76:79], v[146:149], v[224:227], v[76:79]
	v_mfma_f32_16x16x32_bf16 v[68:71], v[184:187], v[224:227], v[68:71]
	v_mfma_f32_16x16x32_bf16 v[64:67], v[192:195], v[224:227], v[64:67]
	v_mfma_f32_16x16x32_bf16 v[80:83], v[192:195], v[216:219], v[80:83]
	v_mfma_f32_16x16x32_bf16 v[84:87], v[184:187], v[216:219], v[84:87]
	v_mfma_f32_16x16x32_bf16 v[100:103], v[184:187], v[208:211], v[100:103]
	v_mfma_f32_16x16x32_bf16 v[96:99], v[192:195], v[208:211], v[96:99]
	v_mfma_f32_16x16x32_bf16 v[112:115], v[192:195], v[200:203], v[112:115]
	v_mfma_f32_16x16x32_bf16 v[116:119], v[184:187], v[200:203], v[116:119]
	v_mfma_f32_16x16x32_bf16 v[124:127], v[166:169], v[204:207], v[124:127]
	v_mfma_f32_16x16x32_bf16 v[120:123], v[180:183], v[204:207], v[120:123]
	v_mfma_f32_16x16x32_bf16 v[104:107], v[180:183], v[212:215], v[104:107]
	v_mfma_f32_16x16x32_bf16 v[108:111], v[166:169], v[212:215], v[108:111]
	v_mfma_f32_16x16x32_bf16 v[92:95], v[166:169], v[220:223], v[92:95]
	v_mfma_f32_16x16x32_bf16 v[88:91], v[180:183], v[220:223], v[88:91]
	v_mfma_f32_16x16x32_bf16 v[72:75], v[180:183], v[230:233], v[72:75]
	v_mfma_f32_16x16x32_bf16 v[76:79], v[166:169], v[230:233], v[76:79]
	v_mfma_f32_16x16x32_bf16 v[68:71], v[188:191], v[230:233], v[68:71]
	v_mfma_f32_16x16x32_bf16 v[64:67], v[196:199], v[230:233], v[64:67]
	v_mfma_f32_16x16x32_bf16 v[80:83], v[196:199], v[220:223], v[80:83]
	v_mfma_f32_16x16x32_bf16 v[84:87], v[188:191], v[220:223], v[84:87]
	v_mfma_f32_16x16x32_bf16 v[100:103], v[188:191], v[212:215], v[100:103]
	v_mfma_f32_16x16x32_bf16 v[96:99], v[196:199], v[212:215], v[96:99]
	v_mfma_f32_16x16x32_bf16 v[112:115], v[196:199], v[204:207], v[112:115]
	v_mfma_f32_16x16x32_bf16 v[116:119], v[188:191], v[204:207], v[116:119]
	s_barrier
	s_setprio 0
	s_add_i32 s68, s53, s42
	v_lshl_add_u64 v[150:151], s[36:37], 0, v[132:133]
	s_mov_b32 m0, s68
	ds_read_b128 v[200:203], v174 offset:16384
	ds_read_b128 v[204:207], v174 offset:17408
	ds_read_b128 v[208:211], v174 offset:18432
	ds_read_b128 v[212:215], v174 offset:19456
	ds_read_b128 v[216:219], v174 offset:20480
	ds_read_b128 v[220:223], v174 offset:21504
	ds_read_b128 v[224:227], v174 offset:22528
	ds_read_b128 v[230:233], v174 offset:23552
	global_load_lds_dwordx4 v[150:151], off
	s_add_i32 m0, s68, 0x2000
	s_add_u32 s68, s36, 0x40000
	v_lshl_add_u64 v[154:155], s[36:37], 0, v[128:129]
	s_addc_u32 s69, s37, 0
	s_add_i32 s70, s54, s42
	global_load_lds_dwordx4 v[154:155], off
	v_lshl_add_u64 v[158:159], s[68:69], 0, v[132:133]
	s_mov_b32 m0, s70
	v_lshl_add_u64 v[162:163], s[38:39], 0, v[130:131]
	global_load_lds_dwordx4 v[158:159], off
	v_lshl_add_u64 v[158:159], s[68:69], 0, v[128:129]
	s_add_i32 m0, s70, 0x2000
	s_nop 0
	global_load_lds_dwordx4 v[158:159], off
	v_lshl_add_u64 v[158:159], s[38:39], 0, v[134:135]
	s_mov_b32 m0, s27
	s_nop 0
	global_load_lds_dwordx4 v[158:159], off
	s_mov_b32 m0, s45
	s_nop 0
	global_load_lds_dwordx4 v[162:163], off
	s_waitcnt vmcnt(8)
	s_waitcnt lgkmcnt(0)
	s_setprio 1
	s_barrier
	v_mfma_f32_16x16x32_bf16 v[60:63], v[146:149], v[200:203], v[60:63]
	v_mfma_f32_16x16x32_bf16 v[56:59], v[176:179], v[200:203], v[56:59]
	v_mfma_f32_16x16x32_bf16 v[40:43], v[176:179], v[208:211], v[40:43]
	v_mfma_f32_16x16x32_bf16 v[44:47], v[146:149], v[208:211], v[44:47]
	v_mfma_f32_16x16x32_bf16 v[28:31], v[146:149], v[216:219], v[28:31]
	v_mfma_f32_16x16x32_bf16 v[24:27], v[176:179], v[216:219], v[24:27]
	v_mfma_f32_16x16x32_bf16 v[8:11], v[176:179], v[224:227], v[8:11]
	v_mfma_f32_16x16x32_bf16 v[12:15], v[146:149], v[224:227], v[12:15]
	v_mfma_f32_16x16x32_bf16 v[4:7], v[184:187], v[224:227], v[4:7]
	v_mfma_f32_16x16x32_bf16 v[0:3], v[192:195], v[224:227], v[0:3]
	v_mfma_f32_16x16x32_bf16 v[16:19], v[192:195], v[216:219], v[16:19]
	v_mfma_f32_16x16x32_bf16 v[20:23], v[184:187], v[216:219], v[20:23]
	v_mfma_f32_16x16x32_bf16 v[36:39], v[184:187], v[208:211], v[36:39]
	v_mfma_f32_16x16x32_bf16 v[32:35], v[192:195], v[208:211], v[32:35]
	v_mfma_f32_16x16x32_bf16 v[48:51], v[192:195], v[200:203], v[48:51]
	v_mfma_f32_16x16x32_bf16 v[52:55], v[184:187], v[200:203], v[52:55]
	v_mfma_f32_16x16x32_bf16 v[60:63], v[166:169], v[204:207], v[60:63]
	v_mfma_f32_16x16x32_bf16 v[56:59], v[180:183], v[204:207], v[56:59]
	v_mfma_f32_16x16x32_bf16 v[40:43], v[180:183], v[212:215], v[40:43]
	v_mfma_f32_16x16x32_bf16 v[44:47], v[166:169], v[212:215], v[44:47]
	v_mfma_f32_16x16x32_bf16 v[28:31], v[166:169], v[220:223], v[28:31]
	v_mfma_f32_16x16x32_bf16 v[24:27], v[180:183], v[220:223], v[24:27]
	v_mfma_f32_16x16x32_bf16 v[8:11], v[180:183], v[230:233], v[8:11]
	v_mfma_f32_16x16x32_bf16 v[12:15], v[166:169], v[230:233], v[12:15]
	v_mfma_f32_16x16x32_bf16 v[4:7], v[188:191], v[230:233], v[4:7]
	v_mfma_f32_16x16x32_bf16 v[0:3], v[196:199], v[230:233], v[0:3]
	v_mfma_f32_16x16x32_bf16 v[16:19], v[196:199], v[220:223], v[16:19]
	v_mfma_f32_16x16x32_bf16 v[20:23], v[188:191], v[220:223], v[20:23]
	v_mfma_f32_16x16x32_bf16 v[36:39], v[188:191], v[212:215], v[36:39]
	v_mfma_f32_16x16x32_bf16 v[32:35], v[196:199], v[212:215], v[32:35]
	v_mfma_f32_16x16x32_bf16 v[48:51], v[196:199], v[204:207], v[48:51]
	v_mfma_f32_16x16x32_bf16 v[52:55], v[188:191], v[204:207], v[52:55]
	s_barrier
	s_setprio 0
	s_add_i32 s68, 0, 0x18000
	v_add_u32_e32 v152, s68, v157
	s_add_i32 s69, 0, 0x1c000
	ds_read_b128 v[146:149], v152
	ds_read_b128 v[166:169], v152 offset:1024
	ds_read_b128 v[176:179], v152 offset:2048
	ds_read_b128 v[180:183], v152 offset:3072
	v_add_u32_e32 v152, s69, v157
	ds_read_b128 v[184:187], v152
	ds_read_b128 v[188:191], v152 offset:1024
	ds_read_b128 v[192:195], v152 offset:2048
	ds_read_b128 v[196:199], v152 offset:3072
	s_add_u32 s38, s38, 0x40000
	s_addc_u32 s39, s39, 0
	s_mov_b32 m0, s46
	v_lshl_add_u64 v[234:235], s[38:39], 0, v[134:135]
	ds_read_b128 v[200:203], v174 offset:32768
	ds_read_b128 v[204:207], v174 offset:33792
	ds_read_b128 v[208:211], v174 offset:34816
	ds_read_b128 v[212:215], v174 offset:35840
	ds_read_b128 v[216:219], v174 offset:36864
	ds_read_b128 v[220:223], v174 offset:37888
	ds_read_b128 v[224:227], v174 offset:38912
	ds_read_b128 v[230:233], v174 offset:39936
	global_load_lds_dwordx4 v[234:235], off
	v_lshl_add_u64 v[234:235], s[38:39], 0, v[130:131]
	s_mov_b32 m0, s47
	s_nop 0
	global_load_lds_dwordx4 v[234:235], off
	s_waitcnt vmcnt(8)
	s_waitcnt lgkmcnt(0)
	s_setprio 1
	s_barrier
	v_mfma_f32_16x16x32_bf16 v[124:127], v[146:149], v[200:203], v[124:127]
	v_mfma_f32_16x16x32_bf16 v[120:123], v[176:179], v[200:203], v[120:123]
	v_mfma_f32_16x16x32_bf16 v[104:107], v[176:179], v[208:211], v[104:107]
	v_mfma_f32_16x16x32_bf16 v[108:111], v[146:149], v[208:211], v[108:111]
	v_mfma_f32_16x16x32_bf16 v[92:95], v[146:149], v[216:219], v[92:95]
	v_mfma_f32_16x16x32_bf16 v[88:91], v[176:179], v[216:219], v[88:91]
	v_mfma_f32_16x16x32_bf16 v[72:75], v[176:179], v[224:227], v[72:75]
	v_mfma_f32_16x16x32_bf16 v[76:79], v[146:149], v[224:227], v[76:79]
	v_mfma_f32_16x16x32_bf16 v[68:71], v[184:187], v[224:227], v[68:71]
	v_mfma_f32_16x16x32_bf16 v[64:67], v[192:195], v[224:227], v[64:67]
	v_mfma_f32_16x16x32_bf16 v[80:83], v[192:195], v[216:219], v[80:83]
	v_mfma_f32_16x16x32_bf16 v[84:87], v[184:187], v[216:219], v[84:87]
	v_mfma_f32_16x16x32_bf16 v[100:103], v[184:187], v[208:211], v[100:103]
	v_mfma_f32_16x16x32_bf16 v[96:99], v[192:195], v[208:211], v[96:99]
	v_mfma_f32_16x16x32_bf16 v[112:115], v[192:195], v[200:203], v[112:115]
	v_mfma_f32_16x16x32_bf16 v[116:119], v[184:187], v[200:203], v[116:119]
	v_mfma_f32_16x16x32_bf16 v[124:127], v[166:169], v[204:207], v[124:127]
	v_mfma_f32_16x16x32_bf16 v[120:123], v[180:183], v[204:207], v[120:123]
	v_mfma_f32_16x16x32_bf16 v[104:107], v[180:183], v[212:215], v[104:107]
	v_mfma_f32_16x16x32_bf16 v[108:111], v[166:169], v[212:215], v[108:111]
	v_mfma_f32_16x16x32_bf16 v[92:95], v[166:169], v[220:223], v[92:95]
	v_mfma_f32_16x16x32_bf16 v[88:91], v[180:183], v[220:223], v[88:91]
	v_mfma_f32_16x16x32_bf16 v[72:75], v[180:183], v[230:233], v[72:75]
	v_mfma_f32_16x16x32_bf16 v[76:79], v[166:169], v[230:233], v[76:79]
	v_mfma_f32_16x16x32_bf16 v[68:71], v[188:191], v[230:233], v[68:71]
	v_mfma_f32_16x16x32_bf16 v[64:67], v[196:199], v[230:233], v[64:67]
	v_mfma_f32_16x16x32_bf16 v[80:83], v[196:199], v[220:223], v[80:83]
	v_mfma_f32_16x16x32_bf16 v[84:87], v[188:191], v[220:223], v[84:87]
	v_mfma_f32_16x16x32_bf16 v[100:103], v[188:191], v[212:215], v[100:103]
	v_mfma_f32_16x16x32_bf16 v[96:99], v[196:199], v[212:215], v[96:99]
	v_mfma_f32_16x16x32_bf16 v[112:115], v[196:199], v[204:207], v[112:115]
	v_mfma_f32_16x16x32_bf16 v[116:119], v[188:191], v[204:207], v[116:119]
	s_barrier
	s_setprio 0
	s_add_i32 s38, s68, s42
	v_lshl_add_u64 v[150:151], v[150:151], 0, s[14:15]
	s_mov_b32 m0, s38
	ds_read_b128 v[200:203], v174 offset:49152
	ds_read_b128 v[204:207], v174 offset:50176
	ds_read_b128 v[208:211], v174 offset:51200
	ds_read_b128 v[212:215], v174 offset:52224
	ds_read_b128 v[216:219], v174 offset:53248
	ds_read_b128 v[220:223], v174 offset:54272
	ds_read_b128 v[224:227], v174 offset:55296
	ds_read_b128 v[230:233], v174 offset:56320
	global_load_lds_dwordx4 v[150:151], off
	s_add_i32 m0, s38, 0x2000
	s_add_u32 s36, s36, 0x40080
	v_lshl_add_u64 v[150:151], v[154:155], 0, s[14:15]
	s_addc_u32 s37, s37, 0
	s_add_i32 s38, s69, s42
	global_load_lds_dwordx4 v[150:151], off
	v_lshl_add_u64 v[150:151], s[36:37], 0, v[132:133]
	s_mov_b32 m0, s38
	s_nop 0
	global_load_lds_dwordx4 v[150:151], off
	v_lshl_add_u64 v[150:151], s[36:37], 0, v[128:129]
	s_add_i32 m0, s38, 0x2000
	s_nop 0
	global_load_lds_dwordx4 v[150:151], off
	v_lshl_add_u64 v[150:151], v[158:159], 0, s[14:15]
	s_mov_b32 m0, s49
	s_nop 0
	global_load_lds_dwordx4 v[150:151], off
	v_lshl_add_u64 v[150:151], v[162:163], 0, s[14:15]
	s_mov_b32 m0, s50
	s_nop 0
	global_load_lds_dwordx4 v[150:151], off
	s_waitcnt vmcnt(8)
	s_waitcnt lgkmcnt(0)
	s_setprio 1
	s_barrier
	v_mfma_f32_16x16x32_bf16 v[60:63], v[146:149], v[200:203], v[60:63]
	v_mfma_f32_16x16x32_bf16 v[56:59], v[176:179], v[200:203], v[56:59]
	v_mfma_f32_16x16x32_bf16 v[40:43], v[176:179], v[208:211], v[40:43]
	v_mfma_f32_16x16x32_bf16 v[44:47], v[146:149], v[208:211], v[44:47]
	v_mfma_f32_16x16x32_bf16 v[28:31], v[146:149], v[216:219], v[28:31]
	v_mfma_f32_16x16x32_bf16 v[24:27], v[176:179], v[216:219], v[24:27]
	v_mfma_f32_16x16x32_bf16 v[8:11], v[176:179], v[224:227], v[8:11]
	v_mfma_f32_16x16x32_bf16 v[12:15], v[146:149], v[224:227], v[12:15]
	v_mfma_f32_16x16x32_bf16 v[4:7], v[184:187], v[224:227], v[4:7]
	v_mfma_f32_16x16x32_bf16 v[0:3], v[192:195], v[224:227], v[0:3]
	v_mfma_f32_16x16x32_bf16 v[16:19], v[192:195], v[216:219], v[16:19]
	v_mfma_f32_16x16x32_bf16 v[20:23], v[184:187], v[216:219], v[20:23]
	v_mfma_f32_16x16x32_bf16 v[36:39], v[184:187], v[208:211], v[36:39]
	v_mfma_f32_16x16x32_bf16 v[32:35], v[192:195], v[208:211], v[32:35]
	v_mfma_f32_16x16x32_bf16 v[48:51], v[192:195], v[200:203], v[48:51]
	v_mfma_f32_16x16x32_bf16 v[52:55], v[184:187], v[200:203], v[52:55]
	v_mfma_f32_16x16x32_bf16 v[60:63], v[166:169], v[204:207], v[60:63]
	v_mfma_f32_16x16x32_bf16 v[56:59], v[180:183], v[204:207], v[56:59]
	v_mfma_f32_16x16x32_bf16 v[40:43], v[180:183], v[212:215], v[40:43]
	v_mfma_f32_16x16x32_bf16 v[44:47], v[166:169], v[212:215], v[44:47]
	v_mfma_f32_16x16x32_bf16 v[28:31], v[166:169], v[220:223], v[28:31]
	v_mfma_f32_16x16x32_bf16 v[24:27], v[180:183], v[220:223], v[24:27]
	v_mfma_f32_16x16x32_bf16 v[8:11], v[180:183], v[230:233], v[8:11]
	v_mfma_f32_16x16x32_bf16 v[12:15], v[166:169], v[230:233], v[12:15]
	v_mfma_f32_16x16x32_bf16 v[4:7], v[188:191], v[230:233], v[4:7]
	v_mfma_f32_16x16x32_bf16 v[0:3], v[196:199], v[230:233], v[0:3]
	v_mfma_f32_16x16x32_bf16 v[16:19], v[196:199], v[220:223], v[16:19]
	v_mfma_f32_16x16x32_bf16 v[20:23], v[188:191], v[220:223], v[20:23]
	v_mfma_f32_16x16x32_bf16 v[36:39], v[188:191], v[212:215], v[36:39]
	v_mfma_f32_16x16x32_bf16 v[32:35], v[196:199], v[212:215], v[32:35]
	v_mfma_f32_16x16x32_bf16 v[48:51], v[196:199], v[204:207], v[48:51]
	v_mfma_f32_16x16x32_bf16 v[52:55], v[188:191], v[204:207], v[52:55]
	s_barrier
	s_setprio 0
	s_add_i32 s67, s67, 2
	s_add_u32 s4, s4, 0x100
	s_addc_u32 s5, s5, 0
	s_add_u32 s59, s59, 0x100
	s_addc_u32 s66, s66, 0
	s_cmp_gt_u32 s67, 13
	s_cbranch_scc0 .LBB0_759
	s_and_b64 vcc, exec, s[16:17]
	s_cbranch_vccz .LBB0_762
	s_barrier

.LBB0_835:
	s_add_u32 s80, s22, 0x100
	s_addc_u32 s81, s23, 0
	s_mov_b32 s82, -2
	ds_read_b128 v[112:115], v203
	ds_read_b128 v[116:119], v203 offset:1024
	ds_read_b128 v[136:139], v203 offset:2048
	ds_read_b128 v[140:143], v203 offset:3072
	ds_read_b128 v[144:147], v204
	ds_read_b128 v[148:151], v204 offset:1024
	ds_read_b128 v[152:155], v204 offset:2048
	ds_read_b128 v[156:159], v204 offset:3072
	s_add_u32 s22, s20, 0x100
	s_addc_u32 s23, s21, 0
	s_cmp_eq_u32 s82, 40
	s_cselect_b32 s37, s7, s23
	s_cselect_b32 s36, s6, s22
	s_cselect_b32 s27, s19, s81
	s_cselect_b32 s26, s18, s80
	v_lshl_add_u64 v[200:201], s[20:21], 0, v[186:187]
	s_add_i32 m0, s43, 0xc000
	ds_read_b128 v[160:163], v205
	ds_read_b128 v[164:167], v205 offset:1024
	ds_read_b128 v[168:171], v205 offset:2048
	ds_read_b128 v[172:175], v205 offset:3072
	ds_read_b128 v[206:209], v205 offset:4096
	ds_read_b128 v[210:213], v205 offset:5120
	ds_read_b128 v[214:217], v205 offset:6144
	ds_read_b128 v[218:221], v205 offset:7168
	global_load_lds_dwordx4 v[200:201], off
	v_lshl_add_u64 v[200:201], s[20:21], 0, v[188:189]
	s_add_i32 m0, s43, 0xe000
	s_nop 0
	global_load_lds_dwordx4 v[200:201], off
	s_waitcnt vmcnt(8)
	s_waitcnt lgkmcnt(0)
	s_setprio 1
	s_barrier
	v_mfma_f32_16x16x32_bf16 v[132:135], v[112:115], v[160:163], 0
	v_mfma_f32_16x16x32_bf16 v[128:131], v[136:139], v[160:163], 0
	v_mfma_f32_16x16x32_bf16 v[104:107], v[136:139], v[168:171], 0
	v_mfma_f32_16x16x32_bf16 v[108:111], v[112:115], v[168:171], 0
	v_mfma_f32_16x16x32_bf16 v[92:95], v[112:115], v[206:209], 0
	v_mfma_f32_16x16x32_bf16 v[88:91], v[136:139], v[206:209], 0
	v_mfma_f32_16x16x32_bf16 v[72:75], v[136:139], v[214:217], 0
	v_mfma_f32_16x16x32_bf16 v[76:79], v[112:115], v[214:217], 0
	v_mfma_f32_16x16x32_bf16 v[68:71], v[144:147], v[214:217], 0
	v_mfma_f32_16x16x32_bf16 v[64:67], v[152:155], v[214:217], 0
	v_mfma_f32_16x16x32_bf16 v[80:83], v[152:155], v[206:209], 0
	v_mfma_f32_16x16x32_bf16 v[84:87], v[144:147], v[206:209], 0
	v_mfma_f32_16x16x32_bf16 v[100:103], v[144:147], v[168:171], 0
	v_mfma_f32_16x16x32_bf16 v[96:99], v[152:155], v[168:171], 0
	v_mfma_f32_16x16x32_bf16 v[120:123], v[152:155], v[160:163], 0
	v_mfma_f32_16x16x32_bf16 v[124:127], v[144:147], v[160:163], 0
	v_mfma_f32_16x16x32_bf16 v[132:135], v[116:119], v[164:167], v[132:135]
	v_mfma_f32_16x16x32_bf16 v[128:131], v[140:143], v[164:167], v[128:131]
	v_mfma_f32_16x16x32_bf16 v[104:107], v[140:143], v[172:175], v[104:107]
	v_mfma_f32_16x16x32_bf16 v[108:111], v[116:119], v[172:175], v[108:111]
	v_mfma_f32_16x16x32_bf16 v[92:95], v[116:119], v[210:213], v[92:95]
	v_mfma_f32_16x16x32_bf16 v[88:91], v[140:143], v[210:213], v[88:91]
	v_mfma_f32_16x16x32_bf16 v[72:75], v[140:143], v[218:221], v[72:75]
	v_mfma_f32_16x16x32_bf16 v[76:79], v[116:119], v[218:221], v[76:79]
	v_mfma_f32_16x16x32_bf16 v[68:71], v[148:151], v[218:221], v[68:71]
	v_mfma_f32_16x16x32_bf16 v[64:67], v[156:159], v[218:221], v[64:67]
	v_mfma_f32_16x16x32_bf16 v[80:83], v[156:159], v[210:213], v[80:83]
	v_mfma_f32_16x16x32_bf16 v[84:87], v[148:151], v[210:213], v[84:87]
	v_mfma_f32_16x16x32_bf16 v[100:103], v[148:151], v[172:175], v[100:103]
	v_mfma_f32_16x16x32_bf16 v[96:99], v[156:159], v[172:175], v[96:99]
	v_mfma_f32_16x16x32_bf16 v[120:123], v[156:159], v[164:167], v[120:123]
	v_mfma_f32_16x16x32_bf16 v[124:127], v[148:151], v[164:167], v[124:127]
	s_barrier
	s_setprio 0
	s_add_i32 s20, s59, s40
	v_lshl_add_u64 v[200:201], s[26:27], 0, v[180:181]
	s_mov_b32 m0, s20
	ds_read_b128 v[160:163], v205 offset:16384
	ds_read_b128 v[164:167], v205 offset:17408
	ds_read_b128 v[168:171], v205 offset:18432
	ds_read_b128 v[172:175], v205 offset:19456
	ds_read_b128 v[206:209], v205 offset:20480
	ds_read_b128 v[210:213], v205 offset:21504
	ds_read_b128 v[214:217], v205 offset:22528
	ds_read_b128 v[218:221], v205 offset:23552
	global_load_lds_dwordx4 v[200:201], off
	s_add_i32 m0, s20, 0x2000
	s_add_u32 s20, s26, 0xb0000
	v_lshl_add_u64 v[222:223], s[26:27], 0, v[176:177]
	s_addc_u32 s21, s27, 0
	s_add_i32 s83, s66, s40
	global_load_lds_dwordx4 v[222:223], off
	v_lshl_add_u64 v[224:225], s[20:21], 0, v[180:181]
	s_mov_b32 m0, s83
	v_lshl_add_u64 v[226:227], s[36:37], 0, v[178:179]
	global_load_lds_dwordx4 v[224:225], off
	v_lshl_add_u64 v[224:225], s[20:21], 0, v[176:177]
	s_add_i32 m0, s83, 0x2000
	s_nop 0
	global_load_lds_dwordx4 v[224:225], off
	v_lshl_add_u64 v[224:225], s[36:37], 0, v[182:183]
	s_mov_b32 m0, s43
	s_nop 0
	global_load_lds_dwordx4 v[224:225], off
	s_mov_b32 m0, s44
	s_nop 0
	global_load_lds_dwordx4 v[226:227], off
	s_waitcnt vmcnt(8)
	s_waitcnt lgkmcnt(0)
	s_setprio 1
	s_barrier
	v_mfma_f32_16x16x32_bf16 v[60:63], v[112:115], v[160:163], 0
	v_mfma_f32_16x16x32_bf16 v[56:59], v[136:139], v[160:163], 0
	v_mfma_f32_16x16x32_bf16 v[40:43], v[136:139], v[168:171], 0
	v_mfma_f32_16x16x32_bf16 v[44:47], v[112:115], v[168:171], 0
	v_mfma_f32_16x16x32_bf16 v[28:31], v[112:115], v[206:209], 0
	v_mfma_f32_16x16x32_bf16 v[24:27], v[136:139], v[206:209], 0
	v_mfma_f32_16x16x32_bf16 v[8:11], v[136:139], v[214:217], 0
	v_mfma_f32_16x16x32_bf16 v[12:15], v[112:115], v[214:217], 0
	v_mfma_f32_16x16x32_bf16 v[4:7], v[144:147], v[214:217], 0
	v_mfma_f32_16x16x32_bf16 v[0:3], v[152:155], v[214:217], 0
	v_mfma_f32_16x16x32_bf16 v[16:19], v[152:155], v[206:209], 0
	v_mfma_f32_16x16x32_bf16 v[20:23], v[144:147], v[206:209], 0
	v_mfma_f32_16x16x32_bf16 v[36:39], v[144:147], v[168:171], 0
	v_mfma_f32_16x16x32_bf16 v[32:35], v[152:155], v[168:171], 0
	v_mfma_f32_16x16x32_bf16 v[48:51], v[152:155], v[160:163], 0
	v_mfma_f32_16x16x32_bf16 v[52:55], v[144:147], v[160:163], 0
	v_mfma_f32_16x16x32_bf16 v[60:63], v[116:119], v[164:167], v[60:63]
	v_mfma_f32_16x16x32_bf16 v[56:59], v[140:143], v[164:167], v[56:59]
	v_mfma_f32_16x16x32_bf16 v[40:43], v[140:143], v[172:175], v[40:43]
	v_mfma_f32_16x16x32_bf16 v[44:47], v[116:119], v[172:175], v[44:47]
	v_mfma_f32_16x16x32_bf16 v[28:31], v[116:119], v[210:213], v[28:31]
	v_mfma_f32_16x16x32_bf16 v[24:27], v[140:143], v[210:213], v[24:27]
	v_mfma_f32_16x16x32_bf16 v[8:11], v[140:143], v[218:221], v[8:11]
	v_mfma_f32_16x16x32_bf16 v[12:15], v[116:119], v[218:221], v[12:15]
	v_mfma_f32_16x16x32_bf16 v[4:7], v[148:151], v[218:221], v[4:7]
	v_mfma_f32_16x16x32_bf16 v[0:3], v[156:159], v[218:221], v[0:3]
	v_mfma_f32_16x16x32_bf16 v[16:19], v[156:159], v[210:213], v[16:19]
	v_mfma_f32_16x16x32_bf16 v[20:23], v[148:151], v[210:213], v[20:23]
	v_mfma_f32_16x16x32_bf16 v[36:39], v[148:151], v[172:175], v[36:39]
	v_mfma_f32_16x16x32_bf16 v[32:35], v[156:159], v[172:175], v[32:35]
	v_mfma_f32_16x16x32_bf16 v[48:51], v[156:159], v[164:167], v[48:51]
	v_mfma_f32_16x16x32_bf16 v[52:55], v[148:151], v[164:167], v[52:55]
	s_barrier
	s_setprio 0
	s_add_i32 s83, 0, 0x18000
	s_add_i32 s85, 0, 0x1c000
	v_add_u32_e32 v140, s83, v202
	v_add_u32_e32 v156, s85, v202
	ds_read_b128 v[112:115], v140
	ds_read_b128 v[116:119], v140 offset:1024
	ds_read_b128 v[136:139], v140 offset:2048
	ds_read_b128 v[140:143], v140 offset:3072
	ds_read_b128 v[144:147], v156
	ds_read_b128 v[148:151], v156 offset:1024
	ds_read_b128 v[152:155], v156 offset:2048
	ds_read_b128 v[156:159], v156 offset:3072
	s_add_u32 s20, s36, 0xb0000
	s_addc_u32 s21, s37, 0
	s_mov_b32 m0, s45
	v_lshl_add_u64 v[230:231], s[20:21], 0, v[182:183]
	ds_read_b128 v[160:163], v205 offset:32768
	ds_read_b128 v[164:167], v205 offset:33792
	ds_read_b128 v[168:171], v205 offset:34816
	ds_read_b128 v[172:175], v205 offset:35840
	ds_read_b128 v[206:209], v205 offset:36864
	ds_read_b128 v[210:213], v205 offset:37888
	ds_read_b128 v[214:217], v205 offset:38912
	ds_read_b128 v[218:221], v205 offset:39936
	global_load_lds_dwordx4 v[230:231], off
	v_lshl_add_u64 v[230:231], s[20:21], 0, v[178:179]
	s_mov_b32 m0, s46
	s_nop 0
	global_load_lds_dwordx4 v[230:231], off
	s_waitcnt vmcnt(8)
	s_waitcnt lgkmcnt(0)
	s_setprio 1
	s_barrier
	v_mfma_f32_16x16x32_bf16 v[132:135], v[112:115], v[160:163], v[132:135]
	v_mfma_f32_16x16x32_bf16 v[128:131], v[136:139], v[160:163], v[128:131]
	v_mfma_f32_16x16x32_bf16 v[104:107], v[136:139], v[168:171], v[104:107]
	v_mfma_f32_16x16x32_bf16 v[108:111], v[112:115], v[168:171], v[108:111]
	v_mfma_f32_16x16x32_bf16 v[92:95], v[112:115], v[206:209], v[92:95]
	v_mfma_f32_16x16x32_bf16 v[88:91], v[136:139], v[206:209], v[88:91]
	v_mfma_f32_16x16x32_bf16 v[72:75], v[136:139], v[214:217], v[72:75]
	v_mfma_f32_16x16x32_bf16 v[76:79], v[112:115], v[214:217], v[76:79]
	v_mfma_f32_16x16x32_bf16 v[68:71], v[144:147], v[214:217], v[68:71]
	v_mfma_f32_16x16x32_bf16 v[64:67], v[152:155], v[214:217], v[64:67]
	v_mfma_f32_16x16x32_bf16 v[80:83], v[152:155], v[206:209], v[80:83]
	v_mfma_f32_16x16x32_bf16 v[84:87], v[144:147], v[206:209], v[84:87]
	v_mfma_f32_16x16x32_bf16 v[100:103], v[144:147], v[168:171], v[100:103]
	v_mfma_f32_16x16x32_bf16 v[96:99], v[152:155], v[168:171], v[96:99]
	v_mfma_f32_16x16x32_bf16 v[120:123], v[152:155], v[160:163], v[120:123]
	v_mfma_f32_16x16x32_bf16 v[124:127], v[144:147], v[160:163], v[124:127]
	v_mfma_f32_16x16x32_bf16 v[132:135], v[116:119], v[164:167], v[132:135]
	v_mfma_f32_16x16x32_bf16 v[128:131], v[140:143], v[164:167], v[128:131]
	v_mfma_f32_16x16x32_bf16 v[104:107], v[140:143], v[172:175], v[104:107]
	v_mfma_f32_16x16x32_bf16 v[108:111], v[116:119], v[172:175], v[108:111]
	v_mfma_f32_16x16x32_bf16 v[92:95], v[116:119], v[210:213], v[92:95]
	v_mfma_f32_16x16x32_bf16 v[88:91], v[140:143], v[210:213], v[88:91]
	v_mfma_f32_16x16x32_bf16 v[72:75], v[140:143], v[218:221], v[72:75]
	v_mfma_f32_16x16x32_bf16 v[76:79], v[116:119], v[218:221], v[76:79]
	v_mfma_f32_16x16x32_bf16 v[68:71], v[148:151], v[218:221], v[68:71]
	v_mfma_f32_16x16x32_bf16 v[64:67], v[156:159], v[218:221], v[64:67]
	v_mfma_f32_16x16x32_bf16 v[80:83], v[156:159], v[210:213], v[80:83]
	v_mfma_f32_16x16x32_bf16 v[84:87], v[148:151], v[210:213], v[84:87]
	v_mfma_f32_16x16x32_bf16 v[100:103], v[148:151], v[172:175], v[100:103]
	v_mfma_f32_16x16x32_bf16 v[96:99], v[156:159], v[172:175], v[96:99]
	v_mfma_f32_16x16x32_bf16 v[120:123], v[156:159], v[164:167], v[120:123]
	v_mfma_f32_16x16x32_bf16 v[124:127], v[148:151], v[164:167], v[124:127]
	s_barrier
	s_setprio 0
	s_add_i32 s20, s83, s40
	v_lshl_add_u64 v[200:201], v[200:201], 0, s[14:15]
	s_mov_b32 m0, s20
	ds_read_b128 v[160:163], v205 offset:49152
	ds_read_b128 v[164:167], v205 offset:50176
	ds_read_b128 v[168:171], v205 offset:51200
	ds_read_b128 v[172:175], v205 offset:52224
	ds_read_b128 v[206:209], v205 offset:53248
	ds_read_b128 v[210:213], v205 offset:54272
	ds_read_b128 v[214:217], v205 offset:55296
	ds_read_b128 v[218:221], v205 offset:56320
	global_load_lds_dwordx4 v[200:201], off
	s_add_i32 m0, s20, 0x2000
	s_add_u32 s20, s26, 0xb0080
	v_lshl_add_u64 v[200:201], v[222:223], 0, s[14:15]
	s_addc_u32 s21, s27, 0
	s_add_i32 s26, s85, s40
	global_load_lds_dwordx4 v[200:201], off
	v_lshl_add_u64 v[200:201], s[20:21], 0, v[180:181]
	s_mov_b32 m0, s26
	s_nop 0
	global_load_lds_dwordx4 v[200:201], off
	v_lshl_add_u64 v[200:201], s[20:21], 0, v[176:177]
	s_add_i32 m0, s26, 0x2000
	s_nop 0
	global_load_lds_dwordx4 v[200:201], off
	v_lshl_add_u64 v[200:201], v[224:225], 0, s[14:15]
	s_mov_b32 m0, s52
	s_nop 0
	global_load_lds_dwordx4 v[200:201], off
	v_lshl_add_u64 v[200:201], v[226:227], 0, s[14:15]
	s_mov_b32 m0, s53
	s_nop 0
	global_load_lds_dwordx4 v[200:201], off
	s_waitcnt vmcnt(8)
	s_waitcnt lgkmcnt(0)
	s_setprio 1
	s_barrier
	v_mfma_f32_16x16x32_bf16 v[60:63], v[112:115], v[160:163], v[60:63]
	v_mfma_f32_16x16x32_bf16 v[56:59], v[136:139], v[160:163], v[56:59]
	v_mfma_f32_16x16x32_bf16 v[40:43], v[136:139], v[168:171], v[40:43]
	v_mfma_f32_16x16x32_bf16 v[44:47], v[112:115], v[168:171], v[44:47]
	v_mfma_f32_16x16x32_bf16 v[28:31], v[112:115], v[206:209], v[28:31]
	v_mfma_f32_16x16x32_bf16 v[24:27], v[136:139], v[206:209], v[24:27]
	v_mfma_f32_16x16x32_bf16 v[8:11], v[136:139], v[214:217], v[8:11]
	v_mfma_f32_16x16x32_bf16 v[12:15], v[112:115], v[214:217], v[12:15]
	v_mfma_f32_16x16x32_bf16 v[4:7], v[144:147], v[214:217], v[4:7]
	v_mfma_f32_16x16x32_bf16 v[0:3], v[152:155], v[214:217], v[0:3]
	v_mfma_f32_16x16x32_bf16 v[16:19], v[152:155], v[206:209], v[16:19]
	v_mfma_f32_16x16x32_bf16 v[20:23], v[144:147], v[206:209], v[20:23]
	v_mfma_f32_16x16x32_bf16 v[36:39], v[144:147], v[168:171], v[36:39]
	v_mfma_f32_16x16x32_bf16 v[32:35], v[152:155], v[168:171], v[32:35]
	v_mfma_f32_16x16x32_bf16 v[48:51], v[152:155], v[160:163], v[48:51]
	v_mfma_f32_16x16x32_bf16 v[52:55], v[144:147], v[160:163], v[52:55]
	v_mfma_f32_16x16x32_bf16 v[60:63], v[116:119], v[164:167], v[60:63]
	v_mfma_f32_16x16x32_bf16 v[56:59], v[140:143], v[164:167], v[56:59]
	v_mfma_f32_16x16x32_bf16 v[40:43], v[140:143], v[172:175], v[40:43]
	v_mfma_f32_16x16x32_bf16 v[44:47], v[116:119], v[172:175], v[44:47]
	v_mfma_f32_16x16x32_bf16 v[28:31], v[116:119], v[210:213], v[28:31]
	v_mfma_f32_16x16x32_bf16 v[24:27], v[140:143], v[210:213], v[24:27]
	v_mfma_f32_16x16x32_bf16 v[8:11], v[140:143], v[218:221], v[8:11]
	v_mfma_f32_16x16x32_bf16 v[12:15], v[116:119], v[218:221], v[12:15]
	v_mfma_f32_16x16x32_bf16 v[4:7], v[148:151], v[218:221], v[4:7]
	v_mfma_f32_16x16x32_bf16 v[0:3], v[156:159], v[218:221], v[0:3]
	v_mfma_f32_16x16x32_bf16 v[16:19], v[156:159], v[210:213], v[16:19]
	v_mfma_f32_16x16x32_bf16 v[20:23], v[148:151], v[210:213], v[20:23]
	v_mfma_f32_16x16x32_bf16 v[36:39], v[148:151], v[172:175], v[36:39]
	v_mfma_f32_16x16x32_bf16 v[32:35], v[156:159], v[172:175], v[32:35]
	v_mfma_f32_16x16x32_bf16 v[48:51], v[156:159], v[164:167], v[48:51]
	v_mfma_f32_16x16x32_bf16 v[52:55], v[148:151], v[164:167], v[52:55]
	s_barrier
	s_setprio 0
	s_add_i32 s82, s82, 2
	s_add_u32 s80, s80, 0x100
	s_addc_u32 s81, s81, 0
	s_cmp_gt_u32 s82, 41
	s_mov_b64 s[20:21], s[22:23]
.LBB0_836:
	ds_read_b128 v[112:115], v203
	ds_read_b128 v[116:119], v203 offset:1024
	ds_read_b128 v[136:139], v203 offset:2048
	ds_read_b128 v[140:143], v203 offset:3072
	ds_read_b128 v[144:147], v204
	ds_read_b128 v[148:151], v204 offset:1024
	ds_read_b128 v[152:155], v204 offset:2048
	ds_read_b128 v[156:159], v204 offset:3072
	s_add_u32 s22, s20, 0x100
	s_addc_u32 s23, s21, 0
	s_cmp_eq_u32 s82, 40
	s_cselect_b32 s37, s7, s23
	s_cselect_b32 s36, s6, s22
	s_cselect_b32 s27, s19, s81
	s_cselect_b32 s26, s18, s80
	v_lshl_add_u64 v[200:201], s[20:21], 0, v[186:187]
	s_add_i32 m0, s43, 0xc000
	ds_read_b128 v[160:163], v205
	ds_read_b128 v[164:167], v205 offset:1024
	ds_read_b128 v[168:171], v205 offset:2048
	ds_read_b128 v[172:175], v205 offset:3072
	ds_read_b128 v[206:209], v205 offset:4096
	ds_read_b128 v[210:213], v205 offset:5120
	ds_read_b128 v[214:217], v205 offset:6144
	ds_read_b128 v[218:221], v205 offset:7168
	global_load_lds_dwordx4 v[200:201], off
	v_lshl_add_u64 v[200:201], s[20:21], 0, v[188:189]
	s_add_i32 m0, s43, 0xe000
	s_nop 0
	global_load_lds_dwordx4 v[200:201], off
	s_waitcnt vmcnt(8)
	s_waitcnt lgkmcnt(0)
	s_setprio 1
	s_barrier
	v_mfma_f32_16x16x32_bf16 v[132:135], v[112:115], v[160:163], v[132:135]
	v_mfma_f32_16x16x32_bf16 v[128:131], v[136:139], v[160:163], v[128:131]
	v_mfma_f32_16x16x32_bf16 v[104:107], v[136:139], v[168:171], v[104:107]
	v_mfma_f32_16x16x32_bf16 v[108:111], v[112:115], v[168:171], v[108:111]
	v_mfma_f32_16x16x32_bf16 v[92:95], v[112:115], v[206:209], v[92:95]
	v_mfma_f32_16x16x32_bf16 v[88:91], v[136:139], v[206:209], v[88:91]
	v_mfma_f32_16x16x32_bf16 v[72:75], v[136:139], v[214:217], v[72:75]
	v_mfma_f32_16x16x32_bf16 v[76:79], v[112:115], v[214:217], v[76:79]
	v_mfma_f32_16x16x32_bf16 v[68:71], v[144:147], v[214:217], v[68:71]
	v_mfma_f32_16x16x32_bf16 v[64:67], v[152:155], v[214:217], v[64:67]
	v_mfma_f32_16x16x32_bf16 v[80:83], v[152:155], v[206:209], v[80:83]
	v_mfma_f32_16x16x32_bf16 v[84:87], v[144:147], v[206:209], v[84:87]
	v_mfma_f32_16x16x32_bf16 v[100:103], v[144:147], v[168:171], v[100:103]
	v_mfma_f32_16x16x32_bf16 v[96:99], v[152:155], v[168:171], v[96:99]
	v_mfma_f32_16x16x32_bf16 v[120:123], v[152:155], v[160:163], v[120:123]
	v_mfma_f32_16x16x32_bf16 v[124:127], v[144:147], v[160:163], v[124:127]
	v_mfma_f32_16x16x32_bf16 v[132:135], v[116:119], v[164:167], v[132:135]
	v_mfma_f32_16x16x32_bf16 v[128:131], v[140:143], v[164:167], v[128:131]
	v_mfma_f32_16x16x32_bf16 v[104:107], v[140:143], v[172:175], v[104:107]
	v_mfma_f32_16x16x32_bf16 v[108:111], v[116:119], v[172:175], v[108:111]
	v_mfma_f32_16x16x32_bf16 v[92:95], v[116:119], v[210:213], v[92:95]
	v_mfma_f32_16x16x32_bf16 v[88:91], v[140:143], v[210:213], v[88:91]
	v_mfma_f32_16x16x32_bf16 v[72:75], v[140:143], v[218:221], v[72:75]
	v_mfma_f32_16x16x32_bf16 v[76:79], v[116:119], v[218:221], v[76:79]
	v_mfma_f32_16x16x32_bf16 v[68:71], v[148:151], v[218:221], v[68:71]
	v_mfma_f32_16x16x32_bf16 v[64:67], v[156:159], v[218:221], v[64:67]
	v_mfma_f32_16x16x32_bf16 v[80:83], v[156:159], v[210:213], v[80:83]
	v_mfma_f32_16x16x32_bf16 v[84:87], v[148:151], v[210:213], v[84:87]
	v_mfma_f32_16x16x32_bf16 v[100:103], v[148:151], v[172:175], v[100:103]
	v_mfma_f32_16x16x32_bf16 v[96:99], v[156:159], v[172:175], v[96:99]
	v_mfma_f32_16x16x32_bf16 v[120:123], v[156:159], v[164:167], v[120:123]
	v_mfma_f32_16x16x32_bf16 v[124:127], v[148:151], v[164:167], v[124:127]
	s_barrier
	s_setprio 0
	s_add_i32 s20, s59, s40
	v_lshl_add_u64 v[200:201], s[26:27], 0, v[180:181]
	s_mov_b32 m0, s20
	ds_read_b128 v[160:163], v205 offset:16384
	ds_read_b128 v[164:167], v205 offset:17408
	ds_read_b128 v[168:171], v205 offset:18432
	ds_read_b128 v[172:175], v205 offset:19456
	ds_read_b128 v[206:209], v205 offset:20480
	ds_read_b128 v[210:213], v205 offset:21504
	ds_read_b128 v[214:217], v205 offset:22528
	ds_read_b128 v[218:221], v205 offset:23552
	global_load_lds_dwordx4 v[200:201], off
	s_add_i32 m0, s20, 0x2000
	s_add_u32 s20, s26, 0xb0000
	v_lshl_add_u64 v[222:223], s[26:27], 0, v[176:177]
	s_addc_u32 s21, s27, 0
	s_add_i32 s83, s66, s40
	global_load_lds_dwordx4 v[222:223], off
	v_lshl_add_u64 v[224:225], s[20:21], 0, v[180:181]
	s_mov_b32 m0, s83
	v_lshl_add_u64 v[226:227], s[36:37], 0, v[178:179]
	global_load_lds_dwordx4 v[224:225], off
	v_lshl_add_u64 v[224:225], s[20:21], 0, v[176:177]
	s_add_i32 m0, s83, 0x2000
	s_nop 0
	global_load_lds_dwordx4 v[224:225], off
	v_lshl_add_u64 v[224:225], s[36:37], 0, v[182:183]
	s_mov_b32 m0, s43
	s_nop 0
	global_load_lds_dwordx4 v[224:225], off
	s_mov_b32 m0, s44
	s_nop 0
	global_load_lds_dwordx4 v[226:227], off
	s_waitcnt vmcnt(8)
	s_waitcnt lgkmcnt(0)
	s_setprio 1
	s_barrier
	v_mfma_f32_16x16x32_bf16 v[60:63], v[112:115], v[160:163], v[60:63]
	v_mfma_f32_16x16x32_bf16 v[56:59], v[136:139], v[160:163], v[56:59]
	v_mfma_f32_16x16x32_bf16 v[40:43], v[136:139], v[168:171], v[40:43]
	v_mfma_f32_16x16x32_bf16 v[44:47], v[112:115], v[168:171], v[44:47]
	v_mfma_f32_16x16x32_bf16 v[28:31], v[112:115], v[206:209], v[28:31]
	v_mfma_f32_16x16x32_bf16 v[24:27], v[136:139], v[206:209], v[24:27]
	v_mfma_f32_16x16x32_bf16 v[8:11], v[136:139], v[214:217], v[8:11]
	v_mfma_f32_16x16x32_bf16 v[12:15], v[112:115], v[214:217], v[12:15]
	v_mfma_f32_16x16x32_bf16 v[4:7], v[144:147], v[214:217], v[4:7]
	v_mfma_f32_16x16x32_bf16 v[0:3], v[152:155], v[214:217], v[0:3]
	v_mfma_f32_16x16x32_bf16 v[16:19], v[152:155], v[206:209], v[16:19]
	v_mfma_f32_16x16x32_bf16 v[20:23], v[144:147], v[206:209], v[20:23]
	v_mfma_f32_16x16x32_bf16 v[36:39], v[144:147], v[168:171], v[36:39]
	v_mfma_f32_16x16x32_bf16 v[32:35], v[152:155], v[168:171], v[32:35]
	v_mfma_f32_16x16x32_bf16 v[48:51], v[152:155], v[160:163], v[48:51]
	v_mfma_f32_16x16x32_bf16 v[52:55], v[144:147], v[160:163], v[52:55]
	v_mfma_f32_16x16x32_bf16 v[60:63], v[116:119], v[164:167], v[60:63]
	v_mfma_f32_16x16x32_bf16 v[56:59], v[140:143], v[164:167], v[56:59]
	v_mfma_f32_16x16x32_bf16 v[40:43], v[140:143], v[172:175], v[40:43]
	v_mfma_f32_16x16x32_bf16 v[44:47], v[116:119], v[172:175], v[44:47]
	v_mfma_f32_16x16x32_bf16 v[28:31], v[116:119], v[210:213], v[28:31]
	v_mfma_f32_16x16x32_bf16 v[24:27], v[140:143], v[210:213], v[24:27]
	v_mfma_f32_16x16x32_bf16 v[8:11], v[140:143], v[218:221], v[8:11]
	v_mfma_f32_16x16x32_bf16 v[12:15], v[116:119], v[218:221], v[12:15]
	v_mfma_f32_16x16x32_bf16 v[4:7], v[148:151], v[218:221], v[4:7]
	v_mfma_f32_16x16x32_bf16 v[0:3], v[156:159], v[218:221], v[0:3]
	v_mfma_f32_16x16x32_bf16 v[16:19], v[156:159], v[210:213], v[16:19]
	v_mfma_f32_16x16x32_bf16 v[20:23], v[148:151], v[210:213], v[20:23]
	v_mfma_f32_16x16x32_bf16 v[36:39], v[148:151], v[172:175], v[36:39]
	v_mfma_f32_16x16x32_bf16 v[32:35], v[156:159], v[172:175], v[32:35]
	v_mfma_f32_16x16x32_bf16 v[48:51], v[156:159], v[164:167], v[48:51]
	v_mfma_f32_16x16x32_bf16 v[52:55], v[148:151], v[164:167], v[52:55]
	s_barrier
	s_setprio 0
	s_add_i32 s83, 0, 0x18000
	s_add_i32 s85, 0, 0x1c000
	v_add_u32_e32 v140, s83, v202
	v_add_u32_e32 v156, s85, v202
	ds_read_b128 v[112:115], v140
	ds_read_b128 v[116:119], v140 offset:1024
	ds_read_b128 v[136:139], v140 offset:2048
	ds_read_b128 v[140:143], v140 offset:3072
	ds_read_b128 v[144:147], v156
	ds_read_b128 v[148:151], v156 offset:1024
	ds_read_b128 v[152:155], v156 offset:2048
	ds_read_b128 v[156:159], v156 offset:3072
	s_add_u32 s20, s36, 0xb0000
	s_addc_u32 s21, s37, 0
	s_mov_b32 m0, s45
	v_lshl_add_u64 v[230:231], s[20:21], 0, v[182:183]
	ds_read_b128 v[160:163], v205 offset:32768
	ds_read_b128 v[164:167], v205 offset:33792
	ds_read_b128 v[168:171], v205 offset:34816
	ds_read_b128 v[172:175], v205 offset:35840
	ds_read_b128 v[206:209], v205 offset:36864
	ds_read_b128 v[210:213], v205 offset:37888
	ds_read_b128 v[214:217], v205 offset:38912
	ds_read_b128 v[218:221], v205 offset:39936
	global_load_lds_dwordx4 v[230:231], off
	v_lshl_add_u64 v[230:231], s[20:21], 0, v[178:179]
	s_mov_b32 m0, s46
	s_nop 0
	global_load_lds_dwordx4 v[230:231], off
	s_waitcnt vmcnt(8)
	s_waitcnt lgkmcnt(0)
	s_setprio 1
	s_barrier
	v_mfma_f32_16x16x32_bf16 v[132:135], v[112:115], v[160:163], v[132:135]
	v_mfma_f32_16x16x32_bf16 v[128:131], v[136:139], v[160:163], v[128:131]
	v_mfma_f32_16x16x32_bf16 v[104:107], v[136:139], v[168:171], v[104:107]
	v_mfma_f32_16x16x32_bf16 v[108:111], v[112:115], v[168:171], v[108:111]
	v_mfma_f32_16x16x32_bf16 v[92:95], v[112:115], v[206:209], v[92:95]
	v_mfma_f32_16x16x32_bf16 v[88:91], v[136:139], v[206:209], v[88:91]
	v_mfma_f32_16x16x32_bf16 v[72:75], v[136:139], v[214:217], v[72:75]
	v_mfma_f32_16x16x32_bf16 v[76:79], v[112:115], v[214:217], v[76:79]
	v_mfma_f32_16x16x32_bf16 v[68:71], v[144:147], v[214:217], v[68:71]
	v_mfma_f32_16x16x32_bf16 v[64:67], v[152:155], v[214:217], v[64:67]
	v_mfma_f32_16x16x32_bf16 v[80:83], v[152:155], v[206:209], v[80:83]
	v_mfma_f32_16x16x32_bf16 v[84:87], v[144:147], v[206:209], v[84:87]
	v_mfma_f32_16x16x32_bf16 v[100:103], v[144:147], v[168:171], v[100:103]
	v_mfma_f32_16x16x32_bf16 v[96:99], v[152:155], v[168:171], v[96:99]
	v_mfma_f32_16x16x32_bf16 v[120:123], v[152:155], v[160:163], v[120:123]
	v_mfma_f32_16x16x32_bf16 v[124:127], v[144:147], v[160:163], v[124:127]
	v_mfma_f32_16x16x32_bf16 v[132:135], v[116:119], v[164:167], v[132:135]
	v_mfma_f32_16x16x32_bf16 v[128:131], v[140:143], v[164:167], v[128:131]
	v_mfma_f32_16x16x32_bf16 v[104:107], v[140:143], v[172:175], v[104:107]
	v_mfma_f32_16x16x32_bf16 v[108:111], v[116:119], v[172:175], v[108:111]
	v_mfma_f32_16x16x32_bf16 v[92:95], v[116:119], v[210:213], v[92:95]
	v_mfma_f32_16x16x32_bf16 v[88:91], v[140:143], v[210:213], v[88:91]
	v_mfma_f32_16x16x32_bf16 v[72:75], v[140:143], v[218:221], v[72:75]
	v_mfma_f32_16x16x32_bf16 v[76:79], v[116:119], v[218:221], v[76:79]
	v_mfma_f32_16x16x32_bf16 v[68:71], v[148:151], v[218:221], v[68:71]
	v_mfma_f32_16x16x32_bf16 v[64:67], v[156:159], v[218:221], v[64:67]
	v_mfma_f32_16x16x32_bf16 v[80:83], v[156:159], v[210:213], v[80:83]
	v_mfma_f32_16x16x32_bf16 v[84:87], v[148:151], v[210:213], v[84:87]
	v_mfma_f32_16x16x32_bf16 v[100:103], v[148:151], v[172:175], v[100:103]
	v_mfma_f32_16x16x32_bf16 v[96:99], v[156:159], v[172:175], v[96:99]
	v_mfma_f32_16x16x32_bf16 v[120:123], v[156:159], v[164:167], v[120:123]
	v_mfma_f32_16x16x32_bf16 v[124:127], v[148:151], v[164:167], v[124:127]
	s_barrier
	s_setprio 0
	s_add_i32 s20, s83, s40
	v_lshl_add_u64 v[200:201], v[200:201], 0, s[14:15]
	s_mov_b32 m0, s20
	ds_read_b128 v[160:163], v205 offset:49152
	ds_read_b128 v[164:167], v205 offset:50176
	ds_read_b128 v[168:171], v205 offset:51200
	ds_read_b128 v[172:175], v205 offset:52224
	ds_read_b128 v[206:209], v205 offset:53248
	ds_read_b128 v[210:213], v205 offset:54272
	ds_read_b128 v[214:217], v205 offset:55296
	ds_read_b128 v[218:221], v205 offset:56320
	global_load_lds_dwordx4 v[200:201], off
	s_add_i32 m0, s20, 0x2000
	s_add_u32 s20, s26, 0xb0080
	v_lshl_add_u64 v[200:201], v[222:223], 0, s[14:15]
	s_addc_u32 s21, s27, 0
	s_add_i32 s26, s85, s40
	global_load_lds_dwordx4 v[200:201], off
	v_lshl_add_u64 v[200:201], s[20:21], 0, v[180:181]
	s_mov_b32 m0, s26
	s_nop 0
	global_load_lds_dwordx4 v[200:201], off
	v_lshl_add_u64 v[200:201], s[20:21], 0, v[176:177]
	s_add_i32 m0, s26, 0x2000
	s_nop 0
	global_load_lds_dwordx4 v[200:201], off
	v_lshl_add_u64 v[200:201], v[224:225], 0, s[14:15]
	s_mov_b32 m0, s52
	s_nop 0
	global_load_lds_dwordx4 v[200:201], off
	v_lshl_add_u64 v[200:201], v[226:227], 0, s[14:15]
	s_mov_b32 m0, s53
	s_nop 0
	global_load_lds_dwordx4 v[200:201], off
	s_waitcnt vmcnt(8)
	s_waitcnt lgkmcnt(0)
	s_setprio 1
	s_barrier
	v_mfma_f32_16x16x32_bf16 v[60:63], v[112:115], v[160:163], v[60:63]
	v_mfma_f32_16x16x32_bf16 v[56:59], v[136:139], v[160:163], v[56:59]
	v_mfma_f32_16x16x32_bf16 v[40:43], v[136:139], v[168:171], v[40:43]
	v_mfma_f32_16x16x32_bf16 v[44:47], v[112:115], v[168:171], v[44:47]
	v_mfma_f32_16x16x32_bf16 v[28:31], v[112:115], v[206:209], v[28:31]
	v_mfma_f32_16x16x32_bf16 v[24:27], v[136:139], v[206:209], v[24:27]
	v_mfma_f32_16x16x32_bf16 v[8:11], v[136:139], v[214:217], v[8:11]
	v_mfma_f32_16x16x32_bf16 v[12:15], v[112:115], v[214:217], v[12:15]
	v_mfma_f32_16x16x32_bf16 v[4:7], v[144:147], v[214:217], v[4:7]
	v_mfma_f32_16x16x32_bf16 v[0:3], v[152:155], v[214:217], v[0:3]
	v_mfma_f32_16x16x32_bf16 v[16:19], v[152:155], v[206:209], v[16:19]
	v_mfma_f32_16x16x32_bf16 v[20:23], v[144:147], v[206:209], v[20:23]
	v_mfma_f32_16x16x32_bf16 v[36:39], v[144:147], v[168:171], v[36:39]
	v_mfma_f32_16x16x32_bf16 v[32:35], v[152:155], v[168:171], v[32:35]
	v_mfma_f32_16x16x32_bf16 v[48:51], v[152:155], v[160:163], v[48:51]
	v_mfma_f32_16x16x32_bf16 v[52:55], v[144:147], v[160:163], v[52:55]
	v_mfma_f32_16x16x32_bf16 v[60:63], v[116:119], v[164:167], v[60:63]
	v_mfma_f32_16x16x32_bf16 v[56:59], v[140:143], v[164:167], v[56:59]
	v_mfma_f32_16x16x32_bf16 v[40:43], v[140:143], v[172:175], v[40:43]
	v_mfma_f32_16x16x32_bf16 v[44:47], v[116:119], v[172:175], v[44:47]
	v_mfma_f32_16x16x32_bf16 v[28:31], v[116:119], v[210:213], v[28:31]
	v_mfma_f32_16x16x32_bf16 v[24:27], v[140:143], v[210:213], v[24:27]
	v_mfma_f32_16x16x32_bf16 v[8:11], v[140:143], v[218:221], v[8:11]
	v_mfma_f32_16x16x32_bf16 v[12:15], v[116:119], v[218:221], v[12:15]
	v_mfma_f32_16x16x32_bf16 v[4:7], v[148:151], v[218:221], v[4:7]
	v_mfma_f32_16x16x32_bf16 v[0:3], v[156:159], v[218:221], v[0:3]
	v_mfma_f32_16x16x32_bf16 v[16:19], v[156:159], v[210:213], v[16:19]
	v_mfma_f32_16x16x32_bf16 v[20:23], v[148:151], v[210:213], v[20:23]
	v_mfma_f32_16x16x32_bf16 v[36:39], v[148:151], v[172:175], v[36:39]
	v_mfma_f32_16x16x32_bf16 v[32:35], v[156:159], v[172:175], v[32:35]
	v_mfma_f32_16x16x32_bf16 v[48:51], v[156:159], v[164:167], v[48:51]
	v_mfma_f32_16x16x32_bf16 v[52:55], v[148:151], v[164:167], v[52:55]
	s_barrier
	s_setprio 0
	s_add_i32 s82, s82, 2
	s_add_u32 s80, s80, 0x100
	s_addc_u32 s81, s81, 0
	s_cmp_gt_u32 s82, 41
	s_mov_b64 s[20:21], s[22:23]
	s_cbranch_scc0 .LBB0_836
	s_and_b64 vcc, exec, s[16:17]
	s_cbranch_vccz .LBB0_839
	s_barrier
